# v53 + sample-task segment loads as global_load, one KC arrival atomic per workgroup, single LDS wait at the head of the steady P.V sections
# speedup vs baseline: 1.0097x; 1.0097x over previous
; #define LAS __attribute__((address_space(3)))
; __device__ __forceinline__ void seg_attend(SegAcc& A, const float* base, int kvh, int nk, bool valid, const LAS float* qs, LAS float* pt, int lane) {
;     f32x4 kv[16]; float vv[64];
;     const f32x4* kp = (const f32x4*)(base + (size_t)(lane < nk ? lane : 0) * 256 + kvh * 64);
; #pragma unroll
;     for (int c4 = 0; c4 < 16; ++c4) kv[c4] = kp[c4];
;     const float* vb = base + 128 + kvh * 64 + lane;
; #pragma unroll
;     for (int k = 0; k < 64; ++k) vv[k] = vb[(size_t)(k < nk ? k : 0) * 256];
.LBB0_1573:
	v_mov_b32_e32 v0, s2
	ds_read_b32 v0, v0
	v_mov_b32_e32 v83, v110
	v_mov_b32_e32 v81, v108
	v_mov_b32_e32 v79, v106
	v_mov_b32_e32 v77, v104
	s_waitcnt lgkmcnt(0)
	v_readfirstlane_b32 s0, v0
	s_cmpk_lt_i32 s0, 0x100
	s_cselect_b64 s[4:5], -1, 0
	v_mov_b32_e32 v0, s3
	s_and_b64 s[0:1], s[4:5], exec
	ds_read_b64 v[66:67], v0
	s_cselect_b32 s6, 64, 4
	v_cmp_gt_i32_e32 vcc, s6, v98
	s_lshl_b32 s78, s33, 2
	s_or_b64 s[0:1], s[46:47], s[4:5]
	v_cndmask_b32_e32 v2, 0, v98, vcc
	v_ashrrev_i32_e32 v3, 31, v2
	v_lshlrev_b64 v[2:3], 10, v[2:3]
	s_waitcnt lgkmcnt(0)
	v_lshl_add_u64 v[2:3], v[66:67], 0, v[2:3]
	v_lshl_add_u64 v[2:3], v[2:3], 0, s[78:79]
	global_load_dwordx4 v[62:65], v[2:3], off
	global_load_dwordx4 v[58:61], v[2:3], off offset:16
	global_load_dwordx4 v[54:57], v[2:3], off offset:32
	global_load_dwordx4 v[50:53], v[2:3], off offset:48
	global_load_dwordx4 v[46:49], v[2:3], off offset:64
	global_load_dwordx4 v[42:45], v[2:3], off offset:80
	global_load_dwordx4 v[38:41], v[2:3], off offset:96
	global_load_dwordx4 v[34:37], v[2:3], off offset:112
	global_load_dwordx4 v[30:33], v[2:3], off offset:128
	global_load_dwordx4 v[26:29], v[2:3], off offset:144
	global_load_dwordx4 v[22:25], v[2:3], off offset:160
	global_load_dwordx4 v[18:21], v[2:3], off offset:176
	global_load_dwordx4 v[14:17], v[2:3], off offset:192
	global_load_dwordx4 v[10:13], v[2:3], off offset:208
	global_load_dwordx4 v[6:9], v[2:3], off offset:224
	s_nop 0
	global_load_dwordx4 v[2:5], v[2:3], off offset:240
	v_lshl_add_u64 v[66:67], v[66:67], 0, s[78:79]
	s_and_b64 s[4:5], s[4:5], exec
	v_lshl_add_u64 v[66:67], v[98:99], 2, v[66:67]
	s_cselect_b32 s78, 0x1000, 0
	v_lshl_add_u64 v[68:69], v[66:67], 0, s[78:79]
	s_cselect_b32 s78, 0x1400, 0
	global_load_dword v138, v[66:67], off offset:512
	global_load_dword v132, v[66:67], off offset:1536
	global_load_dword v134, v[66:67], off offset:2560
	global_load_dword v136, v[66:67], off offset:3584
	global_load_dword v174, v[68:69], off offset:512
	v_lshl_add_u64 v[68:69], v[66:67], 0, s[78:79]
	s_cselect_b32 s78, 0x1800, 0
	global_load_dword v186, v[68:69], off offset:512
	v_lshl_add_u64 v[68:69], v[66:67], 0, s[78:79]
	s_cselect_b32 s78, 0x1c00, 0
	global_load_dword v198, v[68:69], off offset:512
	v_lshl_add_u64 v[68:69], v[66:67], 0, s[78:79]
	s_cselect_b32 s78, 0x2000, 0
	global_load_dword v210, v[68:69], off offset:512
	v_lshl_add_u64 v[68:69], v[66:67], 0, s[78:79]
	s_cselect_b32 s78, 0x2400, 0
	global_load_dword v222, v[68:69], off offset:512
	v_lshl_add_u64 v[68:69], v[66:67], 0, s[78:79]
	s_cselect_b32 s78, 0x2800, 0
	global_load_dword v0, v[68:69], off offset:512
	v_lshl_add_u64 v[68:69], v[66:67], 0, s[78:79]
	s_cselect_b32 s78, 0x2c00, 0
	global_load_dword v78, v[68:69], off offset:512
	v_lshl_add_u64 v[68:69], v[66:67], 0, s[78:79]
	s_cselect_b32 s78, 0x3000, 0
	global_load_dword v88, v[68:69], off offset:512
	v_lshl_add_u64 v[68:69], v[66:67], 0, s[78:79]
	s_cselect_b32 s78, 0x3400, 0
	global_load_dword v112, v[68:69], off offset:512
	v_lshl_add_u64 v[68:69], v[66:67], 0, s[78:79]
	s_cselect_b32 s78, 0x3800, 0
	global_load_dword v122, v[68:69], off offset:512
	v_lshl_add_u64 v[68:69], v[66:67], 0, s[78:79]
	s_cselect_b32 s78, 0x3c00, 0
	global_load_dword v140, v[68:69], off offset:512
	v_lshl_add_u64 v[68:69], v[66:67], 0, s[78:79]
	s_cselect_b32 s78, 0x4000, 0
	global_load_dword v176, v[68:69], off offset:512
	v_lshl_add_u64 v[68:69], v[66:67], 0, s[78:79]
	s_cselect_b32 s78, 0x4400, 0
	global_load_dword v188, v[68:69], off offset:512
	v_lshl_add_u64 v[68:69], v[66:67], 0, s[78:79]
	s_cselect_b32 s78, 0x4800, 0
	global_load_dword v200, v[68:69], off offset:512
	v_lshl_add_u64 v[68:69], v[66:67], 0, s[78:79]
	s_cselect_b32 s78, 0x4c00, 0
	global_load_dword v212, v[68:69], off offset:512
	v_lshl_add_u64 v[68:69], v[66:67], 0, s[78:79]
	s_cselect_b32 s78, 0x5000, 0
	global_load_dword v224, v[68:69], off offset:512
	v_lshl_add_u64 v[68:69], v[66:67], 0, s[78:79]
	s_cselect_b32 s78, 0x5400, 0
	global_load_dword v70, v[68:69], off offset:512
	v_lshl_add_u64 v[68:69], v[66:67], 0, s[78:79]
	s_cselect_b32 s78, 0x5800, 0
	global_load_dword v80, v[68:69], off offset:512
	v_lshl_add_u64 v[68:69], v[66:67], 0, s[78:79]
	s_cselect_b32 s78, 0x5c00, 0
	global_load_dword v90, v[68:69], off offset:512
	v_lshl_add_u64 v[68:69], v[66:67], 0, s[78:79]
	s_cselect_b32 s78, 0x6000, 0
	global_load_dword v114, v[68:69], off offset:512
	v_lshl_add_u64 v[68:69], v[66:67], 0, s[78:79]
	s_cselect_b32 s78, 0x6400, 0
	global_load_dword v124, v[68:69], off offset:512
	v_lshl_add_u64 v[68:69], v[66:67], 0, s[78:79]
	s_cselect_b32 s78, 0x6800, 0
	global_load_dword v142, v[68:69], off offset:512
	v_lshl_add_u64 v[68:69], v[66:67], 0, s[78:79]
	s_cselect_b32 s78, 0x6c00, 0
	global_load_dword v178, v[68:69], off offset:512
	v_lshl_add_u64 v[68:69], v[66:67], 0, s[78:79]
	s_cselect_b32 s78, 0x7000, 0
	global_load_dword v190, v[68:69], off offset:512
	v_lshl_add_u64 v[68:69], v[66:67], 0, s[78:79]
	s_cselect_b32 s78, 0x7400, 0
	global_load_dword v202, v[68:69], off offset:512
	v_lshl_add_u64 v[68:69], v[66:67], 0, s[78:79]
	s_cselect_b32 s78, 0x7800, 0
	global_load_dword v214, v[68:69], off offset:512
	v_lshl_add_u64 v[68:69], v[66:67], 0, s[78:79]
	s_cselect_b32 s78, 0x7c00, 0
	global_load_dword v226, v[68:69], off offset:512
	v_lshl_add_u64 v[68:69], v[66:67], 0, s[78:79]
	s_cselect_b32 s78, 0x8000, 0
	global_load_dword v72, v[68:69], off offset:512
	v_lshl_add_u64 v[68:69], v[66:67], 0, s[78:79]
	s_cselect_b32 s78, 0x8400, 0
	global_load_dword v82, v[68:69], off offset:512
	v_lshl_add_u64 v[68:69], v[66:67], 0, s[78:79]
; #define LAS __attribute__((address_space(3)))
; __device__ __forceinline__ void seg_attend(SegAcc& A, const float* base, int kvh, int nk, bool valid, const LAS float* qs, LAS float* pt, int lane) {
;     ...
;     const float* vb = base + 128 + kvh * 64 + lane;
; #pragma unroll
;     for (int k = 0; k < 64; ++k) vv[k] = vb[(size_t)(k < nk ? k : 0) * 256];
;     float s[4] = {0.f, 0.f, 0.f, 0.f};
; #pragma unroll
;     for (int c4 = 0; c4 < 16; ++c4)
; #pragma unroll
;         for (int gq = 0; gq < 4; ++gq) { const f32x4 qv = *(const LAS f32x4*)(qs + gq * 64 + 4 * c4); s[gq] += kv[c4][0] * qv[0] + kv[c4][1] * qv[1] + kv[c4][2] * qv[2] + kv[c4][3] * qv[3]; }
	s_cselect_b32 s78, 0x8800, 0
	global_load_dword v92, v[68:69], off offset:512
	v_lshl_add_u64 v[68:69], v[66:67], 0, s[78:79]
	s_cselect_b32 s78, 0x8c00, 0
	global_load_dword v116, v[68:69], off offset:512
	v_lshl_add_u64 v[68:69], v[66:67], 0, s[78:79]
	s_cselect_b32 s78, 0x9000, 0
	global_load_dword v126, v[68:69], off offset:512
	v_lshl_add_u64 v[68:69], v[66:67], 0, s[78:79]
	s_cselect_b32 s78, 0x9400, 0
	global_load_dword v144, v[68:69], off offset:512
	v_lshl_add_u64 v[68:69], v[66:67], 0, s[78:79]
	s_cselect_b32 s78, 0x9800, 0
	global_load_dword v180, v[68:69], off offset:512
	v_lshl_add_u64 v[68:69], v[66:67], 0, s[78:79]
	s_cselect_b32 s78, 0x9c00, 0
	global_load_dword v192, v[68:69], off offset:512
	v_lshl_add_u64 v[68:69], v[66:67], 0, s[78:79]
	s_cselect_b32 s78, 0xa000, 0
	global_load_dword v204, v[68:69], off offset:512
	v_lshl_add_u64 v[68:69], v[66:67], 0, s[78:79]
	s_cselect_b32 s78, 0xa400, 0
	global_load_dword v216, v[68:69], off offset:512
	v_lshl_add_u64 v[68:69], v[66:67], 0, s[78:79]
	s_cselect_b32 s78, 0xa800, 0
	global_load_dword v228, v[68:69], off offset:512
	v_lshl_add_u64 v[68:69], v[66:67], 0, s[78:79]
	s_cselect_b32 s78, 0xac00, 0
	global_load_dword v74, v[68:69], off offset:512
	v_lshl_add_u64 v[68:69], v[66:67], 0, s[78:79]
	s_cselect_b32 s78, 0xb000, 0
	global_load_dword v84, v[68:69], off offset:512
	v_lshl_add_u64 v[68:69], v[66:67], 0, s[78:79]
	s_cselect_b32 s78, 0xb400, 0
	global_load_dword v94, v[68:69], off offset:512
	v_lshl_add_u64 v[68:69], v[66:67], 0, s[78:79]
	s_cselect_b32 s78, 0xb800, 0
	global_load_dword v118, v[68:69], off offset:512
	v_lshl_add_u64 v[68:69], v[66:67], 0, s[78:79]
	s_cselect_b32 s78, 0xbc00, 0
	global_load_dword v128, v[68:69], off offset:512
	v_lshl_add_u64 v[68:69], v[66:67], 0, s[78:79]
	s_cselect_b32 s78, 0xc000, 0
	global_load_dword v170, v[68:69], off offset:512
	v_lshl_add_u64 v[68:69], v[66:67], 0, s[78:79]
	s_cselect_b32 s78, 0xc400, 0
	global_load_dword v182, v[68:69], off offset:512
	v_lshl_add_u64 v[68:69], v[66:67], 0, s[78:79]
	s_cselect_b32 s78, 0xc800, 0
	global_load_dword v194, v[68:69], off offset:512
	v_lshl_add_u64 v[68:69], v[66:67], 0, s[78:79]
	s_cselect_b32 s78, 0xcc00, 0
	global_load_dword v206, v[68:69], off offset:512
	v_lshl_add_u64 v[68:69], v[66:67], 0, s[78:79]
	s_cselect_b32 s78, 0xd000, 0
	global_load_dword v218, v[68:69], off offset:512
	v_lshl_add_u64 v[68:69], v[66:67], 0, s[78:79]
	s_cselect_b32 s78, 0xd400, 0
	global_load_dword v230, v[68:69], off offset:512
	v_lshl_add_u64 v[68:69], v[66:67], 0, s[78:79]
	s_cselect_b32 s78, 0xd800, 0
	global_load_dword v76, v[68:69], off offset:512
	v_lshl_add_u64 v[68:69], v[66:67], 0, s[78:79]
	s_cselect_b32 s78, 0xdc00, 0
	global_load_dword v86, v[68:69], off offset:512
	v_lshl_add_u64 v[68:69], v[66:67], 0, s[78:79]
	s_cselect_b32 s78, 0xe000, 0
	global_load_dword v96, v[68:69], off offset:512
	v_lshl_add_u64 v[68:69], v[66:67], 0, s[78:79]
	s_cselect_b32 s78, 0xe400, 0
	global_load_dword v120, v[68:69], off offset:512
	v_lshl_add_u64 v[68:69], v[66:67], 0, s[78:79]
	s_cselect_b32 s78, 0xe800, 0
	global_load_dword v130, v[68:69], off offset:512
	v_lshl_add_u64 v[68:69], v[66:67], 0, s[78:79]
	s_cselect_b32 s78, 0xec00, 0
	global_load_dword v172, v[68:69], off offset:512
	v_lshl_add_u64 v[68:69], v[66:67], 0, s[78:79]
	s_cselect_b32 s78, 0xf000, 0
	global_load_dword v184, v[68:69], off offset:512
	v_lshl_add_u64 v[68:69], v[66:67], 0, s[78:79]
	s_cselect_b32 s78, 0xf400, 0
	global_load_dword v196, v[68:69], off offset:512
	v_lshl_add_u64 v[68:69], v[66:67], 0, s[78:79]
	s_cselect_b32 s78, 0xf800, 0
	global_load_dword v208, v[68:69], off offset:512
	v_lshl_add_u64 v[68:69], v[66:67], 0, s[78:79]
	s_cselect_b32 s78, 0xfc00, 0
	v_lshl_add_u64 v[66:67], v[66:67], 0, s[78:79]
	global_load_dword v220, v[68:69], off offset:512
	global_load_dword v232, v[66:67], off offset:512
	ds_read_b128 v[234:237], v1 offset:55296
	ds_read_b128 v[238:241], v1 offset:55312
	ds_read_b128 v[242:245], v1 offset:55328
	ds_read_b128 v[66:69], v1 offset:55344
	s_and_b64 vcc, s[0:1], vcc
	s_waitcnt vmcnt(0) lgkmcnt(0)
	ds_read_b128 v[146:149], v1 offset:55552
	ds_read_b128 v[150:153], v1 offset:55808
	ds_read_b128 v[154:157], v1 offset:56064
	ds_read_b128 v[158:161], v1 offset:55568
	ds_read_b128 v[162:165], v1 offset:55824
	s_waitcnt lgkmcnt(4)
	ds_read_b128 v[166:169], v1 offset:56080
	v_mul_f32_e32 v85, v63, v235
	v_fmac_f32_e32 v85, v62, v234
	v_fmac_f32_e32 v85, v64, v236
	v_fmac_f32_e32 v85, v65, v237
	v_add_f32_e32 v85, 0, v85
	v_mov_b32_e32 v75, v119
	s_add_i32 s3, s3, 64
	s_add_i32 s2, s2, 32
	v_mul_f32_e32 v87, v63, v147
	v_fmac_f32_e32 v87, v62, v146
	v_fmac_f32_e32 v87, v64, v148
	v_fmac_f32_e32 v87, v65, v149
	s_waitcnt lgkmcnt(4)
	ds_read_b128 v[146:149], v1 offset:55584
	v_add_f32_e32 v87, 0, v87
	v_mul_f32_e32 v89, v63, v151
	v_fmac_f32_e32 v89, v62, v150
	v_fmac_f32_e32 v89, v64, v152
	v_fmac_f32_e32 v89, v65, v153
	s_waitcnt lgkmcnt(4)
	ds_read_b128 v[150:153], v1 offset:55840
	v_add_f32_e32 v89, 0, v89
	v_mul_f32_e32 v63, v63, v155
	v_fmac_f32_e32 v63, v62, v154
	v_mul_f32_e32 v62, v59, v239
	v_fmac_f32_e32 v62, v58, v238
	v_fmac_f32_e32 v63, v64, v156
	v_fmac_f32_e32 v62, v60, v240
	v_fmac_f32_e32 v63, v65, v157
	v_fmac_f32_e32 v62, v61, v241
	v_add_f32_e32 v91, 0, v63
	v_add_f32_e32 v85, v85, v62
	s_waitcnt lgkmcnt(4)
	v_mul_f32_e32 v63, v59, v159
	v_fmac_f32_e32 v63, v58, v158
	v_fmac_f32_e32 v63, v60, v160
	v_fmac_f32_e32 v63, v61, v161
	ds_read_b128 v[158:161], v1 offset:56096
	v_add_f32_e32 v87, v87, v63
	s_waitcnt lgkmcnt(4)
; #define LAS __attribute__((address_space(3)))
; __device__ __forceinline__ void seg_attend(SegAcc& A, const float* base, int kvh, int nk, bool valid, const LAS float* qs, LAS float* pt, int lane) {
;     ...
;     float s[4] = {0.f, 0.f, 0.f, 0.f};
; #pragma unroll
;     for (int c4 = 0; c4 < 16; ++c4)
; #pragma unroll
;         for (int gq = 0; gq < 4; ++gq) { const f32x4 qv = *(const LAS f32x4*)(qs + gq * 64 + 4 * c4); s[gq] += kv[c4][0] * qv[0] + kv[c4][1] * qv[1] + kv[c4][2] * qv[2] + kv[c4][3] * qv[3]; }
	v_mul_f32_e32 v63, v59, v163
	v_fmac_f32_e32 v63, v58, v162
	v_fmac_f32_e32 v63, v60, v164
	v_fmac_f32_e32 v63, v61, v165
	ds_read_b128 v[162:165], v1 offset:55600
	v_add_f32_e32 v89, v89, v63
	s_waitcnt lgkmcnt(4)
	v_mul_f32_e32 v59, v59, v167
	v_fmac_f32_e32 v59, v58, v166
	v_mul_f32_e32 v58, v55, v243
	v_fmac_f32_e32 v58, v54, v242
	v_fmac_f32_e32 v59, v60, v168
	v_fmac_f32_e32 v58, v56, v244
	v_fmac_f32_e32 v59, v61, v169
	ds_read_b128 v[166:169], v1 offset:55856
	v_fmac_f32_e32 v58, v57, v245
	v_add_f32_e32 v62, v91, v59
	v_add_f32_e32 v63, v85, v58
	s_waitcnt lgkmcnt(4)
	v_mul_f32_e32 v59, v55, v147
	v_fmac_f32_e32 v59, v54, v146
	v_fmac_f32_e32 v59, v56, v148
	v_fmac_f32_e32 v59, v57, v149
	ds_read_b128 v[146:149], v1 offset:56112
	v_add_f32_e32 v64, v87, v59
	s_waitcnt lgkmcnt(4)
	v_mul_f32_e32 v59, v55, v151
	v_fmac_f32_e32 v59, v54, v150
	v_fmac_f32_e32 v59, v56, v152
	v_fmac_f32_e32 v59, v57, v153
	ds_read_b128 v[150:153], v1 offset:55360
	v_add_f32_e32 v65, v89, v59
	s_waitcnt lgkmcnt(4)
	v_mul_f32_e32 v55, v55, v159
	v_fmac_f32_e32 v55, v54, v158
	v_mul_f32_e32 v54, v51, v67
	v_fmac_f32_e32 v54, v50, v66
	v_fmac_f32_e32 v55, v56, v160
	v_fmac_f32_e32 v54, v52, v68
	v_fmac_f32_e32 v55, v57, v161
	ds_read_b128 v[158:161], v1 offset:55616
	v_fmac_f32_e32 v54, v53, v69
	v_add_f32_e32 v58, v62, v55
	v_add_f32_e32 v59, v63, v54
	s_waitcnt lgkmcnt(4)
	v_mul_f32_e32 v55, v51, v163
	v_fmac_f32_e32 v55, v50, v162
	v_fmac_f32_e32 v55, v52, v164
	v_fmac_f32_e32 v55, v53, v165
	ds_read_b128 v[162:165], v1 offset:55872
	v_add_f32_e32 v60, v64, v55
	s_waitcnt lgkmcnt(4)
	v_mul_f32_e32 v55, v51, v167
	v_fmac_f32_e32 v55, v50, v166
	v_fmac_f32_e32 v55, v52, v168
	v_fmac_f32_e32 v55, v53, v169
	ds_read_b128 v[166:169], v1 offset:56128
	v_add_f32_e32 v61, v65, v55
	s_waitcnt lgkmcnt(4)
	v_mul_f32_e32 v51, v51, v147
	v_fmac_f32_e32 v51, v50, v146
	v_fmac_f32_e32 v51, v52, v148
	v_fmac_f32_e32 v51, v53, v149
	ds_read_b128 v[146:149], v1 offset:55376
	v_add_f32_e32 v54, v58, v51
	s_waitcnt lgkmcnt(4)
	v_mul_f32_e32 v51, v47, v151
	v_fmac_f32_e32 v51, v46, v150
	v_fmac_f32_e32 v51, v48, v152
	v_fmac_f32_e32 v51, v49, v153
	ds_read_b128 v[150:153], v1 offset:55632
	v_add_f32_e32 v55, v59, v51
	s_waitcnt lgkmcnt(4)
	v_mul_f32_e32 v51, v47, v159
	v_fmac_f32_e32 v51, v46, v158
	v_fmac_f32_e32 v51, v48, v160
	v_fmac_f32_e32 v51, v49, v161
	ds_read_b128 v[158:161], v1 offset:55888
	v_add_f32_e32 v56, v60, v51
	s_waitcnt lgkmcnt(4)
	v_mul_f32_e32 v51, v47, v163
	v_fmac_f32_e32 v51, v46, v162
	v_fmac_f32_e32 v51, v48, v164
	v_fmac_f32_e32 v51, v49, v165
	ds_read_b128 v[162:165], v1 offset:56144
	v_add_f32_e32 v57, v61, v51
	s_waitcnt lgkmcnt(4)
	v_mul_f32_e32 v47, v47, v167
	v_fmac_f32_e32 v47, v46, v166
	v_fmac_f32_e32 v47, v48, v168
	v_fmac_f32_e32 v47, v49, v169
	ds_read_b128 v[166:169], v1 offset:55392
	v_add_f32_e32 v50, v54, v47
	v_mov_b32_e32 v54, v30
	s_waitcnt lgkmcnt(4)
	v_mul_f32_e32 v47, v43, v147
	v_fmac_f32_e32 v47, v42, v146
	v_fmac_f32_e32 v47, v44, v148
	v_fmac_f32_e32 v47, v45, v149
	ds_read_b128 v[146:149], v1 offset:55648
	v_add_f32_e32 v51, v55, v47
	v_mov_b32_e32 v55, v26
	v_mov_b32_e32 v26, v31
	s_waitcnt lgkmcnt(4)
	v_mul_f32_e32 v47, v43, v151
	v_fmac_f32_e32 v47, v42, v150
	v_fmac_f32_e32 v47, v44, v152
	v_fmac_f32_e32 v47, v45, v153
	ds_read_b128 v[150:153], v1 offset:55904
	v_add_f32_e32 v52, v56, v47
	s_waitcnt lgkmcnt(4)
	v_mul_f32_e32 v47, v43, v159
	v_fmac_f32_e32 v47, v42, v158
	v_fmac_f32_e32 v47, v44, v160
	v_fmac_f32_e32 v47, v45, v161
	ds_read_b128 v[158:161], v1 offset:56160
	v_add_f32_e32 v53, v57, v47
	s_waitcnt lgkmcnt(4)
	v_mul_f32_e32 v43, v43, v163
	v_fmac_f32_e32 v43, v42, v162
	v_fmac_f32_e32 v43, v44, v164
	v_fmac_f32_e32 v43, v45, v165
	ds_read_b128 v[162:165], v1 offset:55408
	v_add_f32_e32 v46, v50, v43
	s_waitcnt lgkmcnt(4)
	v_mul_f32_e32 v43, v39, v167
	v_fmac_f32_e32 v43, v38, v166
	v_fmac_f32_e32 v43, v40, v168
	v_fmac_f32_e32 v43, v41, v169
	ds_read_b128 v[166:169], v1 offset:55664
	v_add_f32_e32 v47, v51, v43
	s_waitcnt lgkmcnt(4)
	v_mul_f32_e32 v43, v39, v147
	v_fmac_f32_e32 v43, v38, v146
	v_fmac_f32_e32 v43, v40, v148
	v_fmac_f32_e32 v43, v41, v149
	ds_read_b128 v[146:149], v1 offset:55920
	v_add_f32_e32 v48, v52, v43
	s_waitcnt lgkmcnt(4)
	v_mul_f32_e32 v43, v39, v151
	v_fmac_f32_e32 v43, v38, v150
	v_fmac_f32_e32 v43, v40, v152
	v_fmac_f32_e32 v43, v41, v153
	ds_read_b128 v[150:153], v1 offset:56176
	v_add_f32_e32 v49, v53, v43
	s_waitcnt lgkmcnt(4)
	v_mul_f32_e32 v39, v39, v159
	v_fmac_f32_e32 v39, v38, v158
	v_fmac_f32_e32 v39, v40, v160
	v_fmac_f32_e32 v39, v41, v161
	ds_read_b128 v[158:161], v1 offset:55424
	v_add_f32_e32 v42, v46, v39
	s_waitcnt lgkmcnt(4)
	v_mul_f32_e32 v39, v35, v163
	v_fmac_f32_e32 v39, v34, v162
	v_fmac_f32_e32 v39, v36, v164
	v_fmac_f32_e32 v39, v37, v165
	ds_read_b128 v[162:165], v1 offset:55680
	v_add_f32_e32 v58, v47, v39
	s_waitcnt lgkmcnt(4)
	v_mul_f32_e32 v39, v35, v167
	v_fmac_f32_e32 v39, v34, v166
	v_fmac_f32_e32 v39, v36, v168
	v_fmac_f32_e32 v39, v37, v169
	ds_read_b128 v[166:169], v1 offset:55936
	v_add_f32_e32 v59, v48, v39
	s_waitcnt lgkmcnt(4)
	v_mul_f32_e32 v39, v35, v147
	v_fmac_f32_e32 v39, v34, v146
	v_fmac_f32_e32 v39, v36, v148
	v_fmac_f32_e32 v39, v37, v149
	ds_read_b128 v[146:149], v1 offset:56192
	v_add_f32_e32 v60, v49, v39
	s_waitcnt lgkmcnt(4)
	v_mul_f32_e32 v35, v35, v151
	v_fmac_f32_e32 v35, v34, v150
	v_fmac_f32_e32 v35, v36, v152
	v_fmac_f32_e32 v35, v37, v153
	ds_read_b128 v[150:153], v1 offset:55440
	v_add_f32_e32 v61, v42, v35
	s_waitcnt lgkmcnt(4)
	v_mov_b32_e32 v56, v158
	v_mov_b32_e32 v38, v32
	s_waitcnt lgkmcnt(0)
; #define LAS __attribute__((address_space(3)))
; __device__ __forceinline__ void seg_attend(SegAcc& A, const float* base, int kvh, int nk, bool valid, const LAS float* qs, LAS float* pt, int lane) {
;     ...
;     float s[4] = {0.f, 0.f, 0.f, 0.f};
; #pragma unroll
;     for (int c4 = 0; c4 < 16; ++c4)
; #pragma unroll
;         for (int gq = 0; gq < 4; ++gq) { const f32x4 qv = *(const LAS f32x4*)(qs + gq * 64 + 4 * c4); s[gq] += kv[c4][0] * qv[0] + kv[c4][1] * qv[1] + kv[c4][2] * qv[2] + kv[c4][3] * qv[3]; }
	v_mov_b32_e32 v57, v150
	v_mov_b32_e32 v50, v159
	v_mov_b32_e32 v51, v151
	v_pk_mul_f32 v[30:31], v[26:27], v[50:51]
	v_mov_b32_e32 v39, v28
	v_pk_fma_f32 v[30:31], v[54:55], v[56:57], v[30:31]
	v_mov_b32_e32 v50, v160
	v_mov_b32_e32 v51, v152
	v_pk_fma_f32 v[30:31], v[38:39], v[50:51], v[30:31]
	v_mov_b32_e32 v28, v33
	v_mov_b32_e32 v52, v161
	ds_read_b128 v[158:161], v1 offset:55696
	v_mov_b32_e32 v53, v153
	ds_read_b128 v[150:153], v1 offset:55952
	v_pk_fma_f32 v[30:31], v[28:29], v[52:53], v[30:31]
	v_mov_b32_e32 v40, v162
	v_add_f32_e32 v30, v58, v30
	v_add_f32_e32 v50, v30, v31
	s_waitcnt lgkmcnt(1)
	v_mov_b32_e32 v41, v158
	v_mov_b32_e32 v30, v163
	v_mov_b32_e32 v31, v159
	v_pk_mul_f32 v[30:31], v[26:27], v[30:31]
	s_nop 0
	v_pk_fma_f32 v[30:31], v[54:55], v[40:41], v[30:31]
	v_mov_b32_e32 v40, v164
	v_mov_b32_e32 v41, v160
	v_pk_fma_f32 v[30:31], v[38:39], v[40:41], v[30:31]
	v_mov_b32_e32 v32, v165
	ds_read_b128 v[162:165], v1 offset:56208
	v_mov_b32_e32 v33, v161
	ds_read_b128 v[158:161], v1 offset:55456
	v_pk_fma_f32 v[30:31], v[28:29], v[32:33], v[30:31]
	v_mov_b32_e32 v40, v166
	v_add_f32_e32 v30, v59, v30
	v_add_f32_e32 v51, v30, v31
	v_mov_b32_e32 v46, v22
	s_waitcnt lgkmcnt(2)
	v_mov_b32_e32 v41, v150
	v_mov_b32_e32 v30, v167
	v_mov_b32_e32 v31, v151
	v_pk_mul_f32 v[30:31], v[26:27], v[30:31]
	v_mov_b32_e32 v47, v18
	v_pk_fma_f32 v[30:31], v[54:55], v[40:41], v[30:31]
	v_mov_b32_e32 v40, v168
	v_mov_b32_e32 v41, v152
	v_pk_fma_f32 v[30:31], v[38:39], v[40:41], v[30:31]
	v_mov_b32_e32 v32, v169
	ds_read_b128 v[166:169], v1 offset:55712
	v_mov_b32_e32 v33, v153
	ds_read_b128 v[150:153], v1 offset:55968
	v_pk_fma_f32 v[30:31], v[28:29], v[32:33], v[30:31]
	v_mov_b32_e32 v40, v146
	v_add_f32_e32 v30, v60, v30
	v_add_f32_e32 v52, v30, v31
	v_mov_b32_e32 v18, v23
	s_waitcnt lgkmcnt(3)
	v_mov_b32_e32 v41, v162
	v_mov_b32_e32 v30, v147
	v_mov_b32_e32 v31, v163
	v_pk_mul_f32 v[26:27], v[26:27], v[30:31]
	v_mov_b32_e32 v30, v148
	v_pk_fma_f32 v[26:27], v[54:55], v[40:41], v[26:27]
	v_mov_b32_e32 v31, v164
	v_pk_fma_f32 v[26:27], v[38:39], v[30:31], v[26:27]
	v_mov_b32_e32 v32, v149
	ds_read_b128 v[146:149], v1 offset:56224
	v_mov_b32_e32 v33, v165
	ds_read_b128 v[162:165], v1 offset:55472
	v_pk_fma_f32 v[26:27], v[28:29], v[32:33], v[26:27]
	s_nop 0
	v_add_f32_e32 v26, v61, v26
	v_add_f32_e32 v53, v26, v27
	s_waitcnt lgkmcnt(4)
	v_mov_b32_e32 v48, v158
	v_mov_b32_e32 v30, v24
	s_waitcnt lgkmcnt(0)
	v_mov_b32_e32 v49, v162
	v_mov_b32_e32 v42, v159
	v_mov_b32_e32 v43, v163
	v_pk_mul_f32 v[22:23], v[18:19], v[42:43]
	v_mov_b32_e32 v31, v20
	v_pk_fma_f32 v[22:23], v[46:47], v[48:49], v[22:23]
	v_mov_b32_e32 v42, v160
	v_mov_b32_e32 v43, v164
	v_pk_fma_f32 v[22:23], v[30:31], v[42:43], v[22:23]
	v_mov_b32_e32 v20, v25
	v_mov_b32_e32 v44, v161
	ds_read_b128 v[158:161], v1 offset:55728
	v_mov_b32_e32 v45, v165
	ds_read_b128 v[162:165], v1 offset:55984
	v_pk_fma_f32 v[22:23], v[20:21], v[44:45], v[22:23]
	v_mov_b32_e32 v32, v166
	v_add_f32_e32 v22, v50, v22
	v_add_f32_e32 v42, v22, v23
	v_mov_b32_e32 v50, s7
	s_waitcnt lgkmcnt(1)
	v_mov_b32_e32 v33, v158
	v_mov_b32_e32 v22, v167
	v_mov_b32_e32 v23, v159
	v_pk_mul_f32 v[22:23], v[18:19], v[22:23]
	s_nop 0
	v_pk_fma_f32 v[22:23], v[46:47], v[32:33], v[22:23]
	v_mov_b32_e32 v32, v168
	v_mov_b32_e32 v33, v160
	v_pk_fma_f32 v[22:23], v[30:31], v[32:33], v[22:23]
	v_mov_b32_e32 v24, v169
	ds_read_b128 v[166:169], v1 offset:56240
	v_mov_b32_e32 v25, v161
	ds_read_b128 v[158:161], v1 offset:55488
	v_pk_fma_f32 v[22:23], v[20:21], v[24:25], v[22:23]
	v_mov_b32_e32 v32, v150
	v_add_f32_e32 v22, v51, v22
	v_add_f32_e32 v43, v22, v23
	s_waitcnt lgkmcnt(2)
	v_mov_b32_e32 v33, v162
	v_mov_b32_e32 v22, v151
	v_mov_b32_e32 v23, v163
	v_pk_mul_f32 v[22:23], v[18:19], v[22:23]
	s_nop 0
	v_pk_fma_f32 v[22:23], v[46:47], v[32:33], v[22:23]
	v_mov_b32_e32 v32, v152
	v_mov_b32_e32 v33, v164
	v_pk_fma_f32 v[22:23], v[30:31], v[32:33], v[22:23]
	v_mov_b32_e32 v24, v153
	ds_read_b128 v[150:153], v1 offset:55744
	v_mov_b32_e32 v25, v165
	ds_read_b128 v[162:165], v1 offset:56000
	v_pk_fma_f32 v[22:23], v[20:21], v[24:25], v[22:23]
	v_mov_b32_e32 v32, v146
	v_add_f32_e32 v22, v52, v22
	v_add_f32_e32 v44, v22, v23
	v_mov_b32_e32 v26, v14
	s_waitcnt lgkmcnt(3)
	v_mov_b32_e32 v33, v166
	v_mov_b32_e32 v22, v147
	v_mov_b32_e32 v23, v167
	v_pk_mul_f32 v[18:19], v[18:19], v[22:23]
	v_mov_b32_e32 v22, v148
	v_pk_fma_f32 v[18:19], v[46:47], v[32:33], v[18:19]
	v_mov_b32_e32 v23, v168
	v_pk_fma_f32 v[18:19], v[30:31], v[22:23], v[18:19]
	v_mov_b32_e32 v24, v149
	ds_read_b128 v[146:149], v1 offset:56256
	v_mov_b32_e32 v25, v169
	ds_read_b128 v[166:169], v1 offset:55504
	v_pk_fma_f32 v[18:19], v[20:21], v[24:25], v[18:19]
	v_mov_b32_e32 v27, v10
	v_add_f32_e32 v18, v53, v18
	v_add_f32_e32 v45, v18, v19
	v_mov_b32_e32 v10, v15
	s_waitcnt lgkmcnt(4)
	v_mov_b32_e32 v40, v158
	s_waitcnt lgkmcnt(0)
	v_mov_b32_e32 v41, v166
	v_mov_b32_e32 v36, v159
	v_mov_b32_e32 v37, v167
	v_pk_mul_f32 v[14:15], v[10:11], v[36:37]
	v_mov_b32_e32 v36, v160
	v_pk_fma_f32 v[28:29], v[26:27], v[40:41], v[14:15]
	v_mov_b32_e32 v14, v16
	v_mov_b32_e32 v15, v12
	v_mov_b32_e32 v37, v168
	v_pk_fma_f32 v[28:29], v[14:15], v[36:37], v[28:29]
	v_mov_b32_e32 v12, v17
	v_mov_b32_e32 v38, v161
	ds_read_b128 v[158:161], v1 offset:55760
	v_mov_b32_e32 v39, v169
	ds_read_b128 v[166:169], v1 offset:56016
	v_pk_fma_f32 v[16:17], v[12:13], v[38:39], v[28:29]
	v_add_f32_e32 v16, v42, v16
	v_add_f32_e32 v40, v16, v17
	v_mov_b32_e32 v16, v150
	s_waitcnt lgkmcnt(1)
; #define LAS __attribute__((address_space(3)))
; __device__ __forceinline__ float ex2(float x) { return __builtin_amdgcn_exp2f(x); }
; template <int CTRL> __device__ __forceinline__ float dpp_mov(float old, float x) { return __int_as_float(__builtin_amdgcn_update_dpp(__float_as_int(old), __float_as_int(x), CTRL, 0xF, 0xF, false)); }
; __device__ __forceinline__ float wave_max(float v) {
;     v = fmaxf(v, dpp_mov<0x111>(v, v)); v = fmaxf(v, dpp_mov<0x112>(v, v)); v = fmaxf(v, dpp_mov<0x114>(v, v)); v = fmaxf(v, dpp_mov<0x118>(v, v));
;     v = fmaxf(v, __int_as_float(__builtin_amdgcn_update_dpp(__float_as_int(v), __float_as_int(v), 0x142, 0xA, 0xF, false)));
;     v = fmaxf(v, __int_as_float(__builtin_amdgcn_update_dpp(__float_as_int(v), __float_as_int(v), 0x143, 0xC, 0xF, false)));
;     return __int_as_float(__builtin_amdgcn_readlane(__float_as_int(v), 63));
; }
; __device__ __forceinline__ void seg_attend(SegAcc& A, const float* base, int kvh, int nk, bool valid, const LAS float* qs, LAS float* pt, int lane) {
;     ...
;     float s[4] = {0.f, 0.f, 0.f, 0.f};
; #pragma unroll
;     for (int c4 = 0; c4 < 16; ++c4)
; #pragma unroll
;         for (int gq = 0; gq < 4; ++gq) { const f32x4 qv = *(const LAS f32x4*)(qs + gq * 64 + 4 * c4); s[gq] += kv[c4][0] * qv[0] + kv[c4][1] * qv[1] + kv[c4][2] * qv[2] + kv[c4][3] * qv[3]; }
;     valid = valid && lane < nk;
;     f32x4 p;
; #pragma unroll
;     for (int gq = 0; gq < 4; ++gq) { const float sv = valid ? s[gq] : NEGB; const float mx = wave_max(sv); const float mn = fmaxf(A.m[gq], mx), a = ex2(A.m[gq] - mn);
;         p[gq] = valid ? ex2(sv - mn) : 0.f; A.l[gq] = A.l[gq] * a + p[gq]; A.o[gq] *= a; A.m[gq] = mn; }
	v_mov_b32_e32 v17, v158
	v_mov_b32_e32 v28, v151
	v_mov_b32_e32 v29, v159
	v_pk_mul_f32 v[28:29], v[10:11], v[28:29]
	s_nop 0
	v_pk_fma_f32 v[16:17], v[26:27], v[16:17], v[28:29]
	v_mov_b32_e32 v28, v152
	v_mov_b32_e32 v29, v160
	v_pk_fma_f32 v[16:17], v[14:15], v[28:29], v[16:17]
	v_mov_b32_e32 v30, v153
	ds_read_b128 v[150:153], v1 offset:56272
	v_mov_b32_e32 v31, v161
	ds_read_b128 v[158:161], v1 offset:55520
	v_pk_fma_f32 v[16:17], v[12:13], v[30:31], v[16:17]
	v_add_f32_e32 v16, v43, v16
	v_add_f32_e32 v28, v16, v17
	v_mov_b32_e32 v16, v162
	s_waitcnt lgkmcnt(2)
	v_mov_b32_e32 v17, v166
	v_mov_b32_e32 v30, v163
	v_mov_b32_e32 v31, v167
	v_pk_mul_f32 v[22:23], v[10:11], v[30:31]
	s_nop 0
	v_pk_fma_f32 v[16:17], v[26:27], v[16:17], v[22:23]
	v_mov_b32_e32 v22, v164
	v_mov_b32_e32 v23, v168
	v_pk_fma_f32 v[16:17], v[14:15], v[22:23], v[16:17]
	v_mov_b32_e32 v32, v165
	ds_read_b128 v[162:165], v1 offset:55776
	v_mov_b32_e32 v33, v169
	ds_read_b128 v[166:169], v1 offset:56032
	v_pk_fma_f32 v[16:17], v[12:13], v[32:33], v[16:17]
	v_add_f32_e32 v16, v44, v16
	v_add_f32_e32 v22, v16, v17
	v_mov_b32_e32 v16, v146
	v_mov_b32_e32 v18, v6
	s_waitcnt lgkmcnt(3)
	v_mov_b32_e32 v17, v150
	v_mov_b32_e32 v30, v147
	v_mov_b32_e32 v31, v151
	v_pk_mul_f32 v[10:11], v[10:11], v[30:31]
	v_mov_b32_e32 v19, v2
	v_pk_fma_f32 v[10:11], v[26:27], v[16:17], v[10:11]
	v_mov_b32_e32 v16, v148
	v_mov_b32_e32 v17, v152
	v_pk_fma_f32 v[10:11], v[14:15], v[16:17], v[10:11]
	v_mov_b32_e32 v32, v149
	ds_read_b128 v[146:149], v1 offset:56288
	v_mov_b32_e32 v33, v153
	ds_read_b128 v[150:153], v1 offset:55536
	v_pk_fma_f32 v[10:11], v[12:13], v[32:33], v[10:11]
	v_mov_b32_e32 v2, v7
	v_add_f32_e32 v10, v45, v10
	v_add_f32_e32 v20, v10, v11
	s_waitcnt lgkmcnt(4)
	v_mov_b32_e32 v38, v158
	s_waitcnt lgkmcnt(0)
	v_mov_b32_e32 v39, v150
	v_mov_b32_e32 v34, v159
	v_mov_b32_e32 v35, v151
	v_pk_mul_f32 v[6:7], v[2:3], v[34:35]
	v_mov_b32_e32 v34, v160
	v_pk_fma_f32 v[24:25], v[18:19], v[38:39], v[6:7]
	v_mov_b32_e32 v6, v8
	v_mov_b32_e32 v7, v4
	v_mov_b32_e32 v35, v152
	v_pk_fma_f32 v[24:25], v[6:7], v[34:35], v[24:25]
	v_mov_b32_e32 v4, v9
	v_mov_b32_e32 v36, v161
	ds_read_b128 v[158:161], v1 offset:55792
	v_mov_b32_e32 v37, v153
	v_pk_fma_f32 v[8:9], v[4:5], v[36:37], v[24:25]
	v_mov_b32_e32 v34, v162
	v_mov_b32_e32 v30, v164
	v_add_f32_e32 v8, v40, v8
	v_add_f32_e32 v8, v8, v9
	s_waitcnt lgkmcnt(0)
	v_mov_b32_e32 v35, v158
	v_mov_b32_e32 v24, v163
	v_mov_b32_e32 v25, v159
	v_pk_mul_f32 v[24:25], v[2:3], v[24:25]
	v_mov_b32_e32 v31, v160
	v_pk_fma_f32 v[24:25], v[18:19], v[34:35], v[24:25]
	v_mov_b32_e32 v26, v165
	v_pk_fma_f32 v[24:25], v[6:7], v[30:31], v[24:25]
	s_nop 0
	v_mov_b32_e32 v27, v161
	ds_read_b128 v[158:161], v1 offset:56048
	v_pk_fma_f32 v[24:25], v[4:5], v[26:27], v[24:25]
	s_nop 0
	v_add_f32_e32 v9, v28, v24
	v_add_f32_e32 v9, v9, v25
	v_mov_b32_e32 v28, v166
	s_waitcnt lgkmcnt(0)
	v_mov_b32_e32 v29, v158
	v_mov_b32_e32 v24, v167
	v_mov_b32_e32 v25, v159
	v_pk_mul_f32 v[14:15], v[2:3], v[24:25]
	v_mov_b32_e32 v24, v168
	v_pk_fma_f32 v[14:15], v[18:19], v[28:29], v[14:15]
	v_mov_b32_e32 v25, v160
	v_pk_fma_f32 v[14:15], v[6:7], v[24:25], v[14:15]
	v_mov_b32_e32 v26, v169
	ds_read_b128 v[166:169], v1 offset:56304
	v_mov_b32_e32 v27, v161
	v_pk_fma_f32 v[14:15], v[4:5], v[26:27], v[14:15]
	s_nop 0
	v_add_f32_e32 v14, v22, v14
	v_add_f32_e32 v21, v14, v15
	v_mov_b32_e32 v22, v146
	v_mov_b32_e32 v10, v148
	s_waitcnt lgkmcnt(0)
	v_mov_b32_e32 v23, v166
	v_mov_b32_e32 v14, v147
	v_mov_b32_e32 v15, v167
	v_pk_mul_f32 v[2:3], v[2:3], v[14:15]
	v_mov_b32_e32 v11, v168
	v_pk_fma_f32 v[2:3], v[18:19], v[22:23], v[2:3]
	v_mov_b32_e32 v16, v149
	v_pk_fma_f32 v[2:3], v[6:7], v[10:11], v[2:3]
	s_nop 0
	v_mov_b32_e32 v17, v169
	v_pk_fma_f32 v[2:3], v[4:5], v[16:17], v[2:3]
	s_nop 0
	v_add_f32_e32 v2, v20, v2
	v_add_f32_e32 v5, v2, v3
	v_cndmask_b32_e32 v2, v209, v8, vcc
	v_mov_b32_e32 v3, v2
	v_cndmask_b32_e32 v5, v209, v5, vcc
	s_nop 0
	v_mov_b32_dpp v3, v3 row_shr:1 row_mask:0xf bank_mask:0xf
	v_max_f32_e32 v3, v3, v3
	v_max_f32_e32 v3, v2, v3
	v_mov_b32_e32 v4, v3
	s_nop 1
	v_mov_b32_dpp v4, v4 row_shr:2 row_mask:0xf bank_mask:0xf
	v_max_f32_e32 v4, v4, v4
	v_max_f32_e32 v3, v3, v4
	v_mov_b32_e32 v4, v3
	s_nop 1
	v_mov_b32_dpp v4, v4 row_shr:4 row_mask:0xf bank_mask:0xf
	v_max_f32_e32 v4, v4, v4
	v_max_f32_e32 v3, v3, v4
	v_mov_b32_e32 v4, v3
	s_nop 1
	v_mov_b32_dpp v4, v4 row_shr:8 row_mask:0xf bank_mask:0xf
	v_max_f32_e32 v4, v4, v4
	v_max_f32_e32 v3, v3, v4
	v_mov_b32_e32 v4, v3
	s_nop 1
	v_mov_b32_dpp v4, v4 row_bcast:15 row_mask:0xa bank_mask:0xf
	v_max_f32_e32 v4, v4, v4
	v_max_f32_e32 v3, v3, v4
	v_mov_b32_e32 v4, v3
	s_nop 1
	v_mov_b32_dpp v4, v4 row_bcast:31 row_mask:0xc bank_mask:0xf
	v_max_f32_e32 v4, v4, v4
	v_max_f32_e32 v3, v3, v4
	v_max_f32_e32 v4, v83, v83
	v_readlane_b32 s0, v3, 63
	s_nop 1
	v_max_f32_e64 v3, s0, s0
	v_max_f32_e32 v110, v4, v3
	v_sub_f32_e32 v3, v83, v110
	v_exp_f32_e32 v6, v3
	v_cndmask_b32_e32 v3, v209, v9, vcc
	v_mov_b32_e32 v4, v3
	v_sub_f32_e32 v2, v2, v110
	v_exp_f32_e32 v2, v2
	v_mov_b32_dpp v4, v4 row_shr:1 row_mask:0xf bank_mask:0xf
	v_max_f32_e32 v4, v4, v4
	v_max_f32_e32 v4, v3, v4
	v_mov_b32_e32 v7, v4
	v_cndmask_b32_e32 v2, 0, v2, vcc
	v_fma_f32 v109, v109, v6, v2
	v_mov_b32_dpp v7, v7 row_shr:2 row_mask:0xf bank_mask:0xf
	v_max_f32_e32 v7, v7, v7
	v_max_f32_e32 v4, v4, v7
	v_mov_b32_e32 v7, v4
	s_nop 1
	v_mov_b32_dpp v7, v7 row_shr:4 row_mask:0xf bank_mask:0xf
	v_max_f32_e32 v7, v7, v7
	v_max_f32_e32 v4, v4, v7
	v_mov_b32_e32 v7, v4
	s_nop 1
	v_mov_b32_dpp v7, v7 row_shr:8 row_mask:0xf bank_mask:0xf
	v_max_f32_e32 v7, v7, v7
; #define LAS __attribute__((address_space(3)))
; __device__ __forceinline__ float ex2(float x) { return __builtin_amdgcn_exp2f(x); }
; #define LDS_WAIT() asm volatile("s_waitcnt lgkmcnt(0)" ::: "memory")
; __device__ __forceinline__ void seg_attend(SegAcc& A, const float* base, int kvh, int nk, bool valid, const LAS float* qs, LAS float* pt, int lane) {
;     ...
;     for (int gq = 0; gq < 4; ++gq) { const float sv = valid ? s[gq] : NEGB; const float mx = wave_max(sv); const float mn = fmaxf(A.m[gq], mx), a = ex2(A.m[gq] - mn);
;         p[gq] = valid ? ex2(sv - mn) : 0.f; A.l[gq] = A.l[gq] * a + p[gq]; A.o[gq] *= a; A.m[gq] = mn; }
;     *(LAS f32x4*)(pt + 4 * lane) = p;
;     LDS_WAIT();
; #pragma unroll
;     for (int k = 0; k < 64; ++k) { const f32x4 pk = *(const LAS f32x4*)(pt + 4 * k);
; #pragma unroll
;         for (int gq = 0; gq < 4; ++gq) A.o[gq] += pk[gq] * vv[k]; }
	v_max_f32_e32 v4, v4, v7
	v_mov_b32_e32 v7, v4
	s_nop 1
	v_mov_b32_dpp v7, v7 row_bcast:15 row_mask:0xa bank_mask:0xf
	v_max_f32_e32 v7, v7, v7
	v_max_f32_e32 v4, v4, v7
	v_mov_b32_e32 v7, v4
	s_nop 1
	v_mov_b32_dpp v7, v7 row_bcast:31 row_mask:0xc bank_mask:0xf
	v_max_f32_e32 v7, v7, v7
	v_max_f32_e32 v4, v4, v7
	v_max_f32_e32 v7, v81, v81
	v_readlane_b32 s0, v4, 63
	s_nop 1
	v_max_f32_e64 v4, s0, s0
	v_max_f32_e32 v108, v7, v4
	v_sub_f32_e32 v4, v81, v108
	v_exp_f32_e32 v7, v4
	v_cndmask_b32_e32 v4, v209, v21, vcc
	v_mov_b32_e32 v8, v4
	v_sub_f32_e32 v3, v3, v108
	v_exp_f32_e32 v3, v3
	v_mov_b32_dpp v8, v8 row_shr:1 row_mask:0xf bank_mask:0xf
	v_max_f32_e32 v8, v8, v8
	v_max_f32_e32 v8, v4, v8
	v_mov_b32_e32 v9, v8
	v_cndmask_b32_e32 v3, 0, v3, vcc
	v_fma_f32 v107, v107, v7, v3
	v_mov_b32_dpp v9, v9 row_shr:2 row_mask:0xf bank_mask:0xf
	v_max_f32_e32 v9, v9, v9
	v_max_f32_e32 v8, v8, v9
	v_mov_b32_e32 v9, v8
	s_nop 1
	v_mov_b32_dpp v9, v9 row_shr:4 row_mask:0xf bank_mask:0xf
	v_max_f32_e32 v9, v9, v9
	v_max_f32_e32 v8, v8, v9
	v_mov_b32_e32 v9, v8
	s_nop 1
	v_mov_b32_dpp v9, v9 row_shr:8 row_mask:0xf bank_mask:0xf
	v_max_f32_e32 v9, v9, v9
	v_max_f32_e32 v8, v8, v9
	v_mov_b32_e32 v9, v8
	s_nop 1
	v_mov_b32_dpp v9, v9 row_bcast:15 row_mask:0xa bank_mask:0xf
	v_max_f32_e32 v9, v9, v9
	v_max_f32_e32 v8, v8, v9
	v_mov_b32_e32 v9, v8
	s_nop 1
	v_mov_b32_dpp v9, v9 row_bcast:31 row_mask:0xc bank_mask:0xf
	v_max_f32_e32 v9, v9, v9
	v_max_f32_e32 v8, v8, v9
	v_max_f32_e32 v9, v79, v79
	v_readlane_b32 s0, v8, 63
	s_nop 1
	v_max_f32_e64 v8, s0, s0
	v_max_f32_e32 v106, v9, v8
	v_mov_b32_e32 v9, v5
	v_sub_f32_e32 v4, v4, v106
	v_exp_f32_e32 v4, v4
	v_mov_b32_dpp v9, v9 row_shr:1 row_mask:0xf bank_mask:0xf
	v_max_f32_e32 v9, v9, v9
	v_max_f32_e32 v9, v5, v9
	v_mov_b32_e32 v10, v9
	v_sub_f32_e32 v8, v79, v106
	v_exp_f32_e32 v8, v8
	v_mov_b32_dpp v10, v10 row_shr:2 row_mask:0xf bank_mask:0xf
	v_max_f32_e32 v10, v10, v10
	v_max_f32_e32 v9, v9, v10
	v_mov_b32_e32 v10, v9
	v_cndmask_b32_e32 v4, 0, v4, vcc
	v_fma_f32 v105, v105, v8, v4
	v_mov_b32_dpp v10, v10 row_shr:4 row_mask:0xf bank_mask:0xf
	v_max_f32_e32 v10, v10, v10
	v_max_f32_e32 v9, v9, v10
	v_mov_b32_e32 v10, v9
	s_nop 1
	v_mov_b32_dpp v10, v10 row_shr:8 row_mask:0xf bank_mask:0xf
	v_max_f32_e32 v10, v10, v10
	v_max_f32_e32 v9, v9, v10
	v_mov_b32_e32 v10, v9
	s_nop 1
	v_mov_b32_dpp v10, v10 row_bcast:15 row_mask:0xa bank_mask:0xf
	v_max_f32_e32 v10, v10, v10
	v_max_f32_e32 v9, v9, v10
	v_mov_b32_e32 v10, v9
	s_nop 1
	v_mov_b32_dpp v10, v10 row_bcast:31 row_mask:0xc bank_mask:0xf
	v_max_f32_e32 v10, v10, v10
	v_max_f32_e32 v9, v9, v10
	v_max_f32_e32 v10, v77, v77
	v_readlane_b32 s0, v9, 63
	s_nop 1
	v_max_f32_e64 v9, s0, s0
	v_max_f32_e32 v104, v10, v9
	v_sub_f32_e32 v5, v5, v104
	v_exp_f32_e32 v5, v5
	v_add_u32_e32 v10, s7, v71
	v_sub_f32_e32 v9, v77, v104
	v_exp_f32_e32 v9, v9
	v_cndmask_b32_e32 v5, 0, v5, vcc
	ds_write_b128 v10, v[2:5] offset:18432
	s_waitcnt lgkmcnt(0)
	v_mov_b32_e32 v119, v5
	ds_read_b128 v[2:5], v50 offset:18432
	ds_read_b128 v[10:13], v50 offset:18448
	ds_read_b128 v[14:17], v50 offset:18464
	ds_read_b128 v[18:21], v50 offset:18480
	ds_read_b128 v[22:25], v50 offset:18496
	ds_read_b128 v[26:29], v50 offset:18512
	ds_read_b128 v[30:33], v50 offset:18528
	ds_read_b128 v[34:37], v50 offset:18544
	ds_read_b128 v[38:41], v50 offset:18560
	s_waitcnt lgkmcnt(8)
	v_pk_mul_f32 v[2:3], v[138:139], v[2:3] op_sel_hi:[0,1]
	v_pk_fma_f32 v[2:3], v[102:103], v[6:7], v[2:3]
	v_fmac_f32_e32 v119, v75, v9
	s_waitcnt lgkmcnt(7)
	v_pk_fma_f32 v[2:3], v[132:133], v[10:11], v[2:3] op_sel_hi:[0,1,1]
	s_waitcnt lgkmcnt(6)
	v_pk_fma_f32 v[2:3], v[134:135], v[14:15], v[2:3] op_sel_hi:[0,1,1]
	s_waitcnt lgkmcnt(5)
	v_pk_fma_f32 v[2:3], v[136:137], v[18:19], v[2:3] op_sel_hi:[0,1,1]
	s_waitcnt lgkmcnt(4)
	v_pk_fma_f32 v[2:3], v[174:175], v[22:23], v[2:3] op_sel_hi:[0,1,1]
	s_waitcnt lgkmcnt(3)
	v_pk_fma_f32 v[2:3], v[186:187], v[26:27], v[2:3] op_sel_hi:[0,1,1]
	s_waitcnt lgkmcnt(2)
	v_pk_fma_f32 v[2:3], v[198:199], v[30:31], v[2:3] op_sel_hi:[0,1,1]
	s_waitcnt lgkmcnt(1)
	v_pk_fma_f32 v[2:3], v[210:211], v[34:35], v[2:3] op_sel_hi:[0,1,1]
	s_waitcnt lgkmcnt(0)
	v_pk_fma_f32 v[46:47], v[222:223], v[38:39], v[2:3] op_sel_hi:[0,1,1]
	v_pk_mul_f32 v[2:3], v[138:139], v[4:5] op_sel_hi:[0,1]
	v_pk_fma_f32 v[2:3], v[100:101], v[8:9], v[2:3]
	s_nop 0
	v_pk_fma_f32 v[2:3], v[132:133], v[12:13], v[2:3] op_sel_hi:[0,1,1]
	v_pk_fma_f32 v[2:3], v[134:135], v[16:17], v[2:3] op_sel_hi:[0,1,1]
	v_pk_fma_f32 v[2:3], v[136:137], v[20:21], v[2:3] op_sel_hi:[0,1,1]
	v_pk_fma_f32 v[2:3], v[174:175], v[24:25], v[2:3] op_sel_hi:[0,1,1]
	v_pk_fma_f32 v[2:3], v[186:187], v[28:29], v[2:3] op_sel_hi:[0,1,1]
	v_pk_fma_f32 v[2:3], v[198:199], v[32:33], v[2:3] op_sel_hi:[0,1,1]
	v_pk_fma_f32 v[2:3], v[210:211], v[36:37], v[2:3] op_sel_hi:[0,1,1]
	v_pk_fma_f32 v[48:49], v[222:223], v[40:41], v[2:3] op_sel_hi:[0,1,1]
	ds_read_b128 v[2:5], v50 offset:18576
	ds_read_b128 v[6:9], v50 offset:18592
	ds_read_b128 v[10:13], v50 offset:18608
	ds_read_b128 v[14:17], v50 offset:18624
	ds_read_b128 v[18:21], v50 offset:18640
	ds_read_b128 v[22:25], v50 offset:18656
	ds_read_b128 v[26:29], v50 offset:18672
	ds_read_b128 v[30:33], v50 offset:18688
	ds_read_b128 v[34:37], v50 offset:18704
	ds_read_b128 v[38:41], v50 offset:18720
	ds_read_b128 v[42:45], v50 offset:18736
	s_waitcnt lgkmcnt(10)
	v_pk_fma_f32 v[2:3], v[0:1], v[2:3], v[46:47] op_sel_hi:[0,1,1]
	s_waitcnt lgkmcnt(9)
	v_pk_fma_f32 v[2:3], v[78:79], v[6:7], v[2:3] op_sel_hi:[0,1,1]
	s_waitcnt lgkmcnt(8)
	v_pk_fma_f32 v[2:3], v[88:89], v[10:11], v[2:3] op_sel_hi:[0,1,1]
	s_waitcnt lgkmcnt(7)
; #define LAS __attribute__((address_space(3)))
; __device__ __forceinline__ void seg_attend(SegAcc& A, const float* base, int kvh, int nk, bool valid, const LAS float* qs, LAS float* pt, int lane) {
;     ...
; #pragma unroll
;     for (int k = 0; k < 64; ++k) { const f32x4 pk = *(const LAS f32x4*)(pt + 4 * k);
; #pragma unroll
;         for (int gq = 0; gq < 4; ++gq) A.o[gq] += pk[gq] * vv[k]; }
	v_pk_fma_f32 v[2:3], v[112:113], v[14:15], v[2:3] op_sel_hi:[0,1,1]
	s_waitcnt lgkmcnt(6)
	v_pk_fma_f32 v[2:3], v[122:123], v[18:19], v[2:3] op_sel_hi:[0,1,1]
	s_waitcnt lgkmcnt(5)
	v_pk_fma_f32 v[2:3], v[140:141], v[22:23], v[2:3] op_sel_hi:[0,1,1]
	s_waitcnt lgkmcnt(4)
	v_pk_fma_f32 v[2:3], v[176:177], v[26:27], v[2:3] op_sel_hi:[0,1,1]
	s_waitcnt lgkmcnt(3)
	v_pk_fma_f32 v[2:3], v[188:189], v[30:31], v[2:3] op_sel_hi:[0,1,1]
	s_waitcnt lgkmcnt(2)
	v_pk_fma_f32 v[2:3], v[200:201], v[34:35], v[2:3] op_sel_hi:[0,1,1]
	s_waitcnt lgkmcnt(1)
	v_pk_fma_f32 v[2:3], v[212:213], v[38:39], v[2:3] op_sel_hi:[0,1,1]
	s_waitcnt lgkmcnt(0)
	v_pk_fma_f32 v[46:47], v[224:225], v[42:43], v[2:3] op_sel_hi:[0,1,1]
	v_pk_fma_f32 v[2:3], v[0:1], v[4:5], v[48:49] op_sel_hi:[0,1,1]
	v_pk_fma_f32 v[2:3], v[78:79], v[8:9], v[2:3] op_sel_hi:[0,1,1]
	v_pk_fma_f32 v[2:3], v[88:89], v[12:13], v[2:3] op_sel_hi:[0,1,1]
	v_pk_fma_f32 v[2:3], v[112:113], v[16:17], v[2:3] op_sel_hi:[0,1,1]
	v_pk_fma_f32 v[2:3], v[122:123], v[20:21], v[2:3] op_sel_hi:[0,1,1]
	v_pk_fma_f32 v[2:3], v[140:141], v[24:25], v[2:3] op_sel_hi:[0,1,1]
	v_pk_fma_f32 v[2:3], v[176:177], v[28:29], v[2:3] op_sel_hi:[0,1,1]
	v_pk_fma_f32 v[2:3], v[188:189], v[32:33], v[2:3] op_sel_hi:[0,1,1]
	v_pk_fma_f32 v[2:3], v[200:201], v[36:37], v[2:3] op_sel_hi:[0,1,1]
	v_pk_fma_f32 v[2:3], v[212:213], v[40:41], v[2:3] op_sel_hi:[0,1,1]
	v_pk_fma_f32 v[48:49], v[224:225], v[44:45], v[2:3] op_sel_hi:[0,1,1]
	ds_read_b128 v[2:5], v50 offset:18752
	ds_read_b128 v[6:9], v50 offset:18768
	ds_read_b128 v[10:13], v50 offset:18784
	ds_read_b128 v[14:17], v50 offset:18800
	ds_read_b128 v[18:21], v50 offset:18816
	ds_read_b128 v[22:25], v50 offset:18832
	ds_read_b128 v[26:29], v50 offset:18848
	ds_read_b128 v[30:33], v50 offset:18864
	ds_read_b128 v[34:37], v50 offset:18880
	ds_read_b128 v[38:41], v50 offset:18896
	ds_read_b128 v[42:45], v50 offset:18912
	s_waitcnt lgkmcnt(10)
	v_pk_fma_f32 v[2:3], v[70:71], v[2:3], v[46:47] op_sel_hi:[0,1,1]
	s_waitcnt lgkmcnt(9)
	v_pk_fma_f32 v[2:3], v[80:81], v[6:7], v[2:3] op_sel_hi:[0,1,1]
	s_waitcnt lgkmcnt(8)
	v_pk_fma_f32 v[2:3], v[90:91], v[10:11], v[2:3] op_sel_hi:[0,1,1]
	s_waitcnt lgkmcnt(7)
	v_pk_fma_f32 v[2:3], v[114:115], v[14:15], v[2:3] op_sel_hi:[0,1,1]
	s_waitcnt lgkmcnt(6)
	v_pk_fma_f32 v[2:3], v[124:125], v[18:19], v[2:3] op_sel_hi:[0,1,1]
	s_waitcnt lgkmcnt(5)
	v_pk_fma_f32 v[2:3], v[142:143], v[22:23], v[2:3] op_sel_hi:[0,1,1]
	s_waitcnt lgkmcnt(4)
	v_pk_fma_f32 v[2:3], v[178:179], v[26:27], v[2:3] op_sel_hi:[0,1,1]
	s_waitcnt lgkmcnt(3)
	v_pk_fma_f32 v[2:3], v[190:191], v[30:31], v[2:3] op_sel_hi:[0,1,1]
	s_waitcnt lgkmcnt(2)
	v_pk_fma_f32 v[2:3], v[202:203], v[34:35], v[2:3] op_sel_hi:[0,1,1]
	s_waitcnt lgkmcnt(1)
	v_pk_fma_f32 v[2:3], v[214:215], v[38:39], v[2:3] op_sel_hi:[0,1,1]
	s_waitcnt lgkmcnt(0)
	v_pk_fma_f32 v[46:47], v[226:227], v[42:43], v[2:3] op_sel_hi:[0,1,1]
	v_pk_fma_f32 v[2:3], v[70:71], v[4:5], v[48:49] op_sel_hi:[0,1,1]
	v_pk_fma_f32 v[2:3], v[80:81], v[8:9], v[2:3] op_sel_hi:[0,1,1]
	v_pk_fma_f32 v[2:3], v[90:91], v[12:13], v[2:3] op_sel_hi:[0,1,1]
	v_pk_fma_f32 v[2:3], v[114:115], v[16:17], v[2:3] op_sel_hi:[0,1,1]
	v_pk_fma_f32 v[2:3], v[124:125], v[20:21], v[2:3] op_sel_hi:[0,1,1]
	v_pk_fma_f32 v[2:3], v[142:143], v[24:25], v[2:3] op_sel_hi:[0,1,1]
	v_pk_fma_f32 v[2:3], v[178:179], v[28:29], v[2:3] op_sel_hi:[0,1,1]
	v_pk_fma_f32 v[2:3], v[190:191], v[32:33], v[2:3] op_sel_hi:[0,1,1]
	v_pk_fma_f32 v[2:3], v[202:203], v[36:37], v[2:3] op_sel_hi:[0,1,1]
	v_pk_fma_f32 v[2:3], v[214:215], v[40:41], v[2:3] op_sel_hi:[0,1,1]
	v_pk_fma_f32 v[48:49], v[226:227], v[44:45], v[2:3] op_sel_hi:[0,1,1]
	ds_read_b128 v[2:5], v50 offset:18928
	ds_read_b128 v[6:9], v50 offset:18944
	ds_read_b128 v[10:13], v50 offset:18960
	ds_read_b128 v[14:17], v50 offset:18976
	ds_read_b128 v[18:21], v50 offset:18992
	ds_read_b128 v[22:25], v50 offset:19008
	ds_read_b128 v[26:29], v50 offset:19024
	ds_read_b128 v[30:33], v50 offset:19040
	ds_read_b128 v[34:37], v50 offset:19056
	ds_read_b128 v[38:41], v50 offset:19072
	ds_read_b128 v[42:45], v50 offset:19088
	s_waitcnt lgkmcnt(10)
	v_pk_fma_f32 v[2:3], v[72:73], v[2:3], v[46:47] op_sel_hi:[0,1,1]
	s_waitcnt lgkmcnt(9)
	v_pk_fma_f32 v[2:3], v[82:83], v[6:7], v[2:3] op_sel_hi:[0,1,1]
	s_waitcnt lgkmcnt(8)
	v_pk_fma_f32 v[2:3], v[92:93], v[10:11], v[2:3] op_sel_hi:[0,1,1]
	s_waitcnt lgkmcnt(7)
	v_pk_fma_f32 v[2:3], v[116:117], v[14:15], v[2:3] op_sel_hi:[0,1,1]
	s_waitcnt lgkmcnt(6)
	v_pk_fma_f32 v[2:3], v[126:127], v[18:19], v[2:3] op_sel_hi:[0,1,1]
	s_waitcnt lgkmcnt(5)
	v_pk_fma_f32 v[2:3], v[144:145], v[22:23], v[2:3] op_sel_hi:[0,1,1]
	s_waitcnt lgkmcnt(4)
	v_pk_fma_f32 v[2:3], v[180:181], v[26:27], v[2:3] op_sel_hi:[0,1,1]
	s_waitcnt lgkmcnt(3)
	v_pk_fma_f32 v[2:3], v[192:193], v[30:31], v[2:3] op_sel_hi:[0,1,1]
	s_waitcnt lgkmcnt(2)
	v_pk_fma_f32 v[2:3], v[204:205], v[34:35], v[2:3] op_sel_hi:[0,1,1]
	s_waitcnt lgkmcnt(1)
	v_pk_fma_f32 v[2:3], v[216:217], v[38:39], v[2:3] op_sel_hi:[0,1,1]
	s_waitcnt lgkmcnt(0)
; #define LAS __attribute__((address_space(3)))
; __device__ __forceinline__ void seg_attend(SegAcc& A, const float* base, int kvh, int nk, bool valid, const LAS float* qs, LAS float* pt, int lane) {
;     ...
; #pragma unroll
;     for (int k = 0; k < 64; ++k) { const f32x4 pk = *(const LAS f32x4*)(pt + 4 * k);
; #pragma unroll
;         for (int gq = 0; gq < 4; ++gq) A.o[gq] += pk[gq] * vv[k]; }
; __device__ __forceinline__ void sample_task_part2(const Prm& P, Ctx& C, int b, int kvh, int ts) {
;     ...
; #pragma unroll 1
;     for (int si = C.wave; si < 16; si += NWAVES) { const bool last = blist[si] >= 256; seg_attend(As, (const float*)(uintptr_t)segb[si], kvh, last ? 4 : 64, last ? lane <= ts : true, qs, ptab, lane); }
	v_pk_fma_f32 v[46:47], v[228:229], v[42:43], v[2:3] op_sel_hi:[0,1,1]
	v_pk_fma_f32 v[2:3], v[72:73], v[4:5], v[48:49] op_sel_hi:[0,1,1]
	v_pk_fma_f32 v[2:3], v[82:83], v[8:9], v[2:3] op_sel_hi:[0,1,1]
	v_pk_fma_f32 v[2:3], v[92:93], v[12:13], v[2:3] op_sel_hi:[0,1,1]
	v_pk_fma_f32 v[2:3], v[116:117], v[16:17], v[2:3] op_sel_hi:[0,1,1]
	v_pk_fma_f32 v[2:3], v[126:127], v[20:21], v[2:3] op_sel_hi:[0,1,1]
	v_pk_fma_f32 v[2:3], v[144:145], v[24:25], v[2:3] op_sel_hi:[0,1,1]
	v_pk_fma_f32 v[2:3], v[180:181], v[28:29], v[2:3] op_sel_hi:[0,1,1]
	v_pk_fma_f32 v[2:3], v[192:193], v[32:33], v[2:3] op_sel_hi:[0,1,1]
	v_pk_fma_f32 v[2:3], v[204:205], v[36:37], v[2:3] op_sel_hi:[0,1,1]
	v_pk_fma_f32 v[2:3], v[216:217], v[40:41], v[2:3] op_sel_hi:[0,1,1]
	v_pk_fma_f32 v[48:49], v[228:229], v[44:45], v[2:3] op_sel_hi:[0,1,1]
	ds_read_b128 v[2:5], v50 offset:19104
	ds_read_b128 v[6:9], v50 offset:19120
	ds_read_b128 v[10:13], v50 offset:19136
	ds_read_b128 v[14:17], v50 offset:19152
	ds_read_b128 v[18:21], v50 offset:19168
	ds_read_b128 v[22:25], v50 offset:19184
	ds_read_b128 v[26:29], v50 offset:19200
	ds_read_b128 v[30:33], v50 offset:19216
	ds_read_b128 v[34:37], v50 offset:19232
	ds_read_b128 v[38:41], v50 offset:19248
	ds_read_b128 v[42:45], v50 offset:19264
	s_waitcnt lgkmcnt(10)
	v_pk_fma_f32 v[2:3], v[74:75], v[2:3], v[46:47] op_sel_hi:[0,1,1]
	s_waitcnt lgkmcnt(9)
	v_pk_fma_f32 v[2:3], v[84:85], v[6:7], v[2:3] op_sel_hi:[0,1,1]
	s_waitcnt lgkmcnt(8)
	v_pk_fma_f32 v[2:3], v[94:95], v[10:11], v[2:3] op_sel_hi:[0,1,1]
	s_waitcnt lgkmcnt(7)
	v_pk_fma_f32 v[2:3], v[118:119], v[14:15], v[2:3] op_sel_hi:[0,1,1]
	s_waitcnt lgkmcnt(6)
	v_pk_fma_f32 v[2:3], v[128:129], v[18:19], v[2:3] op_sel_hi:[0,1,1]
	s_waitcnt lgkmcnt(5)
	v_pk_fma_f32 v[2:3], v[170:171], v[22:23], v[2:3] op_sel_hi:[0,1,1]
	s_waitcnt lgkmcnt(4)
	v_pk_fma_f32 v[2:3], v[182:183], v[26:27], v[2:3] op_sel_hi:[0,1,1]
	s_waitcnt lgkmcnt(3)
	v_pk_fma_f32 v[2:3], v[194:195], v[30:31], v[2:3] op_sel_hi:[0,1,1]
	s_waitcnt lgkmcnt(2)
	v_pk_fma_f32 v[2:3], v[206:207], v[34:35], v[2:3] op_sel_hi:[0,1,1]
	s_waitcnt lgkmcnt(1)
	v_pk_fma_f32 v[2:3], v[218:219], v[38:39], v[2:3] op_sel_hi:[0,1,1]
	s_waitcnt lgkmcnt(0)
	v_pk_fma_f32 v[46:47], v[230:231], v[42:43], v[2:3] op_sel_hi:[0,1,1]
	v_pk_fma_f32 v[2:3], v[74:75], v[4:5], v[48:49] op_sel_hi:[0,1,1]
	v_pk_fma_f32 v[2:3], v[84:85], v[8:9], v[2:3] op_sel_hi:[0,1,1]
	v_pk_fma_f32 v[2:3], v[94:95], v[12:13], v[2:3] op_sel_hi:[0,1,1]
	v_pk_fma_f32 v[2:3], v[118:119], v[16:17], v[2:3] op_sel_hi:[0,1,1]
	v_pk_fma_f32 v[2:3], v[128:129], v[20:21], v[2:3] op_sel_hi:[0,1,1]
	v_pk_fma_f32 v[2:3], v[170:171], v[24:25], v[2:3] op_sel_hi:[0,1,1]
	v_pk_fma_f32 v[2:3], v[182:183], v[28:29], v[2:3] op_sel_hi:[0,1,1]
	v_pk_fma_f32 v[2:3], v[194:195], v[32:33], v[2:3] op_sel_hi:[0,1,1]
	v_pk_fma_f32 v[2:3], v[206:207], v[36:37], v[2:3] op_sel_hi:[0,1,1]
	v_pk_fma_f32 v[2:3], v[218:219], v[40:41], v[2:3] op_sel_hi:[0,1,1]
	v_pk_fma_f32 v[48:49], v[230:231], v[44:45], v[2:3] op_sel_hi:[0,1,1]
	ds_read_b128 v[2:5], v50 offset:19280
	ds_read_b128 v[6:9], v50 offset:19296
	ds_read_b128 v[10:13], v50 offset:19312
	ds_read_b128 v[14:17], v50 offset:19328
	ds_read_b128 v[18:21], v50 offset:19344
	ds_read_b128 v[22:25], v50 offset:19360
	ds_read_b128 v[26:29], v50 offset:19376
	ds_read_b128 v[30:33], v50 offset:19392
	ds_read_b128 v[34:37], v50 offset:19408
	ds_read_b128 v[38:41], v50 offset:19424
	ds_read_b128 v[42:45], v50 offset:19440
	s_waitcnt lgkmcnt(10)
	v_pk_fma_f32 v[2:3], v[76:77], v[2:3], v[46:47] op_sel_hi:[0,1,1]
	s_waitcnt lgkmcnt(9)
	v_pk_fma_f32 v[2:3], v[86:87], v[6:7], v[2:3] op_sel_hi:[0,1,1]
	s_waitcnt lgkmcnt(8)
	v_pk_fma_f32 v[2:3], v[96:97], v[10:11], v[2:3] op_sel_hi:[0,1,1]
	s_waitcnt lgkmcnt(7)
	v_pk_fma_f32 v[2:3], v[120:121], v[14:15], v[2:3] op_sel_hi:[0,1,1]
	s_waitcnt lgkmcnt(6)
	v_pk_fma_f32 v[2:3], v[130:131], v[18:19], v[2:3] op_sel_hi:[0,1,1]
	s_waitcnt lgkmcnt(5)
	v_pk_fma_f32 v[2:3], v[172:173], v[22:23], v[2:3] op_sel_hi:[0,1,1]
	s_waitcnt lgkmcnt(4)
	v_pk_fma_f32 v[2:3], v[184:185], v[26:27], v[2:3] op_sel_hi:[0,1,1]
	s_waitcnt lgkmcnt(3)
	v_pk_fma_f32 v[2:3], v[196:197], v[30:31], v[2:3] op_sel_hi:[0,1,1]
	s_waitcnt lgkmcnt(2)
	v_pk_fma_f32 v[2:3], v[208:209], v[34:35], v[2:3] op_sel_hi:[0,1,1]
	s_waitcnt lgkmcnt(1)
	v_pk_fma_f32 v[2:3], v[220:221], v[38:39], v[2:3] op_sel_hi:[0,1,1]
	s_waitcnt lgkmcnt(0)
	v_pk_fma_f32 v[102:103], v[232:233], v[42:43], v[2:3] op_sel_hi:[0,1,1]
	v_pk_fma_f32 v[2:3], v[76:77], v[4:5], v[48:49] op_sel_hi:[0,1,1]
	v_pk_fma_f32 v[2:3], v[86:87], v[8:9], v[2:3] op_sel_hi:[0,1,1]
	v_pk_fma_f32 v[2:3], v[96:97], v[12:13], v[2:3] op_sel_hi:[0,1,1]
	v_pk_fma_f32 v[2:3], v[120:121], v[16:17], v[2:3] op_sel_hi:[0,1,1]
	v_pk_fma_f32 v[2:3], v[130:131], v[20:21], v[2:3] op_sel_hi:[0,1,1]
	v_pk_fma_f32 v[2:3], v[172:173], v[24:25], v[2:3] op_sel_hi:[0,1,1]
	v_pk_fma_f32 v[2:3], v[184:185], v[28:29], v[2:3] op_sel_hi:[0,1,1]
	v_pk_fma_f32 v[2:3], v[196:197], v[32:33], v[2:3] op_sel_hi:[0,1,1]
	v_pk_fma_f32 v[2:3], v[208:209], v[36:37], v[2:3] op_sel_hi:[0,1,1]
	s_waitcnt lgkmcnt(0)
	v_pk_fma_f32 v[2:3], v[220:221], v[40:41], v[2:3] op_sel_hi:[0,1,1]
	v_add_co_u32_e32 v73, vcc, 8, v73
	v_pk_fma_f32 v[100:101], v[232:233], v[44:45], v[2:3] op_sel_hi:[0,1,1]
	s_andn2_b64 vcc, exec, vcc
	s_cbranch_vccz .LBB0_1573
; #define LAS __attribute__((address_space(3)))
; __device__ __forceinline__ void seg_attend(SegAcc& A, const float* base, int kvh, int nk, bool valid, const LAS float* qs, LAS float* pt, int lane) {
;     f32x4 kv[16]; float vv[64];
;     const f32x4* kp = (const f32x4*)(base + (size_t)(lane < nk ? lane : 0) * 256 + kvh * 64);
; #pragma unroll
;     for (int c4 = 0; c4 < 16; ++c4) kv[c4] = kp[c4];
;     const float* vb = base + 128 + kvh * 64 + lane;
; #pragma unroll
;     for (int k = 0; k < 64; ++k) vv[k] = vb[(size_t)(k < nk ? k : 0) * 256];
; __device__ __forceinline__ void sample_task_part2(const Prm& P, Ctx& C, int b, int kvh, int ts) {
;     ...
;     seg_attend(Aw, (const float*)(uintptr_t)segb[16 + C.wave], kvh, 64, (64 * C.wave + lane) >= 1 + ts, qs, ptab, lane);
.LBB0_1574:
	v_readlane_b32 s0, v251, 29
	v_cmp_gt_i32_e64 s[46:47], 64, v98
	s_lshl_b32 s78, s33, 2
	v_mov_b32_e32 v0, s0
	ds_read_b64 v[66:67], v0 offset:128
	v_cndmask_b32_e64 v2, 0, v98, s[46:47]
	v_ashrrev_i32_e32 v3, 31, v2
	v_lshlrev_b64 v[2:3], 10, v[2:3]
	s_movk_i32 s0, 0x1000
	s_waitcnt lgkmcnt(0)
	v_lshl_add_u64 v[2:3], v[66:67], 0, v[2:3]
	v_lshl_add_u64 v[2:3], v[2:3], 0, s[78:79]
	global_load_dwordx4 v[62:65], v[2:3], off
	global_load_dwordx4 v[58:61], v[2:3], off offset:16
	global_load_dwordx4 v[54:57], v[2:3], off offset:32
	global_load_dwordx4 v[50:53], v[2:3], off offset:48
	global_load_dwordx4 v[46:49], v[2:3], off offset:64
	global_load_dwordx4 v[42:45], v[2:3], off offset:80
	global_load_dwordx4 v[38:41], v[2:3], off offset:96
	global_load_dwordx4 v[34:37], v[2:3], off offset:112
	global_load_dwordx4 v[30:33], v[2:3], off offset:128
	global_load_dwordx4 v[26:29], v[2:3], off offset:144
	global_load_dwordx4 v[22:25], v[2:3], off offset:160
	global_load_dwordx4 v[18:21], v[2:3], off offset:176
	global_load_dwordx4 v[10:13], v[2:3], off offset:192
	global_load_dwordx4 v[6:9], v[2:3], off offset:208
	global_load_dwordx4 v[14:17], v[2:3], off offset:224
	s_nop 0
	global_load_dwordx4 v[2:5], v[2:3], off offset:240
	v_lshl_add_u64 v[66:67], v[66:67], 0, s[78:79]
	v_lshl_add_u64 v[66:67], v[98:99], 2, v[66:67]
	v_add_co_u32_e64 v68, s[0:1], s0, v66
	global_load_dword v216, v[66:67], off offset:512
	global_load_dword v218, v[66:67], off offset:1536
	global_load_dword v220, v[66:67], off offset:2560
	global_load_dword v222, v[66:67], off offset:3584
	v_addc_co_u32_e64 v69, s[0:1], 0, v67, s[0:1]
	s_movk_i32 s0, 0x2000
	global_load_dword v224, v[68:69], off offset:512
	global_load_dword v226, v[68:69], off offset:1536
	global_load_dword v228, v[68:69], off offset:2560
	global_load_dword v230, v[68:69], off offset:3584
	v_add_co_u32_e64 v68, s[0:1], s0, v66
	v_cmp_lt_i32_e32 vcc, s25, v117
	s_nop 0
	v_addc_co_u32_e64 v69, s[0:1], 0, v67, s[0:1]
	s_movk_i32 s0, 0x3000
	global_load_dword v232, v[68:69], off offset:512
	global_load_dword v214, v[68:69], off offset:1536
	global_load_dword v212, v[68:69], off offset:2560
	global_load_dword v208, v[68:69], off offset:3584
	v_add_co_u32_e64 v68, s[0:1], s0, v66
	s_and_b64 vcc, s[46:47], vcc
	s_nop 0
	v_addc_co_u32_e64 v69, s[0:1], 0, v67, s[0:1]
	s_movk_i32 s0, 0x4000
	global_load_dword v210, v[68:69], off offset:512
	global_load_dword v206, v[68:69], off offset:1536
	global_load_dword v204, v[68:69], off offset:2560
	global_load_dword v200, v[68:69], off offset:3584
	v_add_co_u32_e64 v68, s[0:1], s0, v66
	v_readlane_b32 s2, v250, 62
	s_nop 0
	v_addc_co_u32_e64 v69, s[0:1], 0, v67, s[0:1]
	s_movk_i32 s0, 0x5000
	global_load_dword v202, v[68:69], off offset:512
	global_load_dword v198, v[68:69], off offset:1536
	global_load_dword v196, v[68:69], off offset:2560
	global_load_dword v194, v[68:69], off offset:3584
	v_add_co_u32_e64 v68, s[0:1], s0, v66
	v_readlane_b32 s3, v250, 63
	s_nop 0
	v_addc_co_u32_e64 v69, s[0:1], 0, v67, s[0:1]
	s_movk_i32 s0, 0x6000
	global_load_dword v172, v[68:69], off offset:512
	global_load_dword v174, v[68:69], off offset:1536
	global_load_dword v176, v[68:69], off offset:2560
	global_load_dword v178, v[68:69], off offset:3584
	v_add_co_u32_e64 v68, s[0:1], s0, v66
	s_nop 1
	v_addc_co_u32_e64 v69, s[0:1], 0, v67, s[0:1]
	s_movk_i32 s0, 0x7000
	global_load_dword v180, v[68:69], off offset:512
	global_load_dword v182, v[68:69], off offset:1536
	global_load_dword v184, v[68:69], off offset:2560
	global_load_dword v186, v[68:69], off offset:3584
	v_add_co_u32_e64 v68, s[0:1], s0, v66
	s_nop 1
	v_addc_co_u32_e64 v69, s[0:1], 0, v67, s[0:1]
	s_mov_b32 s0, 0x8000
	global_load_dword v188, v[68:69], off offset:512
	global_load_dword v190, v[68:69], off offset:1536
	global_load_dword v192, v[68:69], off offset:2560
	global_load_dword v144, v[68:69], off offset:3584
	v_add_co_u32_e64 v68, s[0:1], s0, v66
	s_nop 1
	v_addc_co_u32_e64 v69, s[0:1], 0, v67, s[0:1]
	s_mov_b32 s0, 0x9000
	global_load_dword v170, v[68:69], off offset:512
	global_load_dword v142, v[68:69], off offset:1536
	global_load_dword v140, v[68:69], off offset:2560
	global_load_dword v136, v[68:69], off offset:3584
	v_add_co_u32_e64 v68, s[0:1], s0, v66
	s_nop 1
	v_addc_co_u32_e64 v69, s[0:1], 0, v67, s[0:1]
	s_mov_b32 s0, 0xa000
	global_load_dword v138, v[68:69], off offset:512
	global_load_dword v134, v[68:69], off offset:1536
	global_load_dword v132, v[68:69], off offset:2560
	global_load_dword v128, v[68:69], off offset:3584
	v_add_co_u32_e64 v68, s[0:1], s0, v66
	s_nop 1
	v_addc_co_u32_e64 v69, s[0:1], 0, v67, s[0:1]
	s_mov_b32 s0, 0xb000
	global_load_dword v130, v[68:69], off offset:512
	global_load_dword v126, v[68:69], off offset:1536
	global_load_dword v90, v[68:69], off offset:2560
	global_load_dword v92, v[68:69], off offset:3584
	v_add_co_u32_e64 v68, s[0:1], s0, v66
	s_nop 1
	v_addc_co_u32_e64 v69, s[0:1], 0, v67, s[0:1]
	s_mov_b32 s0, 0xc000
	global_load_dword v94, v[68:69], off offset:512
	global_load_dword v96, v[68:69], off offset:1536
	global_load_dword v112, v[68:69], off offset:2560
	global_load_dword v114, v[68:69], off offset:3584
	v_add_co_u32_e64 v68, s[0:1], s0, v66
	s_nop 1
	v_addc_co_u32_e64 v69, s[0:1], 0, v67, s[0:1]
	s_mov_b32 s0, 0xd000
	global_load_dword v116, v[68:69], off offset:512
	global_load_dword v118, v[68:69], off offset:1536
	global_load_dword v120, v[68:69], off offset:2560
	global_load_dword v122, v[68:69], off offset:3584
	v_add_co_u32_e64 v68, s[0:1], s0, v66
	s_nop 1
	v_addc_co_u32_e64 v69, s[0:1], 0, v67, s[0:1]
	s_mov_b32 s0, 0xe000
	global_load_dword v124, v[68:69], off offset:512
	global_load_dword v88, v[68:69], off offset:1536
	global_load_dword v86, v[68:69], off offset:2560
	global_load_dword v82, v[68:69], off offset:3584
	v_add_co_u32_e64 v68, s[0:1], s0, v66
	s_nop 1
	v_addc_co_u32_e64 v69, s[0:1], 0, v67, s[0:1]
	s_mov_b32 s0, 0xf000
	s_nop 0
	v_add_co_u32_e64 v66, s[0:1], s0, v66
	global_load_dword v84, v[68:69], off offset:512
	global_load_dword v80, v[68:69], off offset:1536
	global_load_dword v78, v[68:69], off offset:2560
	global_load_dword v74, v[68:69], off offset:3584
	v_addc_co_u32_e64 v67, s[0:1], 0, v67, s[0:1]
	global_load_dword v76, v[66:67], off offset:512
	global_load_dword v72, v[66:67], off offset:1536
	global_load_dword v70, v[66:67], off offset:2560
	global_load_dword v0, v[66:67], off offset:3584
	ds_read_b128 v[66:69], v1 offset:55296
	ds_read_b128 v[234:237], v1 offset:55312
	ds_read_b128 v[238:241], v1 offset:55328
	ds_read_b128 v[242:245], v1 offset:55344
	s_waitcnt vmcnt(0) lgkmcnt(0)
; #define LAS __attribute__((address_space(3)))
; __device__ __forceinline__ void seg_attend(SegAcc& A, const float* base, int kvh, int nk, bool valid, const LAS float* qs, LAS float* pt, int lane) {
;     ...
;     float s[4] = {0.f, 0.f, 0.f, 0.f};
; #pragma unroll
;     for (int c4 = 0; c4 < 16; ++c4)
; #pragma unroll
;         for (int gq = 0; gq < 4; ++gq) { const f32x4 qv = *(const LAS f32x4*)(qs + gq * 64 + 4 * c4); s[gq] += kv[c4][0] * qv[0] + kv[c4][1] * qv[1] + kv[c4][2] * qv[2] + kv[c4][3] * qv[3]; }
	ds_read_b128 v[146:149], v1 offset:55552
	ds_read_b128 v[150:153], v1 offset:55808
	ds_read_b128 v[154:157], v1 offset:56064
	ds_read_b128 v[158:161], v1 offset:55568
	ds_read_b128 v[162:165], v1 offset:55824
	s_waitcnt lgkmcnt(4)
	ds_read_b128 v[166:169], v1 offset:56080
	v_mul_f32_e32 v67, v63, v67
	v_fmac_f32_e32 v67, v62, v66
	v_fmac_f32_e32 v67, v64, v68
	v_fmac_f32_e32 v67, v65, v69
	v_add_f32_e32 v73, 0, v67
	v_mul_f32_e32 v67, v63, v147
	v_fmac_f32_e32 v67, v62, v146
	v_fmac_f32_e32 v67, v64, v148
	v_fmac_f32_e32 v67, v65, v149
	s_waitcnt lgkmcnt(4)
	ds_read_b128 v[146:149], v1 offset:55584
	v_add_f32_e32 v75, 0, v67
	v_mul_f32_e32 v67, v63, v151
	v_fmac_f32_e32 v67, v62, v150
	v_fmac_f32_e32 v67, v64, v152
	v_fmac_f32_e32 v67, v65, v153
	s_waitcnt lgkmcnt(4)
	ds_read_b128 v[150:153], v1 offset:55840
	v_add_f32_e32 v77, 0, v67
	v_mul_f32_e32 v63, v63, v155
	v_fmac_f32_e32 v63, v62, v154
	v_mul_f32_e32 v62, v59, v235
	v_fmac_f32_e32 v62, v58, v234
	v_fmac_f32_e32 v63, v64, v156
	v_fmac_f32_e32 v62, v60, v236
	v_fmac_f32_e32 v63, v65, v157
	s_waitcnt lgkmcnt(4)
	ds_read_b128 v[154:157], v1 offset:56096
	v_fmac_f32_e32 v62, v61, v237
	v_add_f32_e32 v66, 0, v63
	v_add_f32_e32 v67, v73, v62
	v_mul_f32_e32 v63, v59, v159
	v_fmac_f32_e32 v63, v58, v158
	v_fmac_f32_e32 v63, v60, v160
	v_fmac_f32_e32 v63, v61, v161
	s_waitcnt lgkmcnt(4)
	ds_read_b128 v[158:161], v1 offset:55600
	v_add_f32_e32 v68, v75, v63
	v_mul_f32_e32 v63, v59, v163
	v_fmac_f32_e32 v63, v58, v162
	v_fmac_f32_e32 v63, v60, v164
	v_fmac_f32_e32 v63, v61, v165
	s_waitcnt lgkmcnt(4)
	ds_read_b128 v[162:165], v1 offset:55856
	v_add_f32_e32 v69, v77, v63
	v_mul_f32_e32 v59, v59, v167
	v_fmac_f32_e32 v59, v58, v166
	v_mul_f32_e32 v58, v55, v239
	v_fmac_f32_e32 v58, v54, v238
	v_fmac_f32_e32 v59, v60, v168
	v_fmac_f32_e32 v58, v56, v240
	v_fmac_f32_e32 v59, v61, v169
	s_waitcnt lgkmcnt(4)
	ds_read_b128 v[166:169], v1 offset:56112
	v_fmac_f32_e32 v58, v57, v241
	v_add_f32_e32 v62, v66, v59
	v_add_f32_e32 v63, v67, v58
	v_mul_f32_e32 v59, v55, v147
	v_fmac_f32_e32 v59, v54, v146
	v_fmac_f32_e32 v59, v56, v148
	v_fmac_f32_e32 v59, v57, v149
	s_waitcnt lgkmcnt(4)
	ds_read_b128 v[146:149], v1 offset:55360
	v_add_f32_e32 v64, v68, v59
	v_mul_f32_e32 v59, v55, v151
	v_fmac_f32_e32 v59, v54, v150
	v_fmac_f32_e32 v59, v56, v152
	v_fmac_f32_e32 v59, v57, v153
	s_waitcnt lgkmcnt(4)
	ds_read_b128 v[150:153], v1 offset:55616
	v_add_f32_e32 v65, v69, v59
	v_mul_f32_e32 v55, v55, v155
	v_fmac_f32_e32 v55, v54, v154
	v_mul_f32_e32 v54, v51, v243
	v_fmac_f32_e32 v54, v50, v242
	v_fmac_f32_e32 v55, v56, v156
	v_fmac_f32_e32 v54, v52, v244
	v_fmac_f32_e32 v55, v57, v157
	s_waitcnt lgkmcnt(4)
	ds_read_b128 v[154:157], v1 offset:55872
	v_fmac_f32_e32 v54, v53, v245
	v_add_f32_e32 v58, v62, v55
	v_add_f32_e32 v59, v63, v54
	v_mul_f32_e32 v55, v51, v159
	v_fmac_f32_e32 v55, v50, v158
	v_fmac_f32_e32 v55, v52, v160
	v_fmac_f32_e32 v55, v53, v161
	s_waitcnt lgkmcnt(4)
	ds_read_b128 v[158:161], v1 offset:56128
	v_add_f32_e32 v60, v64, v55
	v_mul_f32_e32 v55, v51, v163
	v_fmac_f32_e32 v55, v50, v162
	v_fmac_f32_e32 v55, v52, v164
	v_fmac_f32_e32 v55, v53, v165
	s_waitcnt lgkmcnt(4)
	ds_read_b128 v[162:165], v1 offset:55376
	v_add_f32_e32 v61, v65, v55
	v_mul_f32_e32 v51, v51, v167
	v_fmac_f32_e32 v51, v50, v166
	v_fmac_f32_e32 v51, v52, v168
	v_fmac_f32_e32 v51, v53, v169
	s_waitcnt lgkmcnt(4)
	ds_read_b128 v[166:169], v1 offset:55632
	v_add_f32_e32 v54, v58, v51
	v_mul_f32_e32 v51, v47, v147
	v_fmac_f32_e32 v51, v46, v146
	v_fmac_f32_e32 v51, v48, v148
	v_fmac_f32_e32 v51, v49, v149
	s_waitcnt lgkmcnt(4)
	ds_read_b128 v[146:149], v1 offset:55888
	v_add_f32_e32 v55, v59, v51
	v_mul_f32_e32 v51, v47, v151
	v_fmac_f32_e32 v51, v46, v150
	v_fmac_f32_e32 v51, v48, v152
	v_fmac_f32_e32 v51, v49, v153
	s_waitcnt lgkmcnt(4)
	ds_read_b128 v[150:153], v1 offset:56144
	v_add_f32_e32 v56, v60, v51
	v_mul_f32_e32 v51, v47, v155
	v_fmac_f32_e32 v51, v46, v154
	v_fmac_f32_e32 v51, v48, v156
	v_fmac_f32_e32 v51, v49, v157
	s_waitcnt lgkmcnt(4)
	ds_read_b128 v[154:157], v1 offset:55392
	v_add_f32_e32 v57, v61, v51
	v_mul_f32_e32 v47, v47, v159
	v_fmac_f32_e32 v47, v46, v158
	v_fmac_f32_e32 v47, v48, v160
	v_fmac_f32_e32 v47, v49, v161
	s_waitcnt lgkmcnt(4)
	ds_read_b128 v[158:161], v1 offset:55648
	v_add_f32_e32 v50, v54, v47
	v_mov_b32_e32 v54, v30
	v_mul_f32_e32 v47, v43, v163
	v_fmac_f32_e32 v47, v42, v162
	v_fmac_f32_e32 v47, v44, v164
	v_fmac_f32_e32 v47, v45, v165
	s_waitcnt lgkmcnt(4)
	ds_read_b128 v[162:165], v1 offset:55904
	v_add_f32_e32 v51, v55, v47
	v_mov_b32_e32 v55, v26
	v_mov_b32_e32 v26, v31
	v_mul_f32_e32 v47, v43, v167
	v_fmac_f32_e32 v47, v42, v166
	v_fmac_f32_e32 v47, v44, v168
	v_fmac_f32_e32 v47, v45, v169
	s_waitcnt lgkmcnt(4)
	ds_read_b128 v[166:169], v1 offset:56160
	v_add_f32_e32 v52, v56, v47
	v_mul_f32_e32 v47, v43, v147
	v_fmac_f32_e32 v47, v42, v146
	v_fmac_f32_e32 v47, v44, v148
	v_fmac_f32_e32 v47, v45, v149
	s_waitcnt lgkmcnt(4)
	ds_read_b128 v[146:149], v1 offset:55408
	v_add_f32_e32 v53, v57, v47
	v_mul_f32_e32 v43, v43, v151
	v_fmac_f32_e32 v43, v42, v150
	v_fmac_f32_e32 v43, v44, v152
	v_fmac_f32_e32 v43, v45, v153
	s_waitcnt lgkmcnt(4)
	ds_read_b128 v[150:153], v1 offset:55664
	v_add_f32_e32 v46, v50, v43
	v_mul_f32_e32 v43, v39, v155
	v_fmac_f32_e32 v43, v38, v154
	v_fmac_f32_e32 v43, v40, v156
	v_fmac_f32_e32 v43, v41, v157
	s_waitcnt lgkmcnt(4)
	ds_read_b128 v[154:157], v1 offset:55920
	v_add_f32_e32 v47, v51, v43
	v_mul_f32_e32 v43, v39, v159
	v_fmac_f32_e32 v43, v38, v158
	v_fmac_f32_e32 v43, v40, v160
	v_fmac_f32_e32 v43, v41, v161
	s_waitcnt lgkmcnt(4)
; #define LAS __attribute__((address_space(3)))
; __device__ __forceinline__ void seg_attend(SegAcc& A, const float* base, int kvh, int nk, bool valid, const LAS float* qs, LAS float* pt, int lane) {
;     ...
;     float s[4] = {0.f, 0.f, 0.f, 0.f};
; #pragma unroll
;     for (int c4 = 0; c4 < 16; ++c4)
; #pragma unroll
;         for (int gq = 0; gq < 4; ++gq) { const f32x4 qv = *(const LAS f32x4*)(qs + gq * 64 + 4 * c4); s[gq] += kv[c4][0] * qv[0] + kv[c4][1] * qv[1] + kv[c4][2] * qv[2] + kv[c4][3] * qv[3]; }
	ds_read_b128 v[158:161], v1 offset:56176
	v_add_f32_e32 v48, v52, v43
	v_mul_f32_e32 v43, v39, v163
	v_fmac_f32_e32 v43, v38, v162
	v_fmac_f32_e32 v43, v40, v164
	v_fmac_f32_e32 v43, v41, v165
	s_waitcnt lgkmcnt(4)
	ds_read_b128 v[162:165], v1 offset:55424
	v_add_f32_e32 v49, v53, v43
	v_mul_f32_e32 v39, v39, v167
	v_fmac_f32_e32 v39, v38, v166
	v_fmac_f32_e32 v39, v40, v168
	v_fmac_f32_e32 v39, v41, v169
	s_waitcnt lgkmcnt(4)
	ds_read_b128 v[166:169], v1 offset:55680
	v_add_f32_e32 v42, v46, v39
	v_mul_f32_e32 v39, v35, v147
	v_fmac_f32_e32 v39, v34, v146
	v_fmac_f32_e32 v39, v36, v148
	v_fmac_f32_e32 v39, v37, v149
	s_waitcnt lgkmcnt(4)
	ds_read_b128 v[146:149], v1 offset:55936
	v_add_f32_e32 v58, v47, v39
	v_mul_f32_e32 v39, v35, v151
	v_fmac_f32_e32 v39, v34, v150
	v_fmac_f32_e32 v39, v36, v152
	v_fmac_f32_e32 v39, v37, v153
	s_waitcnt lgkmcnt(4)
	ds_read_b128 v[150:153], v1 offset:56192
	v_add_f32_e32 v59, v48, v39
	v_mul_f32_e32 v39, v35, v155
	v_fmac_f32_e32 v39, v34, v154
	v_fmac_f32_e32 v39, v36, v156
	v_fmac_f32_e32 v39, v37, v157
	s_waitcnt lgkmcnt(4)
	ds_read_b128 v[154:157], v1 offset:55440
	v_add_f32_e32 v60, v49, v39
	v_mul_f32_e32 v35, v35, v159
	v_fmac_f32_e32 v35, v34, v158
	v_fmac_f32_e32 v35, v36, v160
	v_fmac_f32_e32 v35, v37, v161
	s_waitcnt lgkmcnt(4)
	ds_read_b128 v[158:161], v1 offset:55696
	v_add_f32_e32 v61, v42, v35
	v_mov_b32_e32 v56, v162
	v_mov_b32_e32 v34, v32
	s_waitcnt lgkmcnt(1)
	v_mov_b32_e32 v57, v154
	v_mov_b32_e32 v50, v163
	v_mov_b32_e32 v51, v155
	v_pk_mul_f32 v[30:31], v[26:27], v[50:51]
	v_mov_b32_e32 v35, v28
	v_pk_fma_f32 v[30:31], v[54:55], v[56:57], v[30:31]
	v_mov_b32_e32 v50, v164
	v_mov_b32_e32 v51, v156
	v_pk_fma_f32 v[30:31], v[34:35], v[50:51], v[30:31]
	v_mov_b32_e32 v28, v33
	v_mov_b32_e32 v52, v165
	ds_read_b128 v[162:165], v1 offset:55952
	v_mov_b32_e32 v53, v157
	ds_read_b128 v[154:157], v1 offset:56208
	v_pk_fma_f32 v[30:31], v[28:29], v[52:53], v[30:31]
	v_mov_b32_e32 v36, v166
	v_add_f32_e32 v30, v58, v30
	v_add_f32_e32 v50, v30, v31
	s_waitcnt lgkmcnt(2)
	v_mov_b32_e32 v37, v158
	v_mov_b32_e32 v30, v167
	v_mov_b32_e32 v31, v159
	v_pk_mul_f32 v[30:31], v[26:27], v[30:31]
	s_nop 0
	v_pk_fma_f32 v[30:31], v[54:55], v[36:37], v[30:31]
	v_mov_b32_e32 v36, v168
	v_mov_b32_e32 v37, v160
	v_pk_fma_f32 v[30:31], v[34:35], v[36:37], v[30:31]
	v_mov_b32_e32 v32, v169
	ds_read_b128 v[166:169], v1 offset:55456
	v_mov_b32_e32 v33, v161
	ds_read_b128 v[158:161], v1 offset:55712
	v_pk_fma_f32 v[30:31], v[28:29], v[32:33], v[30:31]
	v_mov_b32_e32 v36, v146
	v_add_f32_e32 v30, v59, v30
	v_add_f32_e32 v51, v30, v31
	s_waitcnt lgkmcnt(3)
	v_mov_b32_e32 v37, v162
	v_mov_b32_e32 v30, v147
	v_mov_b32_e32 v31, v163
	v_pk_mul_f32 v[30:31], v[26:27], v[30:31]
	s_nop 0
	v_pk_fma_f32 v[30:31], v[54:55], v[36:37], v[30:31]
	v_mov_b32_e32 v36, v148
	v_mov_b32_e32 v37, v164
	v_pk_fma_f32 v[30:31], v[34:35], v[36:37], v[30:31]
	v_mov_b32_e32 v32, v149
	ds_read_b128 v[146:149], v1 offset:55968
	v_mov_b32_e32 v33, v165
	ds_read_b128 v[162:165], v1 offset:56224
	v_pk_fma_f32 v[30:31], v[28:29], v[32:33], v[30:31]
	v_mov_b32_e32 v36, v150
	v_add_f32_e32 v30, v60, v30
	v_add_f32_e32 v52, v30, v31
	v_mov_b32_e32 v46, v22
	s_waitcnt lgkmcnt(4)
	v_mov_b32_e32 v37, v154
	v_mov_b32_e32 v30, v151
	v_mov_b32_e32 v31, v155
	v_pk_mul_f32 v[26:27], v[26:27], v[30:31]
	v_mov_b32_e32 v30, v152
	v_pk_fma_f32 v[26:27], v[54:55], v[36:37], v[26:27]
	v_mov_b32_e32 v31, v156
	v_pk_fma_f32 v[26:27], v[34:35], v[30:31], v[26:27]
	v_mov_b32_e32 v32, v153
	ds_read_b128 v[150:153], v1 offset:55472
	v_mov_b32_e32 v33, v157
	s_waitcnt lgkmcnt(4)
	ds_read_b128 v[154:157], v1 offset:55728
	v_pk_fma_f32 v[26:27], v[28:29], v[32:33], v[26:27]
	v_mov_b32_e32 v47, v18
	v_add_f32_e32 v26, v61, v26
	v_add_f32_e32 v53, v26, v27
	v_mov_b32_e32 v18, v23
	v_mov_b32_e32 v48, v166
	v_mov_b32_e32 v26, v24
	s_waitcnt lgkmcnt(1)
	v_mov_b32_e32 v49, v150
	v_mov_b32_e32 v42, v167
	v_mov_b32_e32 v43, v151
	v_pk_mul_f32 v[22:23], v[18:19], v[42:43]
	v_mov_b32_e32 v27, v20
	v_pk_fma_f32 v[22:23], v[46:47], v[48:49], v[22:23]
	v_mov_b32_e32 v42, v168
	v_mov_b32_e32 v43, v152
	v_pk_fma_f32 v[22:23], v[26:27], v[42:43], v[22:23]
	v_mov_b32_e32 v20, v25
	v_mov_b32_e32 v44, v169
	ds_read_b128 v[166:169], v1 offset:55984
	v_mov_b32_e32 v45, v153
	ds_read_b128 v[150:153], v1 offset:56240
	v_pk_fma_f32 v[22:23], v[20:21], v[44:45], v[22:23]
	v_mov_b32_e32 v28, v158
	v_add_f32_e32 v22, v50, v22
	v_add_f32_e32 v42, v22, v23
	s_waitcnt lgkmcnt(2)
	v_mov_b32_e32 v29, v154
	v_mov_b32_e32 v22, v159
	v_mov_b32_e32 v23, v155
	v_pk_mul_f32 v[22:23], v[18:19], v[22:23]
	s_nop 0
	v_pk_fma_f32 v[22:23], v[46:47], v[28:29], v[22:23]
	v_mov_b32_e32 v28, v160
	v_mov_b32_e32 v29, v156
	v_pk_fma_f32 v[22:23], v[26:27], v[28:29], v[22:23]
	v_mov_b32_e32 v24, v161
	ds_read_b128 v[158:161], v1 offset:55488
	v_mov_b32_e32 v25, v157
	ds_read_b128 v[154:157], v1 offset:55744
	v_pk_fma_f32 v[22:23], v[20:21], v[24:25], v[22:23]
	v_mov_b32_e32 v28, v146
	v_add_f32_e32 v22, v51, v22
	v_add_f32_e32 v43, v22, v23
	s_waitcnt lgkmcnt(3)
	v_mov_b32_e32 v29, v166
	v_mov_b32_e32 v22, v147
	v_mov_b32_e32 v23, v167
	v_pk_mul_f32 v[22:23], v[18:19], v[22:23]
	s_nop 0
	v_pk_fma_f32 v[22:23], v[46:47], v[28:29], v[22:23]
	v_mov_b32_e32 v28, v148
	v_mov_b32_e32 v29, v168
	v_pk_fma_f32 v[22:23], v[26:27], v[28:29], v[22:23]
	v_mov_b32_e32 v24, v149
	ds_read_b128 v[146:149], v1 offset:56000
	v_mov_b32_e32 v25, v169
	ds_read_b128 v[166:169], v1 offset:56256
	v_pk_fma_f32 v[22:23], v[20:21], v[24:25], v[22:23]
	v_mov_b32_e32 v28, v162
	v_add_f32_e32 v22, v52, v22
	v_add_f32_e32 v44, v22, v23
	s_waitcnt lgkmcnt(4)
; #define LAS __attribute__((address_space(3)))
; __device__ __forceinline__ void seg_attend(SegAcc& A, const float* base, int kvh, int nk, bool valid, const LAS float* qs, LAS float* pt, int lane) {
;     ...
;     float s[4] = {0.f, 0.f, 0.f, 0.f};
; #pragma unroll
;     for (int c4 = 0; c4 < 16; ++c4)
; #pragma unroll
;         for (int gq = 0; gq < 4; ++gq) { const f32x4 qv = *(const LAS f32x4*)(qs + gq * 64 + 4 * c4); s[gq] += kv[c4][0] * qv[0] + kv[c4][1] * qv[1] + kv[c4][2] * qv[2] + kv[c4][3] * qv[3]; }
	v_mov_b32_e32 v29, v150
	v_mov_b32_e32 v22, v163
	v_mov_b32_e32 v23, v151
	v_pk_mul_f32 v[18:19], v[18:19], v[22:23]
	v_mov_b32_e32 v22, v164
	v_pk_fma_f32 v[18:19], v[46:47], v[28:29], v[18:19]
	v_mov_b32_e32 v23, v152
	v_pk_fma_f32 v[18:19], v[26:27], v[22:23], v[18:19]
	v_mov_b32_e32 v24, v165
	ds_read_b128 v[162:165], v1 offset:55504
	v_mov_b32_e32 v25, v153
	s_waitcnt lgkmcnt(4)
	ds_read_b128 v[150:153], v1 offset:55760
	v_pk_fma_f32 v[18:19], v[20:21], v[24:25], v[18:19]
	v_mov_b32_e32 v41, v6
	v_add_f32_e32 v18, v53, v18
	v_add_f32_e32 v45, v18, v19
	v_mov_b32_e32 v6, v11
	v_mov_b32_e32 v40, v10
	v_mov_b32_e32 v30, v158
	v_mov_b32_e32 v18, v12
	s_waitcnt lgkmcnt(1)
	v_mov_b32_e32 v31, v162
	v_mov_b32_e32 v36, v159
	v_mov_b32_e32 v37, v163
	v_pk_mul_f32 v[10:11], v[6:7], v[36:37]
	v_mov_b32_e32 v19, v8
	v_pk_fma_f32 v[10:11], v[40:41], v[30:31], v[10:11]
	v_mov_b32_e32 v30, v160
	v_mov_b32_e32 v31, v164
	v_pk_fma_f32 v[10:11], v[18:19], v[30:31], v[10:11]
	v_mov_b32_e32 v8, v13
	v_mov_b32_e32 v38, v161
	ds_read_b128 v[158:161], v1 offset:56016
	v_mov_b32_e32 v39, v165
	v_pk_fma_f32 v[10:11], v[8:9], v[38:39], v[10:11]
	v_mov_b32_e32 v20, v154
	v_add_f32_e32 v10, v42, v10
	v_add_f32_e32 v31, v10, v11
	s_waitcnt lgkmcnt(1)
	v_mov_b32_e32 v21, v150
	v_mov_b32_e32 v10, v155
	v_mov_b32_e32 v11, v151
	v_pk_mul_f32 v[10:11], v[6:7], v[10:11]
	s_nop 0
	v_pk_fma_f32 v[10:11], v[40:41], v[20:21], v[10:11]
	v_mov_b32_e32 v20, v156
	v_mov_b32_e32 v21, v152
	v_pk_fma_f32 v[10:11], v[18:19], v[20:21], v[10:11]
	v_mov_b32_e32 v12, v157
	ds_read_b128 v[154:157], v1 offset:56272
	v_mov_b32_e32 v13, v153
	ds_read_b128 v[150:153], v1 offset:55520
	v_pk_fma_f32 v[10:11], v[8:9], v[12:13], v[10:11]
	v_mov_b32_e32 v20, v146
	v_add_f32_e32 v10, v43, v10
	v_add_f32_e32 v30, v10, v11
	v_mov_b32_e32 v26, v14
	s_waitcnt lgkmcnt(2)
	v_mov_b32_e32 v21, v158
	v_mov_b32_e32 v10, v147
	v_mov_b32_e32 v11, v159
	v_pk_mul_f32 v[10:11], v[6:7], v[10:11]
	v_mov_b32_e32 v27, v2
	v_pk_fma_f32 v[10:11], v[40:41], v[20:21], v[10:11]
	v_mov_b32_e32 v20, v148
	v_mov_b32_e32 v21, v160
	v_pk_fma_f32 v[10:11], v[18:19], v[20:21], v[10:11]
	v_mov_b32_e32 v12, v149
	ds_read_b128 v[146:149], v1 offset:55776
	v_mov_b32_e32 v13, v161
	ds_read_b128 v[158:161], v1 offset:56032
	v_pk_fma_f32 v[10:11], v[8:9], v[12:13], v[10:11]
	v_mov_b32_e32 v20, v166
	v_add_f32_e32 v10, v44, v10
	v_add_f32_e32 v29, v10, v11
	v_mov_b32_e32 v2, v15
	s_waitcnt lgkmcnt(3)
	v_mov_b32_e32 v21, v154
	v_mov_b32_e32 v10, v167
	v_mov_b32_e32 v11, v155
	v_pk_mul_f32 v[6:7], v[6:7], v[10:11]
	v_mov_b32_e32 v10, v168
	v_pk_fma_f32 v[6:7], v[40:41], v[20:21], v[6:7]
	v_mov_b32_e32 v11, v156
	v_pk_fma_f32 v[6:7], v[18:19], v[10:11], v[6:7]
	v_mov_b32_e32 v12, v169
	ds_read_b128 v[166:169], v1 offset:56288
	v_mov_b32_e32 v13, v157
	ds_read_b128 v[154:157], v1 offset:55536
	v_pk_fma_f32 v[6:7], v[8:9], v[12:13], v[6:7]
	s_nop 0
	v_add_f32_e32 v6, v45, v6
	v_add_f32_e32 v28, v6, v7
	s_waitcnt lgkmcnt(4)
	v_mov_b32_e32 v36, v150
	v_mov_b32_e32 v22, v16
	s_waitcnt lgkmcnt(0)
	v_mov_b32_e32 v37, v154
	v_mov_b32_e32 v32, v151
	v_mov_b32_e32 v33, v155
	v_pk_mul_f32 v[14:15], v[2:3], v[32:33]
	v_mov_b32_e32 v23, v4
	v_pk_fma_f32 v[14:15], v[26:27], v[36:37], v[14:15]
	v_mov_b32_e32 v32, v152
	v_mov_b32_e32 v33, v156
	v_pk_fma_f32 v[14:15], v[22:23], v[32:33], v[14:15]
	v_mov_b32_e32 v4, v17
	v_mov_b32_e32 v34, v153
	v_mov_b32_e32 v35, v157
	v_pk_fma_f32 v[14:15], v[4:5], v[34:35], v[14:15]
	v_mov_b32_e32 v32, v146
	v_add_f32_e32 v14, v31, v14
	v_add_f32_e32 v24, v14, v15
	ds_read_b128 v[14:17], v1 offset:55792
	v_mov_b32_e32 v18, v148
	v_mov_b32_e32 v20, v158
	s_waitcnt lgkmcnt(0)
	v_mov_b32_e32 v33, v14
	v_mov_b32_e32 v14, v147
	v_pk_mul_f32 v[14:15], v[2:3], v[14:15]
	v_mov_b32_e32 v19, v16
	v_pk_fma_f32 v[14:15], v[26:27], v[32:33], v[14:15]
	v_mov_b32_e32 v16, v149
	ds_read_b128 v[146:149], v1 offset:56048
	v_pk_fma_f32 v[14:15], v[22:23], v[18:19], v[14:15]
	s_nop 0
	v_pk_fma_f32 v[14:15], v[4:5], v[16:17], v[14:15]
	s_nop 0
	v_add_f32_e32 v14, v30, v14
	v_add_f32_e32 v18, v14, v15
	s_waitcnt lgkmcnt(0)
	v_mov_b32_e32 v21, v146
	v_mov_b32_e32 v14, v159
	v_mov_b32_e32 v15, v147
	v_pk_mul_f32 v[10:11], v[2:3], v[14:15]
	v_mov_b32_e32 v14, v160
	v_pk_fma_f32 v[10:11], v[26:27], v[20:21], v[10:11]
	v_mov_b32_e32 v15, v148
	v_pk_fma_f32 v[10:11], v[22:23], v[14:15], v[10:11]
	v_mov_b32_e32 v16, v161
	ds_read_b128 v[158:161], v1 offset:56304
	v_mov_b32_e32 v17, v149
	v_pk_fma_f32 v[10:11], v[4:5], v[16:17], v[10:11]
	v_mov_b32_e32 v14, v166
	v_add_f32_e32 v10, v29, v10
	v_add_f32_e32 v16, v10, v11
	v_mov_b32_e32 v6, v168
	s_waitcnt lgkmcnt(0)
; #define LAS __attribute__((address_space(3)))
; __device__ __forceinline__ float ex2(float x) { return __builtin_amdgcn_exp2f(x); }
; template <int CTRL> __device__ __forceinline__ float dpp_mov(float old, float x) { return __int_as_float(__builtin_amdgcn_update_dpp(__float_as_int(old), __float_as_int(x), CTRL, 0xF, 0xF, false)); }
; #define LDS_WAIT() asm volatile("s_waitcnt lgkmcnt(0)" ::: "memory")
; __device__ __forceinline__ float wave_max(float v) {
;     v = fmaxf(v, dpp_mov<0x111>(v, v)); v = fmaxf(v, dpp_mov<0x112>(v, v)); v = fmaxf(v, dpp_mov<0x114>(v, v)); v = fmaxf(v, dpp_mov<0x118>(v, v));
;     v = fmaxf(v, __int_as_float(__builtin_amdgcn_update_dpp(__float_as_int(v), __float_as_int(v), 0x142, 0xA, 0xF, false)));
;     v = fmaxf(v, __int_as_float(__builtin_amdgcn_update_dpp(__float_as_int(v), __float_as_int(v), 0x143, 0xC, 0xF, false)));
;     return __int_as_float(__builtin_amdgcn_readlane(__float_as_int(v), 63));
; }
; __device__ __forceinline__ void seg_attend(SegAcc& A, const float* base, int kvh, int nk, bool valid, const LAS float* qs, LAS float* pt, int lane) {
;     ...
;     valid = valid && lane < nk;
;     f32x4 p;
; #pragma unroll
;     for (int gq = 0; gq < 4; ++gq) { const float sv = valid ? s[gq] : NEGB; const float mx = wave_max(sv); const float mn = fmaxf(A.m[gq], mx), a = ex2(A.m[gq] - mn);
;         p[gq] = valid ? ex2(sv - mn) : 0.f; A.l[gq] = A.l[gq] * a + p[gq]; A.o[gq] *= a; A.m[gq] = mn; }
;     *(LAS f32x4*)(pt + 4 * lane) = p;
;     LDS_WAIT();
; #pragma unroll
;     for (int k = 0; k < 64; ++k) { const f32x4 pk = *(const LAS f32x4*)(pt + 4 * k);
	v_mov_b32_e32 v15, v158
	v_mov_b32_e32 v10, v167
	v_mov_b32_e32 v11, v159
	v_pk_mul_f32 v[2:3], v[2:3], v[10:11]
	v_mov_b32_e32 v7, v160
	v_pk_fma_f32 v[2:3], v[26:27], v[14:15], v[2:3]
	v_mov_b32_e32 v12, v169
	v_pk_fma_f32 v[2:3], v[22:23], v[6:7], v[2:3]
	s_nop 0
	v_mov_b32_e32 v13, v161
	v_pk_fma_f32 v[2:3], v[4:5], v[12:13], v[2:3]
	s_nop 0
	v_add_f32_e32 v2, v28, v2
	v_add_f32_e32 v2, v2, v3
	v_cndmask_b32_e32 v3, v209, v24, vcc
	v_mov_b32_e32 v4, v3
	v_cndmask_b32_e32 v2, v209, v2, vcc
	s_nop 0
	v_mov_b32_dpp v4, v4 row_shr:1 row_mask:0xf bank_mask:0xf
	v_max_f32_e32 v4, v4, v4
	v_max_f32_e32 v4, v3, v4
	v_mov_b32_e32 v5, v4
	s_nop 1
	v_mov_b32_dpp v5, v5 row_shr:2 row_mask:0xf bank_mask:0xf
	v_max_f32_e32 v5, v5, v5
	v_max_f32_e32 v4, v4, v5
	v_mov_b32_e32 v5, v4
	s_nop 1
	v_mov_b32_dpp v5, v5 row_shr:4 row_mask:0xf bank_mask:0xf
	v_max_f32_e32 v5, v5, v5
	v_max_f32_e32 v4, v4, v5
	v_mov_b32_e32 v5, v4
	s_nop 1
	v_mov_b32_dpp v5, v5 row_shr:8 row_mask:0xf bank_mask:0xf
	v_max_f32_e32 v5, v5, v5
	v_max_f32_e32 v4, v4, v5
	v_mov_b32_e32 v5, v4
	s_nop 1
	v_mov_b32_dpp v5, v5 row_bcast:15 row_mask:0xa bank_mask:0xf
	v_max_f32_e32 v5, v5, v5
	v_max_f32_e32 v4, v4, v5
	v_mov_b32_e32 v5, v4
	s_nop 1
	v_mov_b32_dpp v5, v5 row_bcast:31 row_mask:0xc bank_mask:0xf
	v_max_f32_e32 v5, v5, v5
	v_max_f32_e32 v4, v4, v5
	s_nop 0
	v_readlane_b32 s0, v4, 63
	s_nop 1
	v_max_f32_e64 v4, s0, s0
	v_max_f32_e32 v240, 0xf149f2ca, v4
	v_sub_f32_e32 v3, v3, v240
	v_exp_f32_e32 v3, v3
	v_sub_f32_e32 v4, 0xf149f2ca, v240
	v_exp_f32_e32 v44, v4
	v_cndmask_b32_e32 v4, 0, v3, vcc
	v_cndmask_b32_e32 v3, v209, v18, vcc
	v_mov_b32_e32 v5, v3
	s_nop 1
	v_mov_b32_dpp v5, v5 row_shr:1 row_mask:0xf bank_mask:0xf
	v_max_f32_e32 v5, v5, v5
	v_max_f32_e32 v5, v3, v5
	v_mov_b32_e32 v6, v5
	s_nop 1
	v_mov_b32_dpp v6, v6 row_shr:2 row_mask:0xf bank_mask:0xf
	v_max_f32_e32 v6, v6, v6
	v_max_f32_e32 v5, v5, v6
	v_mov_b32_e32 v6, v5
	s_nop 1
	v_mov_b32_dpp v6, v6 row_shr:4 row_mask:0xf bank_mask:0xf
	v_max_f32_e32 v6, v6, v6
	v_max_f32_e32 v5, v5, v6
	v_mov_b32_e32 v6, v5
	s_nop 1
	v_mov_b32_dpp v6, v6 row_shr:8 row_mask:0xf bank_mask:0xf
	v_max_f32_e32 v6, v6, v6
	v_max_f32_e32 v5, v5, v6
	v_mov_b32_e32 v6, v5
	s_nop 1
	v_mov_b32_dpp v6, v6 row_bcast:15 row_mask:0xa bank_mask:0xf
	v_max_f32_e32 v6, v6, v6
	v_max_f32_e32 v5, v5, v6
	v_mov_b32_e32 v6, v5
	s_nop 1
	v_mov_b32_dpp v6, v6 row_bcast:31 row_mask:0xc bank_mask:0xf
	v_max_f32_e32 v6, v6, v6
	v_max_f32_e32 v5, v5, v6
	s_nop 0
	v_readlane_b32 s0, v5, 63
	s_nop 1
	v_max_f32_e64 v5, s0, s0
	v_max_f32_e32 v238, 0xf149f2ca, v5
	v_sub_f32_e32 v3, v3, v238
	v_exp_f32_e32 v3, v3
	v_sub_f32_e32 v5, 0xf149f2ca, v238
	v_exp_f32_e32 v45, v5
	v_cndmask_b32_e32 v5, 0, v3, vcc
	v_cndmask_b32_e32 v3, v209, v16, vcc
	v_mov_b32_e32 v6, v3
	v_pk_mul_f32 v[44:45], v[44:45], 0 op_sel_hi:[1,0]
	s_nop 0
	v_mov_b32_dpp v6, v6 row_shr:1 row_mask:0xf bank_mask:0xf
	v_max_f32_e32 v6, v6, v6
	v_max_f32_e32 v6, v3, v6
	v_mov_b32_e32 v7, v6
	v_add_f32_e32 v111, v44, v4
	v_add_f32_e32 v123, v45, v5
	v_mov_b32_dpp v7, v7 row_shr:2 row_mask:0xf bank_mask:0xf
	v_max_f32_e32 v7, v7, v7
	v_max_f32_e32 v6, v6, v7
	v_mov_b32_e32 v7, v6
	s_nop 1
	v_mov_b32_dpp v7, v7 row_shr:4 row_mask:0xf bank_mask:0xf
	v_max_f32_e32 v7, v7, v7
	v_max_f32_e32 v6, v6, v7
	v_mov_b32_e32 v7, v6
	s_nop 1
	v_mov_b32_dpp v7, v7 row_shr:8 row_mask:0xf bank_mask:0xf
	v_max_f32_e32 v7, v7, v7
	v_max_f32_e32 v6, v6, v7
	v_mov_b32_e32 v7, v6
	s_nop 1
	v_mov_b32_dpp v7, v7 row_bcast:15 row_mask:0xa bank_mask:0xf
	v_max_f32_e32 v7, v7, v7
	v_max_f32_e32 v6, v6, v7
	v_mov_b32_e32 v7, v6
	s_nop 1
	v_mov_b32_dpp v7, v7 row_bcast:31 row_mask:0xc bank_mask:0xf
	v_max_f32_e32 v7, v7, v7
	v_max_f32_e32 v6, v6, v7
	s_nop 0
	v_readlane_b32 s0, v6, 63
	s_nop 1
	v_max_f32_e64 v6, s0, s0
	v_max_f32_e32 v236, 0xf149f2ca, v6
	v_sub_f32_e32 v3, v3, v236
	v_exp_f32_e32 v3, v3
	v_sub_f32_e32 v6, 0xf149f2ca, v236
	v_exp_f32_e32 v46, v6
	v_cndmask_b32_e32 v6, 0, v3, vcc
	v_mov_b32_e32 v3, v2
	s_nop 1
	v_mov_b32_dpp v3, v3 row_shr:1 row_mask:0xf bank_mask:0xf
	v_max_f32_e32 v3, v3, v3
	v_max_f32_e32 v3, v2, v3
	v_mov_b32_e32 v7, v3
	s_nop 1
	v_mov_b32_dpp v7, v7 row_shr:2 row_mask:0xf bank_mask:0xf
	v_max_f32_e32 v7, v7, v7
	v_max_f32_e32 v3, v3, v7
	v_mov_b32_e32 v7, v3
	s_nop 1
	v_mov_b32_dpp v7, v7 row_shr:4 row_mask:0xf bank_mask:0xf
	v_max_f32_e32 v7, v7, v7
	v_max_f32_e32 v3, v3, v7
	v_mov_b32_e32 v7, v3
	s_nop 1
	v_mov_b32_dpp v7, v7 row_shr:8 row_mask:0xf bank_mask:0xf
	v_max_f32_e32 v7, v7, v7
	v_max_f32_e32 v3, v3, v7
	v_mov_b32_e32 v7, v3
	s_nop 1
	v_mov_b32_dpp v7, v7 row_bcast:15 row_mask:0xa bank_mask:0xf
	v_max_f32_e32 v7, v7, v7
	v_max_f32_e32 v3, v3, v7
	v_mov_b32_e32 v7, v3
	s_nop 1
	v_mov_b32_dpp v7, v7 row_bcast:31 row_mask:0xc bank_mask:0xf
	v_max_f32_e32 v7, v7, v7
	v_max_f32_e32 v3, v3, v7
	s_nop 0
	v_readlane_b32 s0, v3, 63
	s_nop 1
	v_max_f32_e64 v3, s0, s0
	v_max_f32_e32 v234, 0xf149f2ca, v3
	v_sub_f32_e32 v2, v2, v234
	v_exp_f32_e32 v2, v2
	v_readlane_b32 s0, v251, 15
	v_sub_f32_e32 v3, 0xf149f2ca, v234
	v_exp_f32_e32 v47, v3
	v_cndmask_b32_e32 v7, 0, v2, vcc
	v_add_u32_e32 v127, s0, v71
	ds_write_b128 v127, v[4:7] offset:18432
	s_waitcnt lgkmcnt(0)
	v_mov_b32_e32 v2, s0
	ds_read_b128 v[8:11], v2 offset:18432
	ds_read_b128 v[12:15], v2 offset:18448
	ds_read_b128 v[16:19], v2 offset:18464
	ds_read_b128 v[20:23], v2 offset:18480
	ds_read_b128 v[24:27], v2 offset:18496
	ds_read_b128 v[28:31], v2 offset:18512
	ds_read_b128 v[32:35], v2 offset:18528
	ds_read_b128 v[36:39], v2 offset:18544
	ds_read_b128 v[40:43], v2 offset:18560
	s_waitcnt lgkmcnt(8)
; #define LAS __attribute__((address_space(3)))
; __device__ __forceinline__ void seg_attend(SegAcc& A, const float* base, int kvh, int nk, bool valid, const LAS float* qs, LAS float* pt, int lane) {
;     ...
; #pragma unroll
;     for (int k = 0; k < 64; ++k) { const f32x4 pk = *(const LAS f32x4*)(pt + 4 * k);
; #pragma unroll
;         for (int gq = 0; gq < 4; ++gq) A.o[gq] += pk[gq] * vv[k]; }
	v_pk_fma_f32 v[4:5], v[216:217], v[8:9], v[44:45] op_sel_hi:[0,1,1]
	s_waitcnt lgkmcnt(7)
	v_pk_fma_f32 v[4:5], v[218:219], v[12:13], v[4:5] op_sel_hi:[0,1,1]
	s_waitcnt lgkmcnt(6)
	v_pk_fma_f32 v[4:5], v[220:221], v[16:17], v[4:5] op_sel_hi:[0,1,1]
	s_waitcnt lgkmcnt(5)
	v_pk_fma_f32 v[4:5], v[222:223], v[20:21], v[4:5] op_sel_hi:[0,1,1]
	s_waitcnt lgkmcnt(4)
	v_pk_fma_f32 v[4:5], v[224:225], v[24:25], v[4:5] op_sel_hi:[0,1,1]
	s_waitcnt lgkmcnt(3)
	v_pk_fma_f32 v[4:5], v[226:227], v[28:29], v[4:5] op_sel_hi:[0,1,1]
	s_waitcnt lgkmcnt(2)
	v_pk_fma_f32 v[4:5], v[228:229], v[32:33], v[4:5] op_sel_hi:[0,1,1]
	s_waitcnt lgkmcnt(1)
	v_pk_fma_f32 v[4:5], v[230:231], v[36:37], v[4:5] op_sel_hi:[0,1,1]
	s_waitcnt lgkmcnt(0)
	v_pk_fma_f32 v[48:49], v[232:233], v[40:41], v[4:5] op_sel_hi:[0,1,1]
	v_pk_mul_f32 v[4:5], v[46:47], 0 op_sel_hi:[1,0]
	s_and_b64 vcc, exec, s[2:3]
	v_add_f32_e32 v121, v4, v6
	v_add_f32_e32 v125, v5, v7
	v_pk_fma_f32 v[4:5], v[216:217], v[10:11], v[4:5] op_sel_hi:[0,1,1]
	v_pk_fma_f32 v[4:5], v[218:219], v[14:15], v[4:5] op_sel_hi:[0,1,1]
	v_pk_fma_f32 v[4:5], v[220:221], v[18:19], v[4:5] op_sel_hi:[0,1,1]
	v_pk_fma_f32 v[4:5], v[222:223], v[22:23], v[4:5] op_sel_hi:[0,1,1]
	v_pk_fma_f32 v[4:5], v[224:225], v[26:27], v[4:5] op_sel_hi:[0,1,1]
	v_pk_fma_f32 v[4:5], v[226:227], v[30:31], v[4:5] op_sel_hi:[0,1,1]
	v_pk_fma_f32 v[4:5], v[228:229], v[34:35], v[4:5] op_sel_hi:[0,1,1]
	v_pk_fma_f32 v[4:5], v[230:231], v[38:39], v[4:5] op_sel_hi:[0,1,1]
	v_pk_fma_f32 v[50:51], v[232:233], v[42:43], v[4:5] op_sel_hi:[0,1,1]
	ds_read_b128 v[4:7], v2 offset:18576
	ds_read_b128 v[8:11], v2 offset:18592
	ds_read_b128 v[12:15], v2 offset:18608
	ds_read_b128 v[16:19], v2 offset:18624
	ds_read_b128 v[20:23], v2 offset:18640
	ds_read_b128 v[24:27], v2 offset:18656
	ds_read_b128 v[28:31], v2 offset:18672
	ds_read_b128 v[32:35], v2 offset:18688
	ds_read_b128 v[36:39], v2 offset:18704
	ds_read_b128 v[40:43], v2 offset:18720
	ds_read_b128 v[44:47], v2 offset:18736
	s_waitcnt lgkmcnt(10)
	v_pk_fma_f32 v[4:5], v[214:215], v[4:5], v[48:49] op_sel_hi:[0,1,1]
	s_waitcnt lgkmcnt(9)
	v_pk_fma_f32 v[4:5], v[212:213], v[8:9], v[4:5] op_sel_hi:[0,1,1]
	s_waitcnt lgkmcnt(8)
	v_pk_fma_f32 v[4:5], v[208:209], v[12:13], v[4:5] op_sel_hi:[0,1,1]
	s_waitcnt lgkmcnt(7)
	v_pk_fma_f32 v[4:5], v[210:211], v[16:17], v[4:5] op_sel_hi:[0,1,1]
	s_waitcnt lgkmcnt(6)
	v_pk_fma_f32 v[4:5], v[206:207], v[20:21], v[4:5] op_sel_hi:[0,1,1]
	s_waitcnt lgkmcnt(5)
	v_pk_fma_f32 v[4:5], v[204:205], v[24:25], v[4:5] op_sel_hi:[0,1,1]
	s_waitcnt lgkmcnt(4)
	v_pk_fma_f32 v[4:5], v[200:201], v[28:29], v[4:5] op_sel_hi:[0,1,1]
	s_waitcnt lgkmcnt(3)
	v_pk_fma_f32 v[4:5], v[202:203], v[32:33], v[4:5] op_sel_hi:[0,1,1]
	s_waitcnt lgkmcnt(2)
	v_pk_fma_f32 v[4:5], v[198:199], v[36:37], v[4:5] op_sel_hi:[0,1,1]
	s_waitcnt lgkmcnt(1)
	v_pk_fma_f32 v[4:5], v[196:197], v[40:41], v[4:5] op_sel_hi:[0,1,1]
	s_waitcnt lgkmcnt(0)
	v_pk_fma_f32 v[48:49], v[194:195], v[44:45], v[4:5] op_sel_hi:[0,1,1]
	v_pk_fma_f32 v[4:5], v[214:215], v[6:7], v[50:51] op_sel_hi:[0,1,1]
	v_pk_fma_f32 v[4:5], v[212:213], v[10:11], v[4:5] op_sel_hi:[0,1,1]
	v_pk_fma_f32 v[4:5], v[208:209], v[14:15], v[4:5] op_sel_hi:[0,1,1]
	v_pk_fma_f32 v[4:5], v[210:211], v[18:19], v[4:5] op_sel_hi:[0,1,1]
	v_pk_fma_f32 v[4:5], v[206:207], v[22:23], v[4:5] op_sel_hi:[0,1,1]
	v_pk_fma_f32 v[4:5], v[204:205], v[26:27], v[4:5] op_sel_hi:[0,1,1]
	v_pk_fma_f32 v[4:5], v[200:201], v[30:31], v[4:5] op_sel_hi:[0,1,1]
	v_pk_fma_f32 v[4:5], v[202:203], v[34:35], v[4:5] op_sel_hi:[0,1,1]
	v_pk_fma_f32 v[4:5], v[198:199], v[38:39], v[4:5] op_sel_hi:[0,1,1]
	v_pk_fma_f32 v[4:5], v[196:197], v[42:43], v[4:5] op_sel_hi:[0,1,1]
	v_pk_fma_f32 v[50:51], v[194:195], v[46:47], v[4:5] op_sel_hi:[0,1,1]
	ds_read_b128 v[4:7], v2 offset:18752
	ds_read_b128 v[8:11], v2 offset:18768
	ds_read_b128 v[12:15], v2 offset:18784
	ds_read_b128 v[16:19], v2 offset:18800
	ds_read_b128 v[20:23], v2 offset:18816
	ds_read_b128 v[24:27], v2 offset:18832
	ds_read_b128 v[28:31], v2 offset:18848
	ds_read_b128 v[32:35], v2 offset:18864
	ds_read_b128 v[36:39], v2 offset:18880
	ds_read_b128 v[40:43], v2 offset:18896
	ds_read_b128 v[44:47], v2 offset:18912
	s_waitcnt lgkmcnt(10)
	v_pk_fma_f32 v[4:5], v[172:173], v[4:5], v[48:49] op_sel_hi:[0,1,1]
	s_waitcnt lgkmcnt(9)
	v_pk_fma_f32 v[4:5], v[174:175], v[8:9], v[4:5] op_sel_hi:[0,1,1]
	s_waitcnt lgkmcnt(8)
	v_pk_fma_f32 v[4:5], v[176:177], v[12:13], v[4:5] op_sel_hi:[0,1,1]
	s_waitcnt lgkmcnt(7)
	v_pk_fma_f32 v[4:5], v[178:179], v[16:17], v[4:5] op_sel_hi:[0,1,1]
	s_waitcnt lgkmcnt(6)
	v_pk_fma_f32 v[4:5], v[180:181], v[20:21], v[4:5] op_sel_hi:[0,1,1]
	s_waitcnt lgkmcnt(5)
	v_pk_fma_f32 v[4:5], v[182:183], v[24:25], v[4:5] op_sel_hi:[0,1,1]
	s_waitcnt lgkmcnt(4)
	v_pk_fma_f32 v[4:5], v[184:185], v[28:29], v[4:5] op_sel_hi:[0,1,1]
	s_waitcnt lgkmcnt(3)
	v_pk_fma_f32 v[4:5], v[186:187], v[32:33], v[4:5] op_sel_hi:[0,1,1]
	s_waitcnt lgkmcnt(2)
	v_pk_fma_f32 v[4:5], v[188:189], v[36:37], v[4:5] op_sel_hi:[0,1,1]
	s_waitcnt lgkmcnt(1)
	v_pk_fma_f32 v[4:5], v[190:191], v[40:41], v[4:5] op_sel_hi:[0,1,1]
	s_waitcnt lgkmcnt(0)
; #define LAS __attribute__((address_space(3)))
; __device__ __forceinline__ void seg_attend(SegAcc& A, const float* base, int kvh, int nk, bool valid, const LAS float* qs, LAS float* pt, int lane) {
;     ...
; #pragma unroll
;     for (int k = 0; k < 64; ++k) { const f32x4 pk = *(const LAS f32x4*)(pt + 4 * k);
; #pragma unroll
;         for (int gq = 0; gq < 4; ++gq) A.o[gq] += pk[gq] * vv[k]; }
	v_pk_fma_f32 v[48:49], v[192:193], v[44:45], v[4:5] op_sel_hi:[0,1,1]
	v_pk_fma_f32 v[4:5], v[172:173], v[6:7], v[50:51] op_sel_hi:[0,1,1]
	v_pk_fma_f32 v[4:5], v[174:175], v[10:11], v[4:5] op_sel_hi:[0,1,1]
	v_pk_fma_f32 v[4:5], v[176:177], v[14:15], v[4:5] op_sel_hi:[0,1,1]
	v_pk_fma_f32 v[4:5], v[178:179], v[18:19], v[4:5] op_sel_hi:[0,1,1]
	v_pk_fma_f32 v[4:5], v[180:181], v[22:23], v[4:5] op_sel_hi:[0,1,1]
	v_pk_fma_f32 v[4:5], v[182:183], v[26:27], v[4:5] op_sel_hi:[0,1,1]
	v_pk_fma_f32 v[4:5], v[184:185], v[30:31], v[4:5] op_sel_hi:[0,1,1]
	v_pk_fma_f32 v[4:5], v[186:187], v[34:35], v[4:5] op_sel_hi:[0,1,1]
	v_pk_fma_f32 v[4:5], v[188:189], v[38:39], v[4:5] op_sel_hi:[0,1,1]
	v_pk_fma_f32 v[4:5], v[190:191], v[42:43], v[4:5] op_sel_hi:[0,1,1]
	v_pk_fma_f32 v[50:51], v[192:193], v[46:47], v[4:5] op_sel_hi:[0,1,1]
	ds_read_b128 v[4:7], v2 offset:18928
	ds_read_b128 v[8:11], v2 offset:18944
	ds_read_b128 v[12:15], v2 offset:18960
	ds_read_b128 v[16:19], v2 offset:18976
	ds_read_b128 v[20:23], v2 offset:18992
	ds_read_b128 v[24:27], v2 offset:19008
	ds_read_b128 v[28:31], v2 offset:19024
	ds_read_b128 v[32:35], v2 offset:19040
	ds_read_b128 v[36:39], v2 offset:19056
	ds_read_b128 v[40:43], v2 offset:19072
	ds_read_b128 v[44:47], v2 offset:19088
	s_waitcnt lgkmcnt(10)
	v_pk_fma_f32 v[4:5], v[144:145], v[4:5], v[48:49] op_sel_hi:[0,1,1]
	s_waitcnt lgkmcnt(9)
	v_pk_fma_f32 v[4:5], v[170:171], v[8:9], v[4:5] op_sel_hi:[0,1,1]
	s_waitcnt lgkmcnt(8)
	v_pk_fma_f32 v[4:5], v[142:143], v[12:13], v[4:5] op_sel_hi:[0,1,1]
	s_waitcnt lgkmcnt(7)
	v_pk_fma_f32 v[4:5], v[140:141], v[16:17], v[4:5] op_sel_hi:[0,1,1]
	s_waitcnt lgkmcnt(6)
	v_pk_fma_f32 v[4:5], v[136:137], v[20:21], v[4:5] op_sel_hi:[0,1,1]
	s_waitcnt lgkmcnt(5)
	v_pk_fma_f32 v[4:5], v[138:139], v[24:25], v[4:5] op_sel_hi:[0,1,1]
	s_waitcnt lgkmcnt(4)
	v_pk_fma_f32 v[4:5], v[134:135], v[28:29], v[4:5] op_sel_hi:[0,1,1]
	s_waitcnt lgkmcnt(3)
	v_pk_fma_f32 v[4:5], v[132:133], v[32:33], v[4:5] op_sel_hi:[0,1,1]
	s_waitcnt lgkmcnt(2)
	v_pk_fma_f32 v[4:5], v[128:129], v[36:37], v[4:5] op_sel_hi:[0,1,1]
	s_waitcnt lgkmcnt(1)
	v_pk_fma_f32 v[4:5], v[130:131], v[40:41], v[4:5] op_sel_hi:[0,1,1]
	s_waitcnt lgkmcnt(0)
	v_pk_fma_f32 v[48:49], v[126:127], v[44:45], v[4:5] op_sel_hi:[0,1,1]
	v_pk_fma_f32 v[4:5], v[144:145], v[6:7], v[50:51] op_sel_hi:[0,1,1]
	v_pk_fma_f32 v[4:5], v[170:171], v[10:11], v[4:5] op_sel_hi:[0,1,1]
	v_pk_fma_f32 v[4:5], v[142:143], v[14:15], v[4:5] op_sel_hi:[0,1,1]
	v_pk_fma_f32 v[4:5], v[140:141], v[18:19], v[4:5] op_sel_hi:[0,1,1]
	v_pk_fma_f32 v[4:5], v[136:137], v[22:23], v[4:5] op_sel_hi:[0,1,1]
	v_pk_fma_f32 v[4:5], v[138:139], v[26:27], v[4:5] op_sel_hi:[0,1,1]
	v_pk_fma_f32 v[4:5], v[134:135], v[30:31], v[4:5] op_sel_hi:[0,1,1]
	v_pk_fma_f32 v[4:5], v[132:133], v[34:35], v[4:5] op_sel_hi:[0,1,1]
	v_pk_fma_f32 v[4:5], v[128:129], v[38:39], v[4:5] op_sel_hi:[0,1,1]
	v_pk_fma_f32 v[4:5], v[130:131], v[42:43], v[4:5] op_sel_hi:[0,1,1]
	v_pk_fma_f32 v[50:51], v[126:127], v[46:47], v[4:5] op_sel_hi:[0,1,1]
	ds_read_b128 v[4:7], v2 offset:19104
	ds_read_b128 v[8:11], v2 offset:19120
	ds_read_b128 v[12:15], v2 offset:19136
	ds_read_b128 v[16:19], v2 offset:19152
	ds_read_b128 v[20:23], v2 offset:19168
	ds_read_b128 v[24:27], v2 offset:19184
	ds_read_b128 v[28:31], v2 offset:19200
	ds_read_b128 v[32:35], v2 offset:19216
	ds_read_b128 v[36:39], v2 offset:19232
	ds_read_b128 v[40:43], v2 offset:19248
	ds_read_b128 v[44:47], v2 offset:19264
	s_waitcnt lgkmcnt(10)
	v_pk_fma_f32 v[4:5], v[90:91], v[4:5], v[48:49] op_sel_hi:[0,1,1]
	s_waitcnt lgkmcnt(9)
	v_pk_fma_f32 v[4:5], v[92:93], v[8:9], v[4:5] op_sel_hi:[0,1,1]
	s_waitcnt lgkmcnt(8)
	v_pk_fma_f32 v[4:5], v[94:95], v[12:13], v[4:5] op_sel_hi:[0,1,1]
	s_waitcnt lgkmcnt(7)
	v_pk_fma_f32 v[4:5], v[96:97], v[16:17], v[4:5] op_sel_hi:[0,1,1]
	s_waitcnt lgkmcnt(6)
	v_pk_fma_f32 v[4:5], v[112:113], v[20:21], v[4:5] op_sel_hi:[0,1,1]
	s_waitcnt lgkmcnt(5)
	v_pk_fma_f32 v[4:5], v[114:115], v[24:25], v[4:5] op_sel_hi:[0,1,1]
	s_waitcnt lgkmcnt(4)
	v_pk_fma_f32 v[4:5], v[116:117], v[28:29], v[4:5] op_sel_hi:[0,1,1]
	s_waitcnt lgkmcnt(3)
	v_pk_fma_f32 v[4:5], v[118:119], v[32:33], v[4:5] op_sel_hi:[0,1,1]
	s_waitcnt lgkmcnt(2)
	v_pk_fma_f32 v[4:5], v[120:121], v[36:37], v[4:5] op_sel_hi:[0,1,1]
	s_waitcnt lgkmcnt(1)
	v_pk_fma_f32 v[4:5], v[122:123], v[40:41], v[4:5] op_sel_hi:[0,1,1]
	s_waitcnt lgkmcnt(0)
	v_pk_fma_f32 v[48:49], v[124:125], v[44:45], v[4:5] op_sel_hi:[0,1,1]
	v_pk_fma_f32 v[4:5], v[90:91], v[6:7], v[50:51] op_sel_hi:[0,1,1]
	v_pk_fma_f32 v[4:5], v[92:93], v[10:11], v[4:5] op_sel_hi:[0,1,1]
	v_pk_fma_f32 v[4:5], v[94:95], v[14:15], v[4:5] op_sel_hi:[0,1,1]
	v_pk_fma_f32 v[4:5], v[96:97], v[18:19], v[4:5] op_sel_hi:[0,1,1]
	v_pk_fma_f32 v[4:5], v[112:113], v[22:23], v[4:5] op_sel_hi:[0,1,1]
	v_pk_fma_f32 v[4:5], v[114:115], v[26:27], v[4:5] op_sel_hi:[0,1,1]
	v_pk_fma_f32 v[4:5], v[116:117], v[30:31], v[4:5] op_sel_hi:[0,1,1]
	v_pk_fma_f32 v[4:5], v[118:119], v[34:35], v[4:5] op_sel_hi:[0,1,1]
	v_pk_fma_f32 v[4:5], v[120:121], v[38:39], v[4:5] op_sel_hi:[0,1,1]
	v_pk_fma_f32 v[4:5], v[122:123], v[42:43], v[4:5] op_sel_hi:[0,1,1]
	v_pk_fma_f32 v[50:51], v[124:125], v[46:47], v[4:5] op_sel_hi:[0,1,1]
	ds_read_b128 v[4:7], v2 offset:19280
	ds_read_b128 v[8:11], v2 offset:19296
	ds_read_b128 v[12:15], v2 offset:19312
	ds_read_b128 v[16:19], v2 offset:19328
	ds_read_b128 v[20:23], v2 offset:19344
	ds_read_b128 v[24:27], v2 offset:19360
	ds_read_b128 v[28:31], v2 offset:19376
	ds_read_b128 v[32:35], v2 offset:19392
	ds_read_b128 v[36:39], v2 offset:19408
	ds_read_b128 v[40:43], v2 offset:19424
	ds_read_b128 v[44:47], v2 offset:19440
	s_waitcnt lgkmcnt(10)
; #define LAS __attribute__((address_space(3)))
; __device__ __forceinline__ void seg_attend(SegAcc& A, const float* base, int kvh, int nk, bool valid, const LAS float* qs, LAS float* pt, int lane) {
;     f32x4 kv[16]; float vv[64];
;     const f32x4* kp = (const f32x4*)(base + (size_t)(lane < nk ? lane : 0) * 256 + kvh * 64);
; #pragma unroll
;     for (int c4 = 0; c4 < 16; ++c4) kv[c4] = kp[c4];
;     const float* vb = base + 128 + kvh * 64 + lane;
; #pragma unroll
;     for (int k = 0; k < 64; ++k) vv[k] = vb[(size_t)(k < nk ? k : 0) * 256];
;     float s[4] = {0.f, 0.f, 0.f, 0.f};
; #pragma unroll
;     for (int c4 = 0; c4 < 16; ++c4)
; #pragma unroll
;         for (int gq = 0; gq < 4; ++gq) { const f32x4 qv = *(const LAS f32x4*)(qs + gq * 64 + 4 * c4); s[gq] += kv[c4][0] * qv[0] + kv[c4][1] * qv[1] + kv[c4][2] * qv[2] + kv[c4][3] * qv[3]; }
; __device__ __forceinline__ void sample_task_part2(const Prm& P, Ctx& C, int b, int kvh, int ts) {
;     ...
;     if (C.wave == 0) seg_attend(Aw, (const float*)(uintptr_t)segb[24], kvh, 4, lane <= ts, qs, ptab, lane);
	v_pk_fma_f32 v[2:3], v[88:89], v[4:5], v[48:49] op_sel_hi:[0,1,1]
	s_waitcnt lgkmcnt(9)
	v_pk_fma_f32 v[2:3], v[86:87], v[8:9], v[2:3] op_sel_hi:[0,1,1]
	s_waitcnt lgkmcnt(8)
	v_pk_fma_f32 v[2:3], v[82:83], v[12:13], v[2:3] op_sel_hi:[0,1,1]
	s_waitcnt lgkmcnt(7)
	v_pk_fma_f32 v[2:3], v[84:85], v[16:17], v[2:3] op_sel_hi:[0,1,1]
	s_waitcnt lgkmcnt(6)
	v_pk_fma_f32 v[2:3], v[80:81], v[20:21], v[2:3] op_sel_hi:[0,1,1]
	s_waitcnt lgkmcnt(5)
	v_pk_fma_f32 v[2:3], v[78:79], v[24:25], v[2:3] op_sel_hi:[0,1,1]
	s_waitcnt lgkmcnt(4)
	v_pk_fma_f32 v[2:3], v[74:75], v[28:29], v[2:3] op_sel_hi:[0,1,1]
	s_waitcnt lgkmcnt(3)
	v_pk_fma_f32 v[2:3], v[76:77], v[32:33], v[2:3] op_sel_hi:[0,1,1]
	s_waitcnt lgkmcnt(2)
	v_pk_fma_f32 v[2:3], v[72:73], v[36:37], v[2:3] op_sel_hi:[0,1,1]
	s_waitcnt lgkmcnt(1)
	v_pk_fma_f32 v[2:3], v[70:71], v[40:41], v[2:3] op_sel_hi:[0,1,1]
	s_waitcnt lgkmcnt(0)
	v_pk_fma_f32 v[114:115], v[0:1], v[44:45], v[2:3] op_sel_hi:[0,1,1]
	v_pk_fma_f32 v[2:3], v[88:89], v[6:7], v[50:51] op_sel_hi:[0,1,1]
	v_pk_fma_f32 v[2:3], v[86:87], v[10:11], v[2:3] op_sel_hi:[0,1,1]
	v_pk_fma_f32 v[2:3], v[82:83], v[14:15], v[2:3] op_sel_hi:[0,1,1]
	v_pk_fma_f32 v[2:3], v[84:85], v[18:19], v[2:3] op_sel_hi:[0,1,1]
	v_pk_fma_f32 v[2:3], v[80:81], v[22:23], v[2:3] op_sel_hi:[0,1,1]
	v_pk_fma_f32 v[2:3], v[78:79], v[26:27], v[2:3] op_sel_hi:[0,1,1]
	v_pk_fma_f32 v[2:3], v[74:75], v[30:31], v[2:3] op_sel_hi:[0,1,1]
	v_pk_fma_f32 v[2:3], v[76:77], v[34:35], v[2:3] op_sel_hi:[0,1,1]
	v_pk_fma_f32 v[2:3], v[72:73], v[38:39], v[2:3] op_sel_hi:[0,1,1]
	s_waitcnt lgkmcnt(0)
	v_pk_fma_f32 v[2:3], v[70:71], v[42:43], v[2:3] op_sel_hi:[0,1,1]
	v_pk_fma_f32 v[112:113], v[0:1], v[46:47], v[2:3] op_sel_hi:[0,1,1]
	s_cbranch_vccz .LBB0_1576
	v_readlane_b32 s1, v251, 61
	v_cmp_gt_i32_e32 vcc, 4, v98
	ds_read_b128 v[6:9], v1 offset:55296
	v_mov_b32_e32 v0, s1
	ds_read_b64 v[62:63], v0
	v_cndmask_b32_e32 v2, 0, v98, vcc
	v_ashrrev_i32_e32 v3, 31, v2
	v_lshlrev_b64 v[2:3], 10, v[2:3]
	v_cmp_lt_i32_e32 vcc, s25, v98
	s_waitcnt lgkmcnt(0)
	v_lshl_add_u64 v[2:3], v[62:63], 0, v[2:3]
	v_lshl_add_u64 v[64:65], v[2:3], 0, s[78:79]
	global_load_dwordx4 v[18:21], v[64:65], off
	global_load_dwordx4 v[14:17], v[64:65], off offset:16
	global_load_dwordx4 v[10:13], v[64:65], off offset:32
	ds_read_b128 v[26:29], v1 offset:55312
	ds_read_b128 v[22:25], v1 offset:55328
	ds_read_b128 v[2:5], v1 offset:55344
	ds_read_b128 v[30:33], v1 offset:55568
	ds_read_b128 v[38:41], v1 offset:55584
	ds_read_b128 v[46:49], v1 offset:55824
	ds_read_b128 v[34:37], v1 offset:55840
	ds_read_b128 v[50:53], v1 offset:56080
	ds_read_b128 v[42:45], v1 offset:56096
	ds_read_b128 v[54:57], v1 offset:55552
	ds_read_b128 v[58:61], v1 offset:55536
	ds_read_b128 v[128:131], v1 offset:55808
	ds_read_b128 v[70:73], v1 offset:55792
	ds_read_b128 v[132:135], v1 offset:56064
	ds_read_b128 v[66:69], v1 offset:56048
	global_load_dwordx4 v[136:139], v[64:65], off offset:48
	v_lshl_add_u64 v[62:63], v[62:63], 0, s[78:79]
	v_lshl_add_u64 v[144:145], v[98:99], 2, v[62:63]
	global_load_dwordx4 v[140:143], v[64:65], off offset:64
	global_load_dwordx4 v[242:245], v[64:65], off offset:80
	global_load_dwordx4 v[228:231], v[64:65], off offset:96
	global_load_dwordx4 v[220:223], v[64:65], off offset:112
	global_load_dwordx4 v[224:227], v[64:65], off offset:128
	global_load_dwordx4 v[94:97], v[64:65], off offset:144
	global_load_dwordx4 v[90:93], v[64:65], off offset:160
	global_load_dwordx4 v[86:89], v[64:65], off offset:176
	global_load_dwordx4 v[82:85], v[64:65], off offset:192
	global_load_dwordx4 v[78:81], v[64:65], off offset:208
	global_load_dwordx4 v[74:77], v[64:65], off offset:224
	s_nop 0
	global_load_dwordx4 v[62:65], v[64:65], off offset:240
	s_nop 0
	global_load_dword v0, v[144:145], off offset:512
	global_load_dword v116, v[144:145], off offset:1536
	global_load_dword v118, v[144:145], off offset:2560
	global_load_dword v120, v[144:145], off offset:3584
	s_mov_b32 s1, s0
	s_waitcnt vmcnt(0) lgkmcnt(0)
	ds_read_b128 v[146:149], v1 offset:55600
	ds_read_b128 v[150:153], v1 offset:55616
	v_mul_f32_e32 v7, v19, v7
	v_mul_f32_e32 v27, v15, v27
	v_fmac_f32_e32 v7, v18, v6
	v_mul_f32_e32 v23, v11, v23
	v_fmac_f32_e32 v27, v14, v26
	ds_read_b128 v[154:157], v1 offset:55856
	v_fmac_f32_e32 v7, v20, v8
	v_fmac_f32_e32 v23, v10, v22
	v_fmac_f32_e32 v27, v16, v28
	v_fmac_f32_e32 v7, v21, v9
	ds_read_b128 v[158:161], v1 offset:55872
	ds_read_b128 v[162:165], v1 offset:56112
	v_mul_f32_e32 v99, v19, v129
	v_fmac_f32_e32 v23, v12, v24
	v_fmac_f32_e32 v27, v17, v29
	v_add_f32_e32 v6, 0, v7
	v_mul_f32_e32 v31, v15, v31
	v_mul_f32_e32 v47, v15, v47
	v_mul_f32_e32 v15, v15, v51
	v_fmac_f32_e32 v99, v18, v128
	v_fmac_f32_e32 v23, v13, v25
	s_waitcnt lgkmcnt(4)
	ds_read_b128 v[166:169], v1 offset:56128
	v_add_f32_e32 v6, v6, v27
	v_fmac_f32_e32 v31, v14, v30
	v_fmac_f32_e32 v47, v14, v46
	v_fmac_f32_e32 v15, v14, v50
	v_fmac_f32_e32 v99, v20, v130
	v_add_f32_e32 v14, v6, v23
	v_mul_f32_e32 v6, v11, v35
	v_fmac_f32_e32 v47, v16, v48
	v_fmac_f32_e32 v99, v21, v131
	v_fmac_f32_e32 v6, v10, v34
	v_fmac_f32_e32 v47, v17, v49
	v_add_f32_e32 v8, 0, v99
	v_fmac_f32_e32 v6, v12, v36
	v_add_f32_e32 v8, v8, v47
	v_fmac_f32_e32 v6, v13, v37
	v_mul_f32_e32 v39, v11, v39
	v_add_f32_e32 v22, v8, v6
	v_mul_f32_e32 v6, v11, v43
	v_fmac_f32_e32 v39, v10, v38
	v_fmac_f32_e32 v6, v10, v42
	v_fmac_f32_e32 v39, v12, v40
	v_fmac_f32_e32 v6, v12, v44
	v_fmac_f32_e32 v39, v13, v41
	v_fmac_f32_e32 v6, v13, v45
	v_mul_f32_e32 v3, v137, v3
	v_mul_f32_e32 v55, v19, v55
	v_mul_f32_e32 v19, v19, v133
	v_fmac_f32_e32 v3, v136, v2
	v_fmac_f32_e32 v55, v18, v54
	v_fmac_f32_e32 v19, v18, v132
	v_fmac_f32_e32 v3, v138, v4
	v_fmac_f32_e32 v55, v20, v56
	v_fmac_f32_e32 v19, v20, v134
	v_fmac_f32_e32 v3, v139, v5
	v_fmac_f32_e32 v31, v16, v32
	v_fmac_f32_e32 v15, v16, v52
	v_fmac_f32_e32 v55, v21, v57
	v_fmac_f32_e32 v19, v21, v135
	v_add_f32_e32 v24, v14, v3
	v_mul_f32_e32 v11, v137, v147
	v_fmac_f32_e32 v31, v17, v33
	v_fmac_f32_e32 v15, v17, v53
	v_add_f32_e32 v7, 0, v55
	v_add_f32_e32 v9, 0, v19
	v_fmac_f32_e32 v11, v136, v146
	v_add_f32_e32 v7, v7, v31
	v_add_f32_e32 v9, v9, v15
	v_fmac_f32_e32 v11, v138, v148
	v_add_f32_e32 v18, v7, v39
	v_fmac_f32_e32 v11, v139, v149
	s_waitcnt lgkmcnt(4)
; #define LAS __attribute__((address_space(3)))
; __device__ __forceinline__ void seg_attend(SegAcc& A, const float* base, int kvh, int nk, bool valid, const LAS float* qs, LAS float* pt, int lane) {
;     ...
;     float s[4] = {0.f, 0.f, 0.f, 0.f};
; #pragma unroll
;     for (int c4 = 0; c4 < 16; ++c4)
; #pragma unroll
;         for (int gq = 0; gq < 4; ++gq) { const f32x4 qv = *(const LAS f32x4*)(qs + gq * 64 + 4 * c4); s[gq] += kv[c4][0] * qv[0] + kv[c4][1] * qv[1] + kv[c4][2] * qv[2] + kv[c4][3] * qv[3]; }
	ds_read_b128 v[146:149], v1 offset:55360
	v_add_f32_e32 v25, v18, v11
	s_waitcnt lgkmcnt(4)
	v_mul_f32_e32 v15, v137, v155
	v_fmac_f32_e32 v15, v136, v154
	v_mul_f32_e32 v3, v141, v151
	v_fmac_f32_e32 v15, v138, v156
	v_fmac_f32_e32 v3, v140, v150
	s_waitcnt lgkmcnt(3)
	v_mul_f32_e32 v2, v141, v159
	v_fmac_f32_e32 v15, v139, v157
	ds_read_b128 v[154:157], v1 offset:55376
	v_fmac_f32_e32 v2, v140, v158
	v_add_f32_e32 v22, v22, v15
	s_waitcnt lgkmcnt(3)
	v_mul_f32_e32 v19, v137, v163
	v_fmac_f32_e32 v3, v142, v152
	v_fmac_f32_e32 v2, v142, v160
	v_add_f32_e32 v23, v9, v6
	v_fmac_f32_e32 v19, v136, v162
	v_fmac_f32_e32 v3, v143, v153
	ds_read_b128 v[150:153], v1 offset:55632
	v_fmac_f32_e32 v2, v143, v161
	ds_read_b128 v[158:161], v1 offset:55648
	v_fmac_f32_e32 v19, v138, v164
	v_add_f32_e32 v20, v25, v3
	v_add_f32_e32 v22, v22, v2
	s_waitcnt lgkmcnt(3)
	v_mul_f32_e32 v7, v141, v147
	v_fmac_f32_e32 v7, v140, v146
	v_fmac_f32_e32 v7, v142, v148
	s_waitcnt lgkmcnt(2)
	v_mul_f32_e32 v3, v243, v155
	v_fmac_f32_e32 v3, v242, v154
	v_fmac_f32_e32 v19, v139, v165
	ds_read_b128 v[162:165], v1 offset:55888
	v_fmac_f32_e32 v7, v143, v149
	ds_read_b128 v[146:149], v1 offset:55904
	v_fmac_f32_e32 v3, v244, v156
	v_add_f32_e32 v18, v23, v19
	v_add_f32_e32 v19, v24, v7
	v_mul_f32_e32 v6, v141, v167
	v_fmac_f32_e32 v3, v245, v157
	ds_read_b128 v[154:157], v1 offset:56144
	v_fmac_f32_e32 v6, v140, v166
	v_add_f32_e32 v24, v19, v3
	s_waitcnt lgkmcnt(4)
	v_mul_f32_e32 v11, v243, v151
	v_fmac_f32_e32 v6, v142, v168
	v_fmac_f32_e32 v11, v242, v150
	v_fmac_f32_e32 v6, v143, v169
	ds_read_b128 v[166:169], v1 offset:56160
	v_fmac_f32_e32 v11, v244, v152
	v_fmac_f32_e32 v11, v245, v153
	s_waitcnt lgkmcnt(4)
	ds_read_b128 v[150:153], v1 offset:55392
	v_add_f32_e32 v25, v20, v11
	v_add_f32_e32 v23, v18, v6
	s_waitcnt lgkmcnt(4)
	v_mul_f32_e32 v15, v243, v163
	v_fmac_f32_e32 v15, v242, v162
	v_mul_f32_e32 v3, v229, v159
	v_fmac_f32_e32 v15, v244, v164
	v_fmac_f32_e32 v3, v228, v158
	s_waitcnt lgkmcnt(3)
	v_mul_f32_e32 v2, v229, v147
	v_fmac_f32_e32 v15, v245, v165
	ds_read_b128 v[162:165], v1 offset:55408
	v_fmac_f32_e32 v2, v228, v146
	v_add_f32_e32 v22, v22, v15
	s_waitcnt lgkmcnt(3)
	v_mul_f32_e32 v19, v243, v155
	v_fmac_f32_e32 v3, v230, v160
	v_fmac_f32_e32 v2, v230, v148
	v_fmac_f32_e32 v19, v242, v154
	v_fmac_f32_e32 v3, v231, v161
	ds_read_b128 v[158:161], v1 offset:55664
	v_fmac_f32_e32 v2, v231, v149
	ds_read_b128 v[146:149], v1 offset:55680
	v_fmac_f32_e32 v19, v244, v156
	v_add_f32_e32 v20, v25, v3
	v_add_f32_e32 v22, v22, v2
	s_waitcnt lgkmcnt(3)
	v_mul_f32_e32 v7, v229, v151
	v_fmac_f32_e32 v7, v228, v150
	v_fmac_f32_e32 v7, v230, v152
	s_waitcnt lgkmcnt(2)
	v_mul_f32_e32 v3, v221, v163
	v_fmac_f32_e32 v3, v220, v162
	v_fmac_f32_e32 v19, v245, v157
	ds_read_b128 v[154:157], v1 offset:56176
	v_fmac_f32_e32 v7, v231, v153
	ds_read_b128 v[150:153], v1 offset:55424
	v_fmac_f32_e32 v3, v222, v164
	v_add_f32_e32 v18, v23, v19
	v_add_f32_e32 v19, v24, v7
	v_fmac_f32_e32 v3, v223, v165
	ds_read_b128 v[162:165], v1 offset:55440
	v_mul_f32_e32 v6, v229, v167
	v_add_f32_e32 v30, v19, v3
	s_waitcnt lgkmcnt(4)
	v_mul_f32_e32 v11, v221, v159
	v_fmac_f32_e32 v6, v228, v166
	v_fmac_f32_e32 v11, v220, v158
	v_fmac_f32_e32 v6, v230, v168
	v_fmac_f32_e32 v11, v222, v160
	v_fmac_f32_e32 v6, v231, v169
	ds_read_b128 v[166:169], v1 offset:55920
	v_fmac_f32_e32 v11, v223, v161
	s_waitcnt lgkmcnt(4)
	ds_read_b128 v[158:161], v1 offset:55936
	v_add_f32_e32 v23, v18, v6
	v_add_f32_e32 v32, v20, v11
	v_mov_b32_e32 v27, v94
	v_mov_b32_e32 v94, v225
	v_mov_b32_e32 v26, v224
	s_waitcnt lgkmcnt(4)
	v_mul_f32_e32 v19, v221, v155
	v_fmac_f32_e32 v19, v220, v154
	v_fmac_f32_e32 v19, v222, v156
	v_fmac_f32_e32 v19, v223, v157
	ds_read_b128 v[154:157], v1 offset:55696
	v_add_f32_e32 v34, v23, v19
	s_waitcnt lgkmcnt(4)
	v_mov_b32_e32 v28, v150
	v_mov_b32_e32 v57, s1
	s_waitcnt lgkmcnt(3)
	v_mov_b32_e32 v29, v162
	v_mov_b32_e32 v18, v151
	v_mov_b32_e32 v19, v163
	v_pk_mul_f32 v[6:7], v[94:95], v[18:19]
	v_mov_b32_e32 v18, v152
	v_pk_fma_f32 v[6:7], v[26:27], v[28:29], v[6:7]
	v_mov_b32_e32 v28, v226
	v_mov_b32_e32 v29, v96
	v_mov_b32_e32 v19, v164
	v_pk_fma_f32 v[6:7], v[28:29], v[18:19], v[6:7]
	v_mov_b32_e32 v96, v227
	v_mov_b32_e32 v20, v153
	ds_read_b128 v[150:153], v1 offset:55712
	v_mov_b32_e32 v21, v165
	ds_read_b128 v[162:165], v1 offset:56192
	v_pk_fma_f32 v[18:19], v[96:97], v[20:21], v[6:7]
	v_add_f32_e32 v18, v30, v18
	s_waitcnt lgkmcnt(4)
	v_mul_f32_e32 v15, v221, v167
	v_add_f32_e32 v35, v18, v19
	s_waitcnt lgkmcnt(2)
	v_mov_b32_e32 v31, v154
	v_mov_b32_e32 v6, v147
	v_fmac_f32_e32 v15, v220, v166
	v_mov_b32_e32 v30, v146
	v_mov_b32_e32 v7, v155
	v_pk_mul_f32 v[2:3], v[94:95], v[6:7]
	v_fmac_f32_e32 v15, v222, v168
	v_pk_fma_f32 v[2:3], v[26:27], v[30:31], v[2:3]
	v_mov_b32_e32 v6, v148
	v_mov_b32_e32 v7, v156
	v_fmac_f32_e32 v15, v223, v169
	ds_read_b128 v[166:169], v1 offset:55952
	v_pk_fma_f32 v[2:3], v[28:29], v[6:7], v[2:3]
	v_mov_b32_e32 v8, v149
	ds_read_b128 v[146:149], v1 offset:55456
	v_add_f32_e32 v33, v22, v15
	v_mov_b32_e32 v9, v157
	ds_read_b128 v[154:157], v1 offset:56208
	v_pk_fma_f32 v[6:7], v[96:97], v[8:9], v[2:3]
	v_mov_b32_e32 v30, v158
	v_mov_b32_e32 v10, v160
	v_add_f32_e32 v6, v32, v6
	s_waitcnt lgkmcnt(2)
	v_mov_b32_e32 v31, v166
	v_mov_b32_e32 v2, v159
	v_mov_b32_e32 v3, v167
	v_pk_mul_f32 v[2:3], v[94:95], v[2:3]
	v_mov_b32_e32 v11, v168
	v_pk_fma_f32 v[2:3], v[26:27], v[30:31], v[2:3]
	v_mov_b32_e32 v4, v161
	ds_read_b128 v[158:161], v1 offset:56224
	v_pk_fma_f32 v[2:3], v[28:29], v[10:11], v[2:3]
	v_mov_b32_e32 v30, v162
	v_mov_b32_e32 v5, v169
	ds_read_b128 v[166:169], v1 offset:55472
	v_pk_fma_f32 v[10:11], v[96:97], v[4:5], v[2:3]
	v_add_f32_e32 v10, v33, v10
	v_add_f32_e32 v33, v10, v11
	v_mov_b32_e32 v14, v164
	s_waitcnt lgkmcnt(2)
; #define LAS __attribute__((address_space(3)))
; __device__ __forceinline__ void seg_attend(SegAcc& A, const float* base, int kvh, int nk, bool valid, const LAS float* qs, LAS float* pt, int lane) {
;     ...
;     float s[4] = {0.f, 0.f, 0.f, 0.f};
; #pragma unroll
;     for (int c4 = 0; c4 < 16; ++c4)
; #pragma unroll
;         for (int gq = 0; gq < 4; ++gq) { const f32x4 qv = *(const LAS f32x4*)(qs + gq * 64 + 4 * c4); s[gq] += kv[c4][0] * qv[0] + kv[c4][1] * qv[1] + kv[c4][2] * qv[2] + kv[c4][3] * qv[3]; }
	v_mov_b32_e32 v31, v154
	v_mov_b32_e32 v2, v163
	v_mov_b32_e32 v3, v155
	v_pk_mul_f32 v[2:3], v[94:95], v[2:3]
	v_mov_b32_e32 v15, v156
	v_pk_fma_f32 v[2:3], v[26:27], v[30:31], v[2:3]
	v_mov_b32_e32 v4, v165
	ds_read_b128 v[162:165], v1 offset:55968
	v_pk_fma_f32 v[2:3], v[28:29], v[14:15], v[2:3]
	v_mov_b32_e32 v27, v86
	v_mov_b32_e32 v5, v157
	ds_read_b128 v[154:157], v1 offset:55728
	v_pk_fma_f32 v[2:3], v[96:97], v[4:5], v[2:3]
	v_mov_b32_e32 v86, v91
	v_add_f32_e32 v2, v34, v2
	v_add_f32_e32 v34, v2, v3
	v_mov_b32_e32 v26, v90
	v_mov_b32_e32 v28, v146
	v_mov_b32_e32 v22, v148
	v_add_f32_e32 v32, v6, v7
	s_waitcnt lgkmcnt(2)
	v_mov_b32_e32 v29, v166
	v_mov_b32_e32 v2, v147
	v_mov_b32_e32 v3, v167
	v_pk_mul_f32 v[2:3], v[86:87], v[2:3]
	v_mov_b32_e32 v23, v168
	v_pk_fma_f32 v[2:3], v[26:27], v[28:29], v[2:3]
	v_mov_b32_e32 v28, v92
	v_mov_b32_e32 v29, v88
	v_pk_fma_f32 v[2:3], v[28:29], v[22:23], v[2:3]
	v_mov_b32_e32 v88, v93
	v_mov_b32_e32 v4, v149
	ds_read_b128 v[146:149], v1 offset:55488
	v_mov_b32_e32 v5, v169
	ds_read_b128 v[166:169], v1 offset:55984
	v_pk_fma_f32 v[22:23], v[88:89], v[4:5], v[2:3]
	v_mov_b32_e32 v30, v150
	v_mov_b32_e32 v18, v152
	v_add_f32_e32 v22, v35, v22
	s_waitcnt lgkmcnt(2)
	v_mov_b32_e32 v31, v154
	v_mov_b32_e32 v2, v151
	v_mov_b32_e32 v3, v155
	v_pk_mul_f32 v[2:3], v[86:87], v[2:3]
	v_mov_b32_e32 v19, v156
	v_pk_fma_f32 v[2:3], v[26:27], v[30:31], v[2:3]
	v_mov_b32_e32 v4, v153
	ds_read_b128 v[150:153], v1 offset:56000
	v_pk_fma_f32 v[2:3], v[28:29], v[18:19], v[2:3]
	v_mov_b32_e32 v30, v162
	v_mov_b32_e32 v5, v157
	ds_read_b128 v[154:157], v1 offset:56240
	v_pk_fma_f32 v[18:19], v[88:89], v[4:5], v[2:3]
	v_add_f32_e32 v18, v32, v18
	v_add_f32_e32 v32, v18, v19
	v_mov_b32_e32 v6, v164
	s_waitcnt lgkmcnt(2)
	v_mov_b32_e32 v31, v166
	v_mov_b32_e32 v2, v163
	v_mov_b32_e32 v3, v167
	v_pk_mul_f32 v[2:3], v[86:87], v[2:3]
	v_mov_b32_e32 v7, v168
	v_pk_fma_f32 v[2:3], v[26:27], v[30:31], v[2:3]
	v_mov_b32_e32 v4, v165
	ds_read_b128 v[162:165], v1 offset:56256
	v_pk_fma_f32 v[2:3], v[28:29], v[6:7], v[2:3]
	v_mov_b32_e32 v30, v158
	v_mov_b32_e32 v5, v169
	ds_read_b128 v[166:169], v1 offset:55504
	v_pk_fma_f32 v[6:7], v[88:89], v[4:5], v[2:3]
	v_add_f32_e32 v6, v33, v6
	v_add_f32_e32 v33, v6, v7
	v_mov_b32_e32 v10, v160
	s_waitcnt lgkmcnt(2)
	v_mov_b32_e32 v31, v154
	v_mov_b32_e32 v2, v159
	v_mov_b32_e32 v3, v155
	v_pk_mul_f32 v[2:3], v[86:87], v[2:3]
	v_mov_b32_e32 v11, v156
	v_pk_fma_f32 v[2:3], v[26:27], v[30:31], v[2:3]
	v_mov_b32_e32 v4, v161
	ds_read_b128 v[158:161], v1 offset:55744
	v_pk_fma_f32 v[2:3], v[28:29], v[10:11], v[2:3]
	v_mov_b32_e32 v27, v78
	v_mov_b32_e32 v5, v157
	ds_read_b128 v[154:157], v1 offset:55520
	v_pk_fma_f32 v[2:3], v[88:89], v[4:5], v[2:3]
	v_mov_b32_e32 v78, v83
	v_add_f32_e32 v2, v34, v2
	v_add_f32_e32 v34, v2, v3
	v_mov_b32_e32 v26, v82
	v_mov_b32_e32 v28, v146
	v_mov_b32_e32 v14, v148
	v_add_f32_e32 v35, v22, v23
	s_waitcnt lgkmcnt(2)
	v_mov_b32_e32 v29, v166
	v_mov_b32_e32 v2, v147
	v_mov_b32_e32 v3, v167
	v_pk_mul_f32 v[2:3], v[78:79], v[2:3]
	v_mov_b32_e32 v15, v168
	v_pk_fma_f32 v[2:3], v[26:27], v[28:29], v[2:3]
	v_mov_b32_e32 v28, v84
	v_mov_b32_e32 v29, v80
	v_pk_fma_f32 v[2:3], v[28:29], v[14:15], v[2:3]
	v_mov_b32_e32 v80, v85
	v_mov_b32_e32 v4, v149
	ds_read_b128 v[146:149], v1 offset:55760
	v_mov_b32_e32 v5, v169
	ds_read_b128 v[166:169], v1 offset:55776
	v_pk_fma_f32 v[14:15], v[80:81], v[4:5], v[2:3]
	v_add_f32_e32 v14, v35, v14
	v_add_f32_e32 v35, v14, v15
	s_waitcnt lgkmcnt(3)
	v_mov_b32_e32 v30, v158
	s_waitcnt lgkmcnt(1)
	v_mov_b32_e32 v31, v146
	v_mov_b32_e32 v2, v159
	v_mov_b32_e32 v3, v147
	v_pk_mul_f32 v[2:3], v[78:79], v[2:3]
	v_mov_b32_e32 v22, v160
	v_pk_fma_f32 v[2:3], v[26:27], v[30:31], v[2:3]
	v_mov_b32_e32 v23, v148
	v_pk_fma_f32 v[2:3], v[28:29], v[22:23], v[2:3]
	v_mov_b32_e32 v4, v161
	ds_read_b128 v[158:161], v1 offset:56016
	v_mov_b32_e32 v5, v149
	ds_read_b128 v[146:149], v1 offset:56032
	v_pk_fma_f32 v[22:23], v[80:81], v[4:5], v[2:3]
	v_add_f32_e32 v22, v32, v22
	v_add_f32_e32 v32, v22, v23
	v_mov_b32_e32 v30, v150
	s_waitcnt lgkmcnt(1)
	v_mov_b32_e32 v31, v158
	v_mov_b32_e32 v2, v151
	v_mov_b32_e32 v3, v159
	v_pk_mul_f32 v[2:3], v[78:79], v[2:3]
	v_mov_b32_e32 v18, v152
	v_pk_fma_f32 v[2:3], v[26:27], v[30:31], v[2:3]
	v_mov_b32_e32 v19, v160
	v_pk_fma_f32 v[2:3], v[28:29], v[18:19], v[2:3]
	v_mov_b32_e32 v4, v153
	ds_read_b128 v[150:153], v1 offset:56272
	v_mov_b32_e32 v5, v161
	ds_read_b128 v[158:161], v1 offset:56288
	v_pk_fma_f32 v[18:19], v[80:81], v[4:5], v[2:3]
	v_add_f32_e32 v18, v33, v18
	v_add_f32_e32 v33, v18, v19
	v_mov_b32_e32 v30, v162
	s_waitcnt lgkmcnt(1)
	v_mov_b32_e32 v31, v150
	v_mov_b32_e32 v2, v163
	v_mov_b32_e32 v3, v151
	v_pk_mul_f32 v[2:3], v[78:79], v[2:3]
	v_mov_b32_e32 v6, v164
	v_pk_fma_f32 v[2:3], v[26:27], v[30:31], v[2:3]
	v_mov_b32_e32 v7, v152
	v_pk_fma_f32 v[2:3], v[28:29], v[6:7], v[2:3]
	v_mov_b32_e32 v4, v165
	ds_read_b128 v[162:165], v1 offset:56304
	v_mov_b32_e32 v5, v153
	v_pk_fma_f32 v[2:3], v[80:81], v[4:5], v[2:3]
	v_mov_b32_e32 v7, v62
	v_add_f32_e32 v2, v34, v2
	v_add_f32_e32 v26, v2, v3
	v_mov_b32_e32 v3, v58
	v_mov_b32_e32 v62, v75
	v_mov_b32_e32 v58, v155
	v_mov_b32_e32 v6, v74
	v_mov_b32_e32 v2, v154
	v_pk_mul_f32 v[4:5], v[62:63], v[58:59]
	v_mov_b32_e32 v8, v76
	v_pk_fma_f32 v[2:3], v[6:7], v[2:3], v[4:5]
	v_mov_b32_e32 v9, v64
	v_mov_b32_e32 v4, v156
	v_mov_b32_e32 v5, v60
	v_pk_fma_f32 v[2:3], v[8:9], v[4:5], v[2:3]
	v_mov_b32_e32 v64, v77
	v_mov_b32_e32 v60, v157
	v_pk_fma_f32 v[2:3], v[64:65], v[60:61], v[2:3]
	s_nop 0
	v_add_f32_e32 v2, v35, v2
	v_add_f32_e32 v12, v2, v3
	v_mov_b32_e32 v3, v70
	v_mov_b32_e32 v70, v167
	v_mov_b32_e32 v2, v166
	v_pk_mul_f32 v[4:5], v[62:63], v[70:71]
	s_nop 0
	v_pk_fma_f32 v[2:3], v[6:7], v[2:3], v[4:5]
	v_mov_b32_e32 v4, v168
	v_mov_b32_e32 v5, v72
	v_pk_fma_f32 v[2:3], v[8:9], v[4:5], v[2:3]
	v_mov_b32_e32 v72, v169
	v_pk_fma_f32 v[2:3], v[64:65], v[72:73], v[2:3]
	s_nop 0
	v_add_f32_e32 v2, v32, v2
	v_add_f32_e32 v13, v2, v3
	v_mov_b32_e32 v3, v66
	v_mov_b32_e32 v66, v147
	v_mov_b32_e32 v2, v146
	v_pk_mul_f32 v[4:5], v[62:63], v[66:67]
	s_nop 0
	v_pk_fma_f32 v[2:3], v[6:7], v[2:3], v[4:5]
	v_mov_b32_e32 v4, v148
	v_mov_b32_e32 v5, v68
	v_pk_fma_f32 v[10:11], v[8:9], v[4:5], v[2:3]
	v_mov_b32_e32 v68, v149
	v_pk_fma_f32 v[10:11], v[64:65], v[68:69], v[10:11]
	s_nop 0
	v_add_f32_e32 v10, v33, v10
	v_add_f32_e32 v14, v10, v11
	s_waitcnt lgkmcnt(0)
; #define LAS __attribute__((address_space(3)))
; __device__ __forceinline__ float ex2(float x) { return __builtin_amdgcn_exp2f(x); }
; template <int CTRL> __device__ __forceinline__ float dpp_mov(float old, float x) { return __int_as_float(__builtin_amdgcn_update_dpp(__float_as_int(old), __float_as_int(x), CTRL, 0xF, 0xF, false)); }
; #define LDS_WAIT() asm volatile("s_waitcnt lgkmcnt(0)" ::: "memory")
; __device__ __forceinline__ float wave_max(float v) {
;     v = fmaxf(v, dpp_mov<0x111>(v, v)); v = fmaxf(v, dpp_mov<0x112>(v, v)); v = fmaxf(v, dpp_mov<0x114>(v, v)); v = fmaxf(v, dpp_mov<0x118>(v, v));
;     v = fmaxf(v, __int_as_float(__builtin_amdgcn_update_dpp(__float_as_int(v), __float_as_int(v), 0x142, 0xA, 0xF, false)));
;     v = fmaxf(v, __int_as_float(__builtin_amdgcn_update_dpp(__float_as_int(v), __float_as_int(v), 0x143, 0xC, 0xF, false)));
;     return __int_as_float(__builtin_amdgcn_readlane(__float_as_int(v), 63));
; }
; __device__ __forceinline__ void seg_attend(SegAcc& A, const float* base, int kvh, int nk, bool valid, const LAS float* qs, LAS float* pt, int lane) {
;     ...
;     valid = valid && lane < nk;
;     f32x4 p;
; #pragma unroll
;     for (int gq = 0; gq < 4; ++gq) { const float sv = valid ? s[gq] : NEGB; const float mx = wave_max(sv); const float mn = fmaxf(A.m[gq], mx), a = ex2(A.m[gq] - mn);
;         p[gq] = valid ? ex2(sv - mn) : 0.f; A.l[gq] = A.l[gq] * a + p[gq]; A.o[gq] *= a; A.m[gq] = mn; }
;     *(LAS f32x4*)(pt + 4 * lane) = p;
;     LDS_WAIT();
; #pragma unroll
;     for (int k = 0; k < 64; ++k) { const f32x4 pk = *(const LAS f32x4*)(pt + 4 * k);
	v_mov_b32_e32 v11, v162
	v_mov_b32_e32 v2, v159
	v_mov_b32_e32 v10, v158
	v_mov_b32_e32 v3, v163
	v_pk_mul_f32 v[2:3], v[62:63], v[2:3]
	s_nop 0
	v_pk_fma_f32 v[2:3], v[6:7], v[10:11], v[2:3]
	v_mov_b32_e32 v6, v160
	v_mov_b32_e32 v7, v164
	v_pk_fma_f32 v[2:3], v[8:9], v[6:7], v[2:3]
	v_mov_b32_e32 v4, v161
	v_mov_b32_e32 v5, v165
	v_pk_fma_f32 v[2:3], v[64:65], v[4:5], v[2:3]
	v_cndmask_b32_e32 v5, v12, v209, vcc
	v_add_f32_e32 v4, v26, v2
	v_mov_b32_e32 v2, v5
	v_add_f32_e32 v3, v4, v3
	v_cndmask_b32_e32 v3, v3, v209, vcc
	v_mov_b32_dpp v2, v2 row_shr:1 row_mask:0xf bank_mask:0xf
	v_max_f32_e32 v2, v2, v2
	v_max_f32_e32 v2, v5, v2
	v_mov_b32_e32 v6, v2
	s_nop 1
	v_mov_b32_dpp v6, v6 row_shr:2 row_mask:0xf bank_mask:0xf
	v_max_f32_e32 v6, v6, v6
	v_max_f32_e32 v2, v2, v6
	v_mov_b32_e32 v6, v2
	s_nop 1
	v_mov_b32_dpp v6, v6 row_shr:4 row_mask:0xf bank_mask:0xf
	v_max_f32_e32 v6, v6, v6
	v_max_f32_e32 v2, v2, v6
	v_mov_b32_e32 v6, v2
	s_nop 1
	v_mov_b32_dpp v6, v6 row_shr:8 row_mask:0xf bank_mask:0xf
	v_max_f32_e32 v6, v6, v6
	v_max_f32_e32 v2, v2, v6
	v_mov_b32_e32 v6, v2
	s_nop 1
	v_mov_b32_dpp v6, v6 row_bcast:15 row_mask:0xa bank_mask:0xf
	v_max_f32_e32 v6, v6, v6
	v_max_f32_e32 v2, v2, v6
	v_mov_b32_e32 v6, v2
	s_nop 1
	v_mov_b32_dpp v6, v6 row_bcast:31 row_mask:0xc bank_mask:0xf
	v_max_f32_e32 v6, v6, v6
	v_max_f32_e32 v2, v2, v6
	v_max_f32_e32 v6, v240, v240
	v_readlane_b32 s0, v2, 63
	s_nop 1
	v_max_f32_e64 v2, s0, s0
	v_max_f32_e32 v2, v6, v2
	v_sub_f32_e32 v5, v5, v2
	v_exp_f32_e32 v5, v5
	v_sub_f32_e32 v4, v240, v2
	v_exp_f32_e32 v40, v4
	v_mov_b32_e32 v240, v2
	v_cndmask_b32_e64 v4, v5, 0, vcc
	v_cndmask_b32_e32 v5, v13, v209, vcc
	v_mov_b32_e32 v6, v5
	v_fma_f32 v111, v111, v40, v4
	s_nop 0
	v_mov_b32_dpp v6, v6 row_shr:1 row_mask:0xf bank_mask:0xf
	v_max_f32_e32 v6, v6, v6
	v_max_f32_e32 v6, v5, v6
	v_mov_b32_e32 v7, v6
	s_nop 1
	v_mov_b32_dpp v7, v7 row_shr:2 row_mask:0xf bank_mask:0xf
	v_max_f32_e32 v7, v7, v7
	v_max_f32_e32 v6, v6, v7
	v_mov_b32_e32 v7, v6
	s_nop 1
	v_mov_b32_dpp v7, v7 row_shr:4 row_mask:0xf bank_mask:0xf
	v_max_f32_e32 v7, v7, v7
	v_max_f32_e32 v6, v6, v7
	v_mov_b32_e32 v7, v6
	s_nop 1
	v_mov_b32_dpp v7, v7 row_shr:8 row_mask:0xf bank_mask:0xf
	v_max_f32_e32 v7, v7, v7
	v_max_f32_e32 v6, v6, v7
	v_mov_b32_e32 v7, v6
	s_nop 1
	v_mov_b32_dpp v7, v7 row_bcast:15 row_mask:0xa bank_mask:0xf
	v_max_f32_e32 v7, v7, v7
	v_max_f32_e32 v6, v6, v7
	v_mov_b32_e32 v7, v6
	s_nop 1
	v_mov_b32_dpp v7, v7 row_bcast:31 row_mask:0xc bank_mask:0xf
	v_max_f32_e32 v7, v7, v7
	v_max_f32_e32 v6, v6, v7
	v_max_f32_e32 v7, v238, v238
	v_readlane_b32 s0, v6, 63
	s_nop 1
	v_max_f32_e64 v6, s0, s0
	v_max_f32_e32 v54, v7, v6
	v_sub_f32_e32 v6, v238, v54
	v_exp_f32_e32 v41, v6
	v_cndmask_b32_e32 v6, v14, v209, vcc
	v_mov_b32_e32 v7, v6
	v_sub_f32_e32 v5, v5, v54
	v_exp_f32_e32 v5, v5
	v_mov_b32_dpp v7, v7 row_shr:1 row_mask:0xf bank_mask:0xf
	v_max_f32_e32 v7, v7, v7
	v_max_f32_e32 v7, v6, v7
	v_mov_b32_e32 v8, v7
	v_cndmask_b32_e64 v5, v5, 0, vcc
	v_fma_f32 v123, v123, v41, v5
	v_mov_b32_dpp v8, v8 row_shr:2 row_mask:0xf bank_mask:0xf
	v_max_f32_e32 v8, v8, v8
	v_max_f32_e32 v7, v7, v8
	v_mov_b32_e32 v8, v7
	v_mov_b32_e32 v238, v54
	s_nop 0
	v_mov_b32_dpp v8, v8 row_shr:4 row_mask:0xf bank_mask:0xf
	v_max_f32_e32 v8, v8, v8
	v_max_f32_e32 v7, v7, v8
	v_mov_b32_e32 v8, v7
	s_nop 1
	v_mov_b32_dpp v8, v8 row_shr:8 row_mask:0xf bank_mask:0xf
	v_max_f32_e32 v8, v8, v8
	v_max_f32_e32 v7, v7, v8
	v_mov_b32_e32 v8, v7
	s_nop 1
	v_mov_b32_dpp v8, v8 row_bcast:15 row_mask:0xa bank_mask:0xf
	v_max_f32_e32 v8, v8, v8
	v_max_f32_e32 v7, v7, v8
	v_mov_b32_e32 v8, v7
	s_nop 1
	v_mov_b32_dpp v8, v8 row_bcast:31 row_mask:0xc bank_mask:0xf
	v_max_f32_e32 v8, v8, v8
	v_max_f32_e32 v7, v7, v8
	v_max_f32_e32 v8, v236, v236
	v_readlane_b32 s0, v7, 63
	s_nop 1
	v_max_f32_e64 v7, s0, s0
	v_max_f32_e32 v55, v8, v7
	v_sub_f32_e32 v7, v236, v55
	v_exp_f32_e32 v44, v7
	v_mov_b32_e32 v7, v3
	v_sub_f32_e32 v6, v6, v55
	v_exp_f32_e32 v6, v6
	v_mov_b32_dpp v7, v7 row_shr:1 row_mask:0xf bank_mask:0xf
	v_max_f32_e32 v7, v7, v7
	v_max_f32_e32 v7, v3, v7
	v_mov_b32_e32 v8, v7
	v_cndmask_b32_e64 v6, v6, 0, vcc
	v_fma_f32 v121, v121, v44, v6
	v_mov_b32_dpp v8, v8 row_shr:2 row_mask:0xf bank_mask:0xf
	v_max_f32_e32 v8, v8, v8
	v_max_f32_e32 v7, v7, v8
	v_mov_b32_e32 v8, v7
	v_mov_b32_e32 v236, v55
	s_nop 0
	v_mov_b32_dpp v8, v8 row_shr:4 row_mask:0xf bank_mask:0xf
	v_max_f32_e32 v8, v8, v8
	v_max_f32_e32 v7, v7, v8
	v_mov_b32_e32 v8, v7
	s_nop 1
	v_mov_b32_dpp v8, v8 row_shr:8 row_mask:0xf bank_mask:0xf
	v_max_f32_e32 v8, v8, v8
	v_max_f32_e32 v7, v7, v8
	v_mov_b32_e32 v8, v7
	s_nop 1
	v_mov_b32_dpp v8, v8 row_bcast:15 row_mask:0xa bank_mask:0xf
	v_max_f32_e32 v8, v8, v8
	v_max_f32_e32 v7, v7, v8
	v_mov_b32_e32 v8, v7
	s_nop 1
	v_mov_b32_dpp v8, v8 row_bcast:31 row_mask:0xc bank_mask:0xf
	v_max_f32_e32 v8, v8, v8
	v_max_f32_e32 v7, v7, v8
	v_max_f32_e32 v8, v234, v234
	v_readlane_b32 s0, v7, 63
	s_nop 1
	v_max_f32_e64 v7, s0, s0
	v_max_f32_e32 v56, v8, v7
	v_sub_f32_e32 v3, v3, v56
	v_exp_f32_e32 v3, v3
	v_sub_f32_e32 v7, v234, v56
	v_exp_f32_e32 v45, v7
	v_mov_b32_e32 v234, v56
	v_cndmask_b32_e64 v7, v3, 0, vcc
	ds_write_b128 v127, v[4:7] offset:18432
	s_waitcnt lgkmcnt(0)
	v_mov_b32_e32 v3, v7
	ds_read_b128 v[4:7], v57 offset:18432
	ds_read_b128 v[8:11], v57 offset:18448
	ds_read_b128 v[12:15], v57 offset:18464
	ds_read_b128 v[16:19], v57 offset:18480
	ds_read_b128 v[20:23], v57 offset:18496
	ds_read_b128 v[24:27], v57 offset:18512
	ds_read_b128 v[28:31], v57 offset:18528
	ds_read_b128 v[32:35], v57 offset:18544
	ds_read_b128 v[36:39], v57 offset:18560
	s_waitcnt lgkmcnt(8)
; #define LAS __attribute__((address_space(3)))
; __device__ __forceinline__ void seg_attend(SegAcc& A, const float* base, int kvh, int nk, bool valid, const LAS float* qs, LAS float* pt, int lane) {
;     ...
; #pragma unroll
;     for (int k = 0; k < 64; ++k) { const f32x4 pk = *(const LAS f32x4*)(pt + 4 * k);
; #pragma unroll
;         for (int gq = 0; gq < 4; ++gq) A.o[gq] += pk[gq] * vv[k]; }
	v_pk_mul_f32 v[4:5], v[0:1], v[4:5] op_sel_hi:[0,1]
	v_pk_fma_f32 v[4:5], v[114:115], v[40:41], v[4:5]
	ds_read_b128 v[40:43], v57 offset:18576
	s_waitcnt lgkmcnt(8)
	v_pk_fma_f32 v[4:5], v[116:117], v[8:9], v[4:5] op_sel_hi:[0,1,1]
	s_waitcnt lgkmcnt(7)
	v_pk_fma_f32 v[4:5], v[118:119], v[12:13], v[4:5] op_sel_hi:[0,1,1]
	s_waitcnt lgkmcnt(6)
	v_pk_fma_f32 v[4:5], v[120:121], v[16:17], v[4:5] op_sel_hi:[0,1,1]
	s_waitcnt lgkmcnt(5)
	v_pk_fma_f32 v[4:5], v[0:1], v[20:21], v[4:5] op_sel_hi:[0,1,1]
	s_waitcnt lgkmcnt(4)
	v_pk_fma_f32 v[4:5], v[0:1], v[24:25], v[4:5] op_sel_hi:[0,1,1]
	s_waitcnt lgkmcnt(3)
	v_pk_fma_f32 v[4:5], v[0:1], v[28:29], v[4:5] op_sel_hi:[0,1,1]
	s_waitcnt lgkmcnt(2)
	v_pk_fma_f32 v[4:5], v[0:1], v[32:33], v[4:5] op_sel_hi:[0,1,1]
	s_waitcnt lgkmcnt(1)
	v_pk_fma_f32 v[48:49], v[0:1], v[36:37], v[4:5] op_sel_hi:[0,1,1]
	v_pk_mul_f32 v[4:5], v[0:1], v[6:7] op_sel_hi:[0,1]
	v_pk_fma_f32 v[4:5], v[112:113], v[44:45], v[4:5]
	v_fmac_f32_e32 v3, v125, v45
	v_pk_fma_f32 v[4:5], v[116:117], v[10:11], v[4:5] op_sel_hi:[0,1,1]
	v_pk_fma_f32 v[4:5], v[118:119], v[14:15], v[4:5] op_sel_hi:[0,1,1]
	v_pk_fma_f32 v[4:5], v[120:121], v[18:19], v[4:5] op_sel_hi:[0,1,1]
	v_pk_fma_f32 v[4:5], v[0:1], v[22:23], v[4:5] op_sel_hi:[0,1,1]
	v_pk_fma_f32 v[4:5], v[0:1], v[26:27], v[4:5] op_sel_hi:[0,1,1]
	v_pk_fma_f32 v[4:5], v[0:1], v[30:31], v[4:5] op_sel_hi:[0,1,1]
	v_pk_fma_f32 v[4:5], v[0:1], v[34:35], v[4:5] op_sel_hi:[0,1,1]
	v_pk_fma_f32 v[50:51], v[0:1], v[38:39], v[4:5] op_sel_hi:[0,1,1]
	ds_read_b128 v[4:7], v57 offset:18592
	ds_read_b128 v[8:11], v57 offset:18608
	ds_read_b128 v[12:15], v57 offset:18624
	ds_read_b128 v[16:19], v57 offset:18640
	ds_read_b128 v[20:23], v57 offset:18656
	ds_read_b128 v[24:27], v57 offset:18672
	ds_read_b128 v[28:31], v57 offset:18688
	ds_read_b128 v[32:35], v57 offset:18704
	ds_read_b128 v[36:39], v57 offset:18720
	ds_read_b128 v[44:47], v57 offset:18736
	s_waitcnt lgkmcnt(10)
	v_pk_fma_f32 v[40:41], v[0:1], v[40:41], v[48:49] op_sel_hi:[0,1,1]
	s_waitcnt lgkmcnt(9)
	v_pk_fma_f32 v[4:5], v[0:1], v[4:5], v[40:41] op_sel_hi:[0,1,1]
	s_waitcnt lgkmcnt(8)
	v_pk_fma_f32 v[4:5], v[0:1], v[8:9], v[4:5] op_sel_hi:[0,1,1]
	s_waitcnt lgkmcnt(7)
	v_pk_fma_f32 v[4:5], v[0:1], v[12:13], v[4:5] op_sel_hi:[0,1,1]
	s_waitcnt lgkmcnt(6)
	v_pk_fma_f32 v[4:5], v[0:1], v[16:17], v[4:5] op_sel_hi:[0,1,1]
	s_waitcnt lgkmcnt(5)
	v_pk_fma_f32 v[4:5], v[0:1], v[20:21], v[4:5] op_sel_hi:[0,1,1]
	s_waitcnt lgkmcnt(4)
	v_pk_fma_f32 v[4:5], v[0:1], v[24:25], v[4:5] op_sel_hi:[0,1,1]
	s_waitcnt lgkmcnt(3)
	v_pk_fma_f32 v[4:5], v[0:1], v[28:29], v[4:5] op_sel_hi:[0,1,1]
	s_waitcnt lgkmcnt(2)
	v_pk_fma_f32 v[4:5], v[0:1], v[32:33], v[4:5] op_sel_hi:[0,1,1]
	s_waitcnt lgkmcnt(1)
	v_pk_fma_f32 v[4:5], v[0:1], v[36:37], v[4:5] op_sel_hi:[0,1,1]
	s_waitcnt lgkmcnt(0)
	v_pk_fma_f32 v[48:49], v[0:1], v[44:45], v[4:5] op_sel_hi:[0,1,1]
	v_pk_fma_f32 v[4:5], v[0:1], v[42:43], v[50:51] op_sel_hi:[0,1,1]
	v_pk_fma_f32 v[4:5], v[0:1], v[6:7], v[4:5] op_sel_hi:[0,1,1]
	v_pk_fma_f32 v[4:5], v[0:1], v[10:11], v[4:5] op_sel_hi:[0,1,1]
	v_pk_fma_f32 v[4:5], v[0:1], v[14:15], v[4:5] op_sel_hi:[0,1,1]
	v_pk_fma_f32 v[4:5], v[0:1], v[18:19], v[4:5] op_sel_hi:[0,1,1]
	v_pk_fma_f32 v[4:5], v[0:1], v[22:23], v[4:5] op_sel_hi:[0,1,1]
	v_pk_fma_f32 v[4:5], v[0:1], v[26:27], v[4:5] op_sel_hi:[0,1,1]
	v_pk_fma_f32 v[4:5], v[0:1], v[30:31], v[4:5] op_sel_hi:[0,1,1]
	v_pk_fma_f32 v[4:5], v[0:1], v[34:35], v[4:5] op_sel_hi:[0,1,1]
	v_pk_fma_f32 v[4:5], v[0:1], v[38:39], v[4:5] op_sel_hi:[0,1,1]
	v_pk_fma_f32 v[52:53], v[0:1], v[46:47], v[4:5] op_sel_hi:[0,1,1]
	ds_read_b128 v[4:7], v57 offset:18752
	ds_read_b128 v[8:11], v57 offset:18768
	ds_read_b128 v[12:15], v57 offset:18784
	ds_read_b128 v[16:19], v57 offset:18800
	ds_read_b128 v[20:23], v57 offset:18816
	ds_read_b128 v[24:27], v57 offset:18832
	ds_read_b128 v[28:31], v57 offset:18848
	ds_read_b128 v[32:35], v57 offset:18864
	ds_read_b128 v[36:39], v57 offset:18880
	ds_read_b128 v[40:43], v57 offset:18896
	ds_read_b128 v[44:47], v57 offset:18912
	s_waitcnt lgkmcnt(10)
	v_pk_fma_f32 v[4:5], v[0:1], v[4:5], v[48:49] op_sel_hi:[0,1,1]
	s_waitcnt lgkmcnt(9)
	v_pk_fma_f32 v[4:5], v[0:1], v[8:9], v[4:5] op_sel_hi:[0,1,1]
	s_waitcnt lgkmcnt(8)
	v_pk_fma_f32 v[4:5], v[0:1], v[12:13], v[4:5] op_sel_hi:[0,1,1]
	s_waitcnt lgkmcnt(7)
	v_pk_fma_f32 v[4:5], v[0:1], v[16:17], v[4:5] op_sel_hi:[0,1,1]
	s_waitcnt lgkmcnt(6)
	v_pk_fma_f32 v[4:5], v[0:1], v[20:21], v[4:5] op_sel_hi:[0,1,1]
	s_waitcnt lgkmcnt(5)
	v_pk_fma_f32 v[4:5], v[0:1], v[24:25], v[4:5] op_sel_hi:[0,1,1]
	s_waitcnt lgkmcnt(4)
	v_pk_fma_f32 v[4:5], v[0:1], v[28:29], v[4:5] op_sel_hi:[0,1,1]
	s_waitcnt lgkmcnt(3)
	v_pk_fma_f32 v[4:5], v[0:1], v[32:33], v[4:5] op_sel_hi:[0,1,1]
	s_waitcnt lgkmcnt(2)
	v_pk_fma_f32 v[4:5], v[0:1], v[36:37], v[4:5] op_sel_hi:[0,1,1]
	s_waitcnt lgkmcnt(1)
	v_pk_fma_f32 v[4:5], v[0:1], v[40:41], v[4:5] op_sel_hi:[0,1,1]
	s_waitcnt lgkmcnt(0)
	v_pk_fma_f32 v[44:45], v[0:1], v[44:45], v[4:5] op_sel_hi:[0,1,1]
	v_pk_fma_f32 v[4:5], v[0:1], v[6:7], v[52:53] op_sel_hi:[0,1,1]
	v_pk_fma_f32 v[4:5], v[0:1], v[10:11], v[4:5] op_sel_hi:[0,1,1]
	v_pk_fma_f32 v[4:5], v[0:1], v[14:15], v[4:5] op_sel_hi:[0,1,1]
	v_pk_fma_f32 v[4:5], v[0:1], v[18:19], v[4:5] op_sel_hi:[0,1,1]
	v_pk_fma_f32 v[4:5], v[0:1], v[22:23], v[4:5] op_sel_hi:[0,1,1]
	ds_read_b128 v[48:51], v57 offset:18928
	v_pk_fma_f32 v[4:5], v[0:1], v[26:27], v[4:5] op_sel_hi:[0,1,1]
	v_pk_fma_f32 v[4:5], v[0:1], v[30:31], v[4:5] op_sel_hi:[0,1,1]
	v_pk_fma_f32 v[4:5], v[0:1], v[34:35], v[4:5] op_sel_hi:[0,1,1]
	v_pk_fma_f32 v[4:5], v[0:1], v[38:39], v[4:5] op_sel_hi:[0,1,1]
	v_pk_fma_f32 v[4:5], v[0:1], v[42:43], v[4:5] op_sel_hi:[0,1,1]
	v_pk_fma_f32 v[46:47], v[0:1], v[46:47], v[4:5] op_sel_hi:[0,1,1]
	ds_read_b128 v[4:7], v57 offset:18944
	ds_read_b128 v[8:11], v57 offset:18960
	ds_read_b128 v[12:15], v57 offset:18976
	ds_read_b128 v[16:19], v57 offset:18992
	ds_read_b128 v[20:23], v57 offset:19008
	ds_read_b128 v[24:27], v57 offset:19024
	ds_read_b128 v[28:31], v57 offset:19040
	ds_read_b128 v[32:35], v57 offset:19056
	ds_read_b128 v[36:39], v57 offset:19072
	ds_read_b128 v[40:43], v57 offset:19088
	s_waitcnt lgkmcnt(10)
; #define LAS __attribute__((address_space(3)))
; __device__ __forceinline__ void seg_attend(SegAcc& A, const float* base, int kvh, int nk, bool valid, const LAS float* qs, LAS float* pt, int lane) {
;     ...
; #pragma unroll
;     for (int k = 0; k < 64; ++k) { const f32x4 pk = *(const LAS f32x4*)(pt + 4 * k);
; #pragma unroll
;         for (int gq = 0; gq < 4; ++gq) A.o[gq] += pk[gq] * vv[k]; }
	v_pk_fma_f32 v[44:45], v[0:1], v[48:49], v[44:45] op_sel_hi:[0,1,1]
	s_waitcnt lgkmcnt(9)
	v_pk_fma_f32 v[4:5], v[0:1], v[4:5], v[44:45] op_sel_hi:[0,1,1]
	s_waitcnt lgkmcnt(8)
	v_pk_fma_f32 v[4:5], v[0:1], v[8:9], v[4:5] op_sel_hi:[0,1,1]
	s_waitcnt lgkmcnt(7)
	v_pk_fma_f32 v[4:5], v[0:1], v[12:13], v[4:5] op_sel_hi:[0,1,1]
	s_waitcnt lgkmcnt(6)
	v_pk_fma_f32 v[4:5], v[0:1], v[16:17], v[4:5] op_sel_hi:[0,1,1]
	s_waitcnt lgkmcnt(5)
	v_pk_fma_f32 v[4:5], v[0:1], v[20:21], v[4:5] op_sel_hi:[0,1,1]
	s_waitcnt lgkmcnt(4)
	v_pk_fma_f32 v[4:5], v[0:1], v[24:25], v[4:5] op_sel_hi:[0,1,1]
	s_waitcnt lgkmcnt(3)
	v_pk_fma_f32 v[4:5], v[0:1], v[28:29], v[4:5] op_sel_hi:[0,1,1]
	s_waitcnt lgkmcnt(2)
	v_pk_fma_f32 v[4:5], v[0:1], v[32:33], v[4:5] op_sel_hi:[0,1,1]
	s_waitcnt lgkmcnt(1)
	v_pk_fma_f32 v[4:5], v[0:1], v[36:37], v[4:5] op_sel_hi:[0,1,1]
	s_waitcnt lgkmcnt(0)
	v_pk_fma_f32 v[48:49], v[0:1], v[40:41], v[4:5] op_sel_hi:[0,1,1]
	v_pk_fma_f32 v[4:5], v[0:1], v[50:51], v[46:47] op_sel_hi:[0,1,1]
	v_pk_fma_f32 v[4:5], v[0:1], v[6:7], v[4:5] op_sel_hi:[0,1,1]
	v_pk_fma_f32 v[4:5], v[0:1], v[10:11], v[4:5] op_sel_hi:[0,1,1]
	v_pk_fma_f32 v[4:5], v[0:1], v[14:15], v[4:5] op_sel_hi:[0,1,1]
	v_pk_fma_f32 v[4:5], v[0:1], v[18:19], v[4:5] op_sel_hi:[0,1,1]
	v_pk_fma_f32 v[4:5], v[0:1], v[22:23], v[4:5] op_sel_hi:[0,1,1]
	v_pk_fma_f32 v[4:5], v[0:1], v[26:27], v[4:5] op_sel_hi:[0,1,1]
	v_pk_fma_f32 v[4:5], v[0:1], v[30:31], v[4:5] op_sel_hi:[0,1,1]
	v_pk_fma_f32 v[4:5], v[0:1], v[34:35], v[4:5] op_sel_hi:[0,1,1]
	v_pk_fma_f32 v[4:5], v[0:1], v[38:39], v[4:5] op_sel_hi:[0,1,1]
	v_pk_fma_f32 v[52:53], v[0:1], v[42:43], v[4:5] op_sel_hi:[0,1,1]
	ds_read_b128 v[4:7], v57 offset:19104
	ds_read_b128 v[8:11], v57 offset:19120
	ds_read_b128 v[12:15], v57 offset:19136
	ds_read_b128 v[16:19], v57 offset:19152
	ds_read_b128 v[20:23], v57 offset:19168
	ds_read_b128 v[24:27], v57 offset:19184
	ds_read_b128 v[28:31], v57 offset:19200
	ds_read_b128 v[32:35], v57 offset:19216
	ds_read_b128 v[36:39], v57 offset:19232
	ds_read_b128 v[40:43], v57 offset:19248
	ds_read_b128 v[44:47], v57 offset:19264
	s_waitcnt lgkmcnt(10)
	v_pk_fma_f32 v[4:5], v[0:1], v[4:5], v[48:49] op_sel_hi:[0,1,1]
	s_waitcnt lgkmcnt(9)
	v_pk_fma_f32 v[4:5], v[0:1], v[8:9], v[4:5] op_sel_hi:[0,1,1]
	s_waitcnt lgkmcnt(8)
	v_pk_fma_f32 v[4:5], v[0:1], v[12:13], v[4:5] op_sel_hi:[0,1,1]
	s_waitcnt lgkmcnt(7)
	v_pk_fma_f32 v[4:5], v[0:1], v[16:17], v[4:5] op_sel_hi:[0,1,1]
	s_waitcnt lgkmcnt(6)
	v_pk_fma_f32 v[4:5], v[0:1], v[20:21], v[4:5] op_sel_hi:[0,1,1]
	s_waitcnt lgkmcnt(5)
	v_pk_fma_f32 v[4:5], v[0:1], v[24:25], v[4:5] op_sel_hi:[0,1,1]
	s_waitcnt lgkmcnt(4)
	v_pk_fma_f32 v[4:5], v[0:1], v[28:29], v[4:5] op_sel_hi:[0,1,1]
	s_waitcnt lgkmcnt(3)
	v_pk_fma_f32 v[4:5], v[0:1], v[32:33], v[4:5] op_sel_hi:[0,1,1]
	s_waitcnt lgkmcnt(2)
	v_pk_fma_f32 v[4:5], v[0:1], v[36:37], v[4:5] op_sel_hi:[0,1,1]
	s_waitcnt lgkmcnt(1)
	v_pk_fma_f32 v[4:5], v[0:1], v[40:41], v[4:5] op_sel_hi:[0,1,1]
	s_waitcnt lgkmcnt(0)
	v_pk_fma_f32 v[44:45], v[0:1], v[44:45], v[4:5] op_sel_hi:[0,1,1]
	v_pk_fma_f32 v[4:5], v[0:1], v[6:7], v[52:53] op_sel_hi:[0,1,1]
	v_pk_fma_f32 v[4:5], v[0:1], v[10:11], v[4:5] op_sel_hi:[0,1,1]
	v_pk_fma_f32 v[4:5], v[0:1], v[14:15], v[4:5] op_sel_hi:[0,1,1]
	v_pk_fma_f32 v[4:5], v[0:1], v[18:19], v[4:5] op_sel_hi:[0,1,1]
	v_pk_fma_f32 v[4:5], v[0:1], v[22:23], v[4:5] op_sel_hi:[0,1,1]
	ds_read_b128 v[48:51], v57 offset:19280
	v_pk_fma_f32 v[4:5], v[0:1], v[26:27], v[4:5] op_sel_hi:[0,1,1]
	v_pk_fma_f32 v[4:5], v[0:1], v[30:31], v[4:5] op_sel_hi:[0,1,1]
	v_pk_fma_f32 v[4:5], v[0:1], v[34:35], v[4:5] op_sel_hi:[0,1,1]
	v_pk_fma_f32 v[4:5], v[0:1], v[38:39], v[4:5] op_sel_hi:[0,1,1]
	v_pk_fma_f32 v[4:5], v[0:1], v[42:43], v[4:5] op_sel_hi:[0,1,1]
	v_pk_fma_f32 v[46:47], v[0:1], v[46:47], v[4:5] op_sel_hi:[0,1,1]
	ds_read_b128 v[4:7], v57 offset:19296
	ds_read_b128 v[8:11], v57 offset:19312
	ds_read_b128 v[12:15], v57 offset:19328
	ds_read_b128 v[16:19], v57 offset:19344
	ds_read_b128 v[20:23], v57 offset:19360
	ds_read_b128 v[24:27], v57 offset:19376
	ds_read_b128 v[28:31], v57 offset:19392
	ds_read_b128 v[32:35], v57 offset:19408
	ds_read_b128 v[36:39], v57 offset:19424
	ds_read_b128 v[40:43], v57 offset:19440
	s_waitcnt lgkmcnt(10)
	v_pk_fma_f32 v[44:45], v[0:1], v[48:49], v[44:45] op_sel_hi:[0,1,1]
	s_waitcnt lgkmcnt(9)
	v_pk_fma_f32 v[4:5], v[0:1], v[4:5], v[44:45] op_sel_hi:[0,1,1]
	s_waitcnt lgkmcnt(8)
	v_pk_fma_f32 v[4:5], v[0:1], v[8:9], v[4:5] op_sel_hi:[0,1,1]
	s_waitcnt lgkmcnt(7)
	v_pk_fma_f32 v[4:5], v[0:1], v[12:13], v[4:5] op_sel_hi:[0,1,1]
	s_waitcnt lgkmcnt(6)
	v_pk_fma_f32 v[4:5], v[0:1], v[16:17], v[4:5] op_sel_hi:[0,1,1]
	s_waitcnt lgkmcnt(5)
	v_pk_fma_f32 v[4:5], v[0:1], v[20:21], v[4:5] op_sel_hi:[0,1,1]
	s_waitcnt lgkmcnt(4)
	v_pk_fma_f32 v[4:5], v[0:1], v[24:25], v[4:5] op_sel_hi:[0,1,1]
	s_waitcnt lgkmcnt(3)
	v_pk_fma_f32 v[4:5], v[0:1], v[28:29], v[4:5] op_sel_hi:[0,1,1]
	s_waitcnt lgkmcnt(2)
	v_pk_fma_f32 v[4:5], v[0:1], v[32:33], v[4:5] op_sel_hi:[0,1,1]
	s_waitcnt lgkmcnt(1)
	v_pk_fma_f32 v[4:5], v[0:1], v[36:37], v[4:5] op_sel_hi:[0,1,1]
	s_waitcnt lgkmcnt(0)
	v_pk_fma_f32 v[114:115], v[0:1], v[40:41], v[4:5] op_sel_hi:[0,1,1]
	v_pk_fma_f32 v[4:5], v[0:1], v[50:51], v[46:47] op_sel_hi:[0,1,1]
	v_pk_fma_f32 v[4:5], v[0:1], v[6:7], v[4:5] op_sel_hi:[0,1,1]
	v_pk_fma_f32 v[4:5], v[0:1], v[10:11], v[4:5] op_sel_hi:[0,1,1]
	v_pk_fma_f32 v[4:5], v[0:1], v[14:15], v[4:5] op_sel_hi:[0,1,1]
	v_pk_fma_f32 v[4:5], v[0:1], v[18:19], v[4:5] op_sel_hi:[0,1,1]
	v_pk_fma_f32 v[4:5], v[0:1], v[22:23], v[4:5] op_sel_hi:[0,1,1]
	v_pk_fma_f32 v[4:5], v[0:1], v[26:27], v[4:5] op_sel_hi:[0,1,1]
	v_pk_fma_f32 v[4:5], v[0:1], v[30:31], v[4:5] op_sel_hi:[0,1,1]
	v_pk_fma_f32 v[4:5], v[0:1], v[34:35], v[4:5] op_sel_hi:[0,1,1]
	s_waitcnt lgkmcnt(0)
	v_pk_fma_f32 v[4:5], v[0:1], v[38:39], v[4:5] op_sel_hi:[0,1,1]
	v_pk_fma_f32 v[112:113], v[0:1], v[42:43], v[4:5] op_sel_hi:[0,1,1]
	v_mov_b32_e32 v125, v3
